# loop-invariant LDS fragment addresses precomputed once per tile into VGPRs freed by the DMA conversion; the 4 per-iteration v_add_u32 removed from the loader half in all six K-loops
# speedup vs baseline: 1.0014x; 1.0014x over previous
; #define PG8_STAGE(bufoff, gbase, voff) do { _Pragma("unroll") for (int _i = 0; _i < 2; ++_i) \
;         __builtin_amdgcn_global_load_lds((const unsigned*)((const char*)(gbase) + (voff)[_i]), (PG8_LAS unsigned*)(lds + (bufoff) + ldsw + _i * 8192), 16, 0, 0); } while (0)
; #define PG8_LDA(dst, b, h) do { _Pragma("unroll") for (int m = 0; m < 4; ++m) _Pragma("unroll") for (int k = 0; k < 2; ++k) dst[m][k] = *(const PG8_LAS bf16x8*)(lds + PG8_SA(b, h) + aoff + m * 2048 + k * 1024); } while (0)
; #define PG8_LDB(dst, b, h) do { _Pragma("unroll") for (int n = 0; n < 2; ++n) _Pragma("unroll") for (int k = 0; k < 2; ++k) dst[n][k] = *(const PG8_LAS bf16x8*)(lds + PG8_SB(b, h) + boff + n * 2048 + k * 1024); } while (0)
; #define PG8_MMA(ai, bj, At, Bt) do { __builtin_amdgcn_s_setprio(1); _Pragma("unroll") for (int m = 0; m < 4; ++m) _Pragma("unroll") for (int n = 0; n < 2; ++n) _Pragma("unroll") for (int k = 0; k < 2; ++k) \
;         acc[ai][bj][m][n] = __builtin_amdgcn_mfma_f32_16x16x32_bf16(Bt[n][k], At[m][k], acc[ai][bj][m][n], 0, 0, 0); __builtin_amdgcn_s_setprio(0); } while (0)
; #define PG8_WAIT_V(n) asm volatile("s_waitcnt vmcnt(" #n ")" ::: "memory")
; #define PG8_WAIT_L(n) asm volatile("s_waitcnt lgkmcnt(" #n ")" ::: "memory")
; #define PG8_BAR __builtin_amdgcn_s_barrier()
; #define PG8_SCHED __builtin_amdgcn_sched_barrier(0)
; template <class Epi, class Sched, bool ALIGN_EPI = false, bool SP2 = false>
; __device__ __forceinline__ void gemm_phase(PG8_LAS unsigned char* lds, const Gemm g, const Sched& S, const Epi& E) {
;     ...
;             PG8_LDB(B0, 0, 0); PG8_LDB(B1, 0, 1); PG8_SCHED; PG8_LDA(At, 0, 0); PG8_STAGE(PG8_SA(1, 1), a1 + hstep, voffA);
;             PG8_WAIT_V(8); PG8_WAIT_L(0); PG8_BAR; PG8_MMA(0, 0, At, B0); PG8_MMA(0, 1, At, B1); PG8_BAR; PG8_SCHED;
;             PG8_LDA(At, 0, 1); PG8_STAGE(PG8_SB(0, 0), b2, voffB); PG8_STAGE(PG8_SB(0, 1), b2 + hstep, voffB); PG8_STAGE(PG8_SA(0, 0), a2, voffA);
;             PG8_WAIT_V(8); PG8_WAIT_L(0); PG8_BAR; PG8_MMA(1, 0, At, B0); PG8_MMA(1, 1, At, B1); PG8_BAR; PG8_SCHED;
.LBB0_84:
	s_ashr_i32 s11, s10, 31
	s_lshl_b64 s[12:13], s[10:11], 20
	s_add_u32 s12, s46, s12
	s_addc_u32 s13, s47, s13
	s_and_b64 s[14:15], s[2:3], exec
	s_cselect_b32 s11, s13, s19
	s_cselect_b32 s42, s12, s18
	s_ashr_i32 s9, s8, 31
	s_lshl_b64 s[14:15], s[8:9], 20
	v_readlane_b32 s9, v255, 30
	s_add_u32 s14, s9, s14
	v_readlane_b32 s9, v255, 31
	s_addc_u32 s15, s9, s15
	s_and_b64 s[22:23], s[2:3], exec
	s_cselect_b32 s9, s15, s21
	s_cselect_b32 s44, s14, s20
	s_add_u32 s18, s18, 0x80080
	s_addc_u32 s19, s19, 0
	s_add_u32 s45, s20, 0x100
	s_addc_u32 s50, s21, 0
	s_mov_b32 s51, -2
	v_add_u32_e32 v166, 0x10000, v153
	v_add_u32_e32 v167, 0x14000, v153
	v_add_u32_e32 v248, 0x18000, v153
	v_add_u32_e32 v249, 0x1c000, v153
	s_add_u32 s20, s18, 0xfff80080
	s_addc_u32 s21, s19, -1
	s_add_i32 s56, 0, 0x10000
	s_cmp_eq_u32 s51, 28
	s_cselect_b32 s23, s11, s21
	s_cselect_b32 s22, s42, s20
	s_cselect_b32 s21, s9, s50
	s_cselect_b32 s20, s44, s45
	s_add_i32 s63, 0, 0x14000
	ds_read_b128 v[184:187], v166
	ds_read_b128 v[188:191], v166 offset:1024
	ds_read_b128 v[192:195], v166 offset:2048
	ds_read_b128 v[196:199], v166 offset:3072
	ds_read_b128 v[200:203], v167
	ds_read_b128 v[204:207], v167 offset:1024
	ds_read_b128 v[208:211], v167 offset:2048
	ds_read_b128 v[212:215], v167 offset:3072
	s_add_i32 m0, s27, 0xc000
	ds_read_b128 v[216:219], v155
	ds_read_b128 v[220:223], v155 offset:1024
	ds_read_b128 v[224:227], v155 offset:2048
	ds_read_b128 v[228:231], v155 offset:3072
	ds_read_b128 v[232:235], v155 offset:4096
	ds_read_b128 v[236:239], v155 offset:5120
	ds_read_b128 v[240:243], v155 offset:6144
	ds_read_b128 v[244:247], v155 offset:7168
	global_load_lds_dwordx4 v136, s[18:19]
	s_add_i32 m0, s27, 0xe000
	s_nop 0
	global_load_lds_dwordx4 v138, s[18:19]
	s_waitcnt vmcnt(8)
	s_waitcnt lgkmcnt(0)
	s_setprio 1
	s_barrier
	v_mfma_f32_16x16x32_bf16 v[128:131], v[184:187], v[216:219], 0
	v_mfma_f32_16x16x32_bf16 v[120:123], v[192:195], v[216:219], 0
	v_mfma_f32_16x16x32_bf16 v[112:115], v[184:187], v[224:227], 0
	v_mfma_f32_16x16x32_bf16 v[104:107], v[192:195], v[224:227], 0
	v_mfma_f32_16x16x32_bf16 v[96:99], v[184:187], v[232:235], 0
	v_mfma_f32_16x16x32_bf16 v[88:91], v[192:195], v[232:235], 0
	v_mfma_f32_16x16x32_bf16 v[80:83], v[184:187], v[240:243], 0
	v_mfma_f32_16x16x32_bf16 v[72:75], v[192:195], v[240:243], 0
	v_mfma_f32_16x16x32_bf16 v[128:131], v[188:191], v[220:223], v[128:131]
	v_mfma_f32_16x16x32_bf16 v[120:123], v[196:199], v[220:223], v[120:123]
	v_mfma_f32_16x16x32_bf16 v[112:115], v[188:191], v[228:231], v[112:115]
	v_mfma_f32_16x16x32_bf16 v[104:107], v[196:199], v[228:231], v[104:107]
	v_mfma_f32_16x16x32_bf16 v[96:99], v[188:191], v[236:239], v[96:99]
	v_mfma_f32_16x16x32_bf16 v[88:91], v[196:199], v[236:239], v[88:91]
	v_mfma_f32_16x16x32_bf16 v[80:83], v[188:191], v[244:247], v[80:83]
	v_mfma_f32_16x16x32_bf16 v[72:75], v[196:199], v[244:247], v[72:75]
	v_mfma_f32_16x16x32_bf16 v[124:127], v[200:203], v[216:219], 0
	v_mfma_f32_16x16x32_bf16 v[116:119], v[208:211], v[216:219], 0
	v_mfma_f32_16x16x32_bf16 v[108:111], v[200:203], v[224:227], 0
	v_mfma_f32_16x16x32_bf16 v[100:103], v[208:211], v[224:227], 0
	v_mfma_f32_16x16x32_bf16 v[92:95], v[200:203], v[232:235], 0
	v_mfma_f32_16x16x32_bf16 v[84:87], v[208:211], v[232:235], 0
	v_mfma_f32_16x16x32_bf16 v[76:79], v[200:203], v[240:243], 0
	v_mfma_f32_16x16x32_bf16 v[68:71], v[208:211], v[240:243], 0
	v_mfma_f32_16x16x32_bf16 v[124:127], v[204:207], v[220:223], v[124:127]
	v_mfma_f32_16x16x32_bf16 v[116:119], v[212:215], v[220:223], v[116:119]
	v_mfma_f32_16x16x32_bf16 v[108:111], v[204:207], v[228:231], v[108:111]
	v_mfma_f32_16x16x32_bf16 v[100:103], v[212:215], v[228:231], v[100:103]
	v_mfma_f32_16x16x32_bf16 v[92:95], v[204:207], v[236:239], v[92:95]
	v_mfma_f32_16x16x32_bf16 v[84:87], v[212:215], v[236:239], v[84:87]
	v_mfma_f32_16x16x32_bf16 v[76:79], v[204:207], v[244:247], v[76:79]
	v_mfma_f32_16x16x32_bf16 v[68:71], v[212:215], v[244:247], v[68:71]
	s_barrier
	s_setprio 0
	s_add_i32 s56, s56, s25
	s_mov_b32 m0, s56
	ds_read_b128 v[216:219], v155 offset:16384
	ds_read_b128 v[220:223], v155 offset:17408
	ds_read_b128 v[224:227], v155 offset:18432
	ds_read_b128 v[228:231], v155 offset:19456
	ds_read_b128 v[232:235], v155 offset:20480
	ds_read_b128 v[236:239], v155 offset:21504
	ds_read_b128 v[240:243], v155 offset:22528
	ds_read_b128 v[244:247], v155 offset:23552
	global_load_lds_dwordx4 v2, s[20:21]
	s_add_i32 m0, s56, 0x2000
	s_add_u32 s56, s20, 0x80000
	s_addc_u32 s57, s21, 0
	s_add_i32 s63, s63, s25
	global_load_lds_dwordx4 v0, s[20:21]
	s_mov_b32 m0, s63
	v_lshl_add_u64 v[252:253], s[22:23], 0, v[132:133]
	global_load_lds_dwordx4 v2, s[56:57]
	s_add_i32 m0, s63, 0x2000
	s_nop 0
	global_load_lds_dwordx4 v0, s[56:57]
	v_lshl_add_u64 v[250:251], s[22:23], 0, v[134:135]
	s_mov_b32 m0, s27
	s_nop 0
	global_load_lds_dwordx4 v[250:251], off
	s_mov_b32 m0, s28
	s_nop 0
	global_load_lds_dwordx4 v[252:253], off
	s_waitcnt vmcnt(8)
	s_waitcnt lgkmcnt(0)
	s_setprio 1
	s_barrier
; #define PG8_STAGE(bufoff, gbase, voff) do { _Pragma("unroll") for (int _i = 0; _i < 2; ++_i) \
;         __builtin_amdgcn_global_load_lds((const unsigned*)((const char*)(gbase) + (voff)[_i]), (PG8_LAS unsigned*)(lds + (bufoff) + ldsw + _i * 8192), 16, 0, 0); } while (0)
; #define PG8_LDA(dst, b, h) do { _Pragma("unroll") for (int m = 0; m < 4; ++m) _Pragma("unroll") for (int k = 0; k < 2; ++k) dst[m][k] = *(const PG8_LAS bf16x8*)(lds + PG8_SA(b, h) + aoff + m * 2048 + k * 1024); } while (0)
; #define PG8_LDB(dst, b, h) do { _Pragma("unroll") for (int n = 0; n < 2; ++n) _Pragma("unroll") for (int k = 0; k < 2; ++k) dst[n][k] = *(const PG8_LAS bf16x8*)(lds + PG8_SB(b, h) + boff + n * 2048 + k * 1024); } while (0)
; #define PG8_MMA(ai, bj, At, Bt) do { __builtin_amdgcn_s_setprio(1); _Pragma("unroll") for (int m = 0; m < 4; ++m) _Pragma("unroll") for (int n = 0; n < 2; ++n) _Pragma("unroll") for (int k = 0; k < 2; ++k) \
;         acc[ai][bj][m][n] = __builtin_amdgcn_mfma_f32_16x16x32_bf16(Bt[n][k], At[m][k], acc[ai][bj][m][n], 0, 0, 0); __builtin_amdgcn_s_setprio(0); } while (0)
; #define PG8_WAIT_V(n) asm volatile("s_waitcnt vmcnt(" #n ")" ::: "memory")
; #define PG8_WAIT_L(n) asm volatile("s_waitcnt lgkmcnt(" #n ")" ::: "memory")
; #define PG8_BAR __builtin_amdgcn_s_barrier()
; #define PG8_SCHED __builtin_amdgcn_sched_barrier(0)
; template <class Epi, class Sched, bool ALIGN_EPI = false, bool SP2 = false>
; __device__ __forceinline__ void gemm_phase(PG8_LAS unsigned char* lds, const Gemm g, const Sched& S, const Epi& E) {
;     ...
;             PG8_WAIT_V(8); PG8_WAIT_L(0); PG8_BAR; PG8_MMA(1, 0, At, B0); PG8_MMA(1, 1, At, B1); PG8_BAR; PG8_SCHED;
;             PG8_LDB(B0, 1, 0); PG8_LDB(B1, 1, 1); PG8_SCHED; PG8_LDA(At, 1, 0); PG8_STAGE(PG8_SA(0, 1), a2 + hstep, voffA);
;             PG8_WAIT_V(8); PG8_WAIT_L(0); PG8_BAR; PG8_MMA(0, 0, At, B0); PG8_MMA(0, 1, At, B1); PG8_BAR; PG8_SCHED;
	v_mfma_f32_16x16x32_bf16 v[64:67], v[184:187], v[216:219], 0
	v_mfma_f32_16x16x32_bf16 v[56:59], v[192:195], v[216:219], 0
	v_mfma_f32_16x16x32_bf16 v[48:51], v[184:187], v[224:227], 0
	v_mfma_f32_16x16x32_bf16 v[40:43], v[192:195], v[224:227], 0
	v_mfma_f32_16x16x32_bf16 v[32:35], v[184:187], v[232:235], 0
	v_mfma_f32_16x16x32_bf16 v[24:27], v[192:195], v[232:235], 0
	v_mfma_f32_16x16x32_bf16 v[16:19], v[184:187], v[240:243], 0
	v_mfma_f32_16x16x32_bf16 v[8:11], v[192:195], v[240:243], 0
	v_mfma_f32_16x16x32_bf16 v[64:67], v[188:191], v[220:223], v[64:67]
	v_mfma_f32_16x16x32_bf16 v[56:59], v[196:199], v[220:223], v[56:59]
	v_mfma_f32_16x16x32_bf16 v[48:51], v[188:191], v[228:231], v[48:51]
	v_mfma_f32_16x16x32_bf16 v[40:43], v[196:199], v[228:231], v[40:43]
	v_mfma_f32_16x16x32_bf16 v[32:35], v[188:191], v[236:239], v[32:35]
	v_mfma_f32_16x16x32_bf16 v[24:27], v[196:199], v[236:239], v[24:27]
	v_mfma_f32_16x16x32_bf16 v[16:19], v[188:191], v[244:247], v[16:19]
	v_mfma_f32_16x16x32_bf16 v[8:11], v[196:199], v[244:247], v[8:11]
	v_mfma_f32_16x16x32_bf16 v[60:63], v[200:203], v[216:219], 0
	v_mfma_f32_16x16x32_bf16 v[52:55], v[208:211], v[216:219], 0
	v_mfma_f32_16x16x32_bf16 v[44:47], v[200:203], v[224:227], 0
	v_mfma_f32_16x16x32_bf16 v[36:39], v[208:211], v[224:227], 0
	v_mfma_f32_16x16x32_bf16 v[28:31], v[200:203], v[232:235], 0
	v_mfma_f32_16x16x32_bf16 v[20:23], v[208:211], v[232:235], 0
	v_mfma_f32_16x16x32_bf16 v[12:15], v[200:203], v[240:243], 0
	v_mfma_f32_16x16x32_bf16 v[4:7], v[208:211], v[240:243], 0
	v_mfma_f32_16x16x32_bf16 v[60:63], v[204:207], v[220:223], v[60:63]
	v_mfma_f32_16x16x32_bf16 v[52:55], v[212:215], v[220:223], v[52:55]
	v_mfma_f32_16x16x32_bf16 v[44:47], v[204:207], v[228:231], v[44:47]
	v_mfma_f32_16x16x32_bf16 v[36:39], v[212:215], v[228:231], v[36:39]
	v_mfma_f32_16x16x32_bf16 v[28:31], v[204:207], v[236:239], v[28:31]
	v_mfma_f32_16x16x32_bf16 v[20:23], v[212:215], v[236:239], v[20:23]
	v_mfma_f32_16x16x32_bf16 v[12:15], v[204:207], v[244:247], v[12:15]
	v_mfma_f32_16x16x32_bf16 v[4:7], v[212:215], v[244:247], v[4:7]
	s_barrier
	s_setprio 0
	s_add_i32 s56, 0, 0x18000
	s_add_i32 s57, 0, 0x1c000
	ds_read_b128 v[184:187], v248
	ds_read_b128 v[188:191], v248 offset:1024
	ds_read_b128 v[192:195], v248 offset:2048
	ds_read_b128 v[196:199], v248 offset:3072
	ds_read_b128 v[200:203], v249
	ds_read_b128 v[204:207], v249 offset:1024
	ds_read_b128 v[208:211], v249 offset:2048
	ds_read_b128 v[212:215], v249 offset:3072
	s_add_u32 s22, s22, 0x80000
	s_addc_u32 s23, s23, 0
	s_mov_b32 m0, s29
	ds_read_b128 v[216:219], v155 offset:32768
	ds_read_b128 v[220:223], v155 offset:33792
	ds_read_b128 v[224:227], v155 offset:34816
	ds_read_b128 v[228:231], v155 offset:35840
	ds_read_b128 v[232:235], v155 offset:36864
	ds_read_b128 v[236:239], v155 offset:37888
	ds_read_b128 v[240:243], v155 offset:38912
	ds_read_b128 v[244:247], v155 offset:39936
	global_load_lds_dwordx4 v134, s[22:23]
	s_mov_b32 m0, s30
	s_nop 0
	global_load_lds_dwordx4 v132, s[22:23]
	s_waitcnt vmcnt(8)
	s_waitcnt lgkmcnt(0)
	s_setprio 1
	s_barrier
	v_mfma_f32_16x16x32_bf16 v[128:131], v[184:187], v[216:219], v[128:131]
	v_mfma_f32_16x16x32_bf16 v[120:123], v[192:195], v[216:219], v[120:123]
	v_mfma_f32_16x16x32_bf16 v[112:115], v[184:187], v[224:227], v[112:115]
	v_mfma_f32_16x16x32_bf16 v[104:107], v[192:195], v[224:227], v[104:107]
	v_mfma_f32_16x16x32_bf16 v[96:99], v[184:187], v[232:235], v[96:99]
	v_mfma_f32_16x16x32_bf16 v[88:91], v[192:195], v[232:235], v[88:91]
	v_mfma_f32_16x16x32_bf16 v[80:83], v[184:187], v[240:243], v[80:83]
	v_mfma_f32_16x16x32_bf16 v[72:75], v[192:195], v[240:243], v[72:75]
	v_mfma_f32_16x16x32_bf16 v[128:131], v[188:191], v[220:223], v[128:131]
	v_mfma_f32_16x16x32_bf16 v[120:123], v[196:199], v[220:223], v[120:123]
	v_mfma_f32_16x16x32_bf16 v[112:115], v[188:191], v[228:231], v[112:115]
	v_mfma_f32_16x16x32_bf16 v[104:107], v[196:199], v[228:231], v[104:107]
	v_mfma_f32_16x16x32_bf16 v[96:99], v[188:191], v[236:239], v[96:99]
	v_mfma_f32_16x16x32_bf16 v[88:91], v[196:199], v[236:239], v[88:91]
	v_mfma_f32_16x16x32_bf16 v[80:83], v[188:191], v[244:247], v[80:83]
	v_mfma_f32_16x16x32_bf16 v[72:75], v[196:199], v[244:247], v[72:75]
	v_mfma_f32_16x16x32_bf16 v[124:127], v[200:203], v[216:219], v[124:127]
	v_mfma_f32_16x16x32_bf16 v[116:119], v[208:211], v[216:219], v[116:119]
	v_mfma_f32_16x16x32_bf16 v[108:111], v[200:203], v[224:227], v[108:111]
	v_mfma_f32_16x16x32_bf16 v[100:103], v[208:211], v[224:227], v[100:103]
	v_mfma_f32_16x16x32_bf16 v[92:95], v[200:203], v[232:235], v[92:95]
	v_mfma_f32_16x16x32_bf16 v[84:87], v[208:211], v[232:235], v[84:87]
	v_mfma_f32_16x16x32_bf16 v[76:79], v[200:203], v[240:243], v[76:79]
	v_mfma_f32_16x16x32_bf16 v[68:71], v[208:211], v[240:243], v[68:71]
	v_mfma_f32_16x16x32_bf16 v[124:127], v[204:207], v[220:223], v[124:127]
	v_mfma_f32_16x16x32_bf16 v[116:119], v[212:215], v[220:223], v[116:119]
	v_mfma_f32_16x16x32_bf16 v[108:111], v[204:207], v[228:231], v[108:111]
	v_mfma_f32_16x16x32_bf16 v[100:103], v[212:215], v[228:231], v[100:103]
	v_mfma_f32_16x16x32_bf16 v[92:95], v[204:207], v[236:239], v[92:95]
	v_mfma_f32_16x16x32_bf16 v[84:87], v[212:215], v[236:239], v[84:87]
	v_mfma_f32_16x16x32_bf16 v[76:79], v[204:207], v[244:247], v[76:79]
	v_mfma_f32_16x16x32_bf16 v[68:71], v[212:215], v[244:247], v[68:71]
	s_barrier
; #define PG8_STAGE(bufoff, gbase, voff) do { _Pragma("unroll") for (int _i = 0; _i < 2; ++_i) \
;         __builtin_amdgcn_global_load_lds((const unsigned*)((const char*)(gbase) + (voff)[_i]), (PG8_LAS unsigned*)(lds + (bufoff) + ldsw + _i * 8192), 16, 0, 0); } while (0)
; #define PG8_LDA(dst, b, h) do { _Pragma("unroll") for (int m = 0; m < 4; ++m) _Pragma("unroll") for (int k = 0; k < 2; ++k) dst[m][k] = *(const PG8_LAS bf16x8*)(lds + PG8_SA(b, h) + aoff + m * 2048 + k * 1024); } while (0)
; #define PG8_LDB(dst, b, h) do { _Pragma("unroll") for (int n = 0; n < 2; ++n) _Pragma("unroll") for (int k = 0; k < 2; ++k) dst[n][k] = *(const PG8_LAS bf16x8*)(lds + PG8_SB(b, h) + boff + n * 2048 + k * 1024); } while (0)
; #define PG8_MMA(ai, bj, At, Bt) do { __builtin_amdgcn_s_setprio(1); _Pragma("unroll") for (int m = 0; m < 4; ++m) _Pragma("unroll") for (int n = 0; n < 2; ++n) _Pragma("unroll") for (int k = 0; k < 2; ++k) \
;         acc[ai][bj][m][n] = __builtin_amdgcn_mfma_f32_16x16x32_bf16(Bt[n][k], At[m][k], acc[ai][bj][m][n], 0, 0, 0); __builtin_amdgcn_s_setprio(0); } while (0)
; #define PG8_WAIT_V(n) asm volatile("s_waitcnt vmcnt(" #n ")" ::: "memory")
; #define PG8_WAIT_L(n) asm volatile("s_waitcnt lgkmcnt(" #n ")" ::: "memory")
; #define PG8_BAR __builtin_amdgcn_s_barrier()
; #define PG8_SCHED __builtin_amdgcn_sched_barrier(0)
; template <class Epi, class Sched, bool ALIGN_EPI = false, bool SP2 = false>
; __device__ __forceinline__ void gemm_phase(PG8_LAS unsigned char* lds, const Gemm g, const Sched& S, const Epi& E) {
;     ...
;             PG8_LDB(B0, 0, 0); PG8_LDB(B1, 0, 1); PG8_SCHED; PG8_LDA(At, 0, 0); PG8_STAGE(PG8_SA(1, 1), a1 + hstep, voffA);
;             PG8_WAIT_V(8); PG8_WAIT_L(0); PG8_BAR; PG8_MMA(0, 0, At, B0); PG8_MMA(0, 1, At, B1); PG8_BAR; PG8_SCHED;
;     ...
;             PG8_LDA(At, 1, 1); PG8_STAGE(PG8_SB(1, 0), b3, voffB); PG8_STAGE(PG8_SB(1, 1), b3 + hstep, voffB); PG8_STAGE(PG8_SA(1, 0), a3, voffA);
;             PG8_WAIT_V(8); PG8_WAIT_L(0); PG8_BAR; PG8_MMA(1, 0, At, B0); PG8_MMA(1, 1, At, B1); PG8_BAR; PG8_SCHED;
	s_setprio 0
	s_add_i32 s22, s56, s25
	s_mov_b32 m0, s22
	ds_read_b128 v[216:219], v155 offset:49152
	ds_read_b128 v[220:223], v155 offset:50176
	ds_read_b128 v[224:227], v155 offset:51200
	ds_read_b128 v[228:231], v155 offset:52224
	ds_read_b128 v[232:235], v155 offset:53248
	ds_read_b128 v[236:239], v155 offset:54272
	ds_read_b128 v[240:243], v155 offset:55296
	ds_read_b128 v[244:247], v155 offset:56320
	s_add_u32 vcc_lo, s20, 0x80
	s_addc_u32 vcc_hi, s21, 0
	global_load_lds_dwordx4 v2, vcc
	s_add_i32 m0, s22, 0x2000
	s_add_u32 s20, s20, 0x80080
	s_addc_u32 s21, s21, 0
	s_add_i32 s22, s57, s25
	s_add_u32 vcc_lo, s20, 0xfff80000
	s_addc_u32 vcc_hi, s21, -1
	global_load_lds_dwordx4 v0, vcc
	s_mov_b32 m0, s22
	s_nop 0
	global_load_lds_dwordx4 v2, s[20:21]
	s_add_i32 m0, s22, 0x2000
	s_nop 0
	global_load_lds_dwordx4 v0, s[20:21]
	v_lshl_add_u64 v[150:151], v[250:251], 0, s[36:37]
	s_mov_b32 m0, s31
	s_nop 0
	global_load_lds_dwordx4 v[150:151], off
	v_lshl_add_u64 v[150:151], v[252:253], 0, s[36:37]
	s_mov_b32 m0, s34
	s_nop 0
	global_load_lds_dwordx4 v[150:151], off
	s_waitcnt vmcnt(8)
	s_waitcnt lgkmcnt(0)
	s_setprio 1
	s_barrier
	v_mfma_f32_16x16x32_bf16 v[64:67], v[184:187], v[216:219], v[64:67]
	v_mfma_f32_16x16x32_bf16 v[56:59], v[192:195], v[216:219], v[56:59]
	v_mfma_f32_16x16x32_bf16 v[48:51], v[184:187], v[224:227], v[48:51]
	v_mfma_f32_16x16x32_bf16 v[40:43], v[192:195], v[224:227], v[40:43]
	v_mfma_f32_16x16x32_bf16 v[32:35], v[184:187], v[232:235], v[32:35]
	v_mfma_f32_16x16x32_bf16 v[24:27], v[192:195], v[232:235], v[24:27]
	v_mfma_f32_16x16x32_bf16 v[16:19], v[184:187], v[240:243], v[16:19]
	v_mfma_f32_16x16x32_bf16 v[8:11], v[192:195], v[240:243], v[8:11]
	v_mfma_f32_16x16x32_bf16 v[64:67], v[188:191], v[220:223], v[64:67]
	v_mfma_f32_16x16x32_bf16 v[56:59], v[196:199], v[220:223], v[56:59]
	v_mfma_f32_16x16x32_bf16 v[48:51], v[188:191], v[228:231], v[48:51]
	v_mfma_f32_16x16x32_bf16 v[40:43], v[196:199], v[228:231], v[40:43]
	v_mfma_f32_16x16x32_bf16 v[32:35], v[188:191], v[236:239], v[32:35]
	v_mfma_f32_16x16x32_bf16 v[24:27], v[196:199], v[236:239], v[24:27]
	v_mfma_f32_16x16x32_bf16 v[16:19], v[188:191], v[244:247], v[16:19]
	v_mfma_f32_16x16x32_bf16 v[8:11], v[196:199], v[244:247], v[8:11]
	v_mfma_f32_16x16x32_bf16 v[60:63], v[200:203], v[216:219], v[60:63]
	v_mfma_f32_16x16x32_bf16 v[52:55], v[208:211], v[216:219], v[52:55]
	v_mfma_f32_16x16x32_bf16 v[44:47], v[200:203], v[224:227], v[44:47]
	v_mfma_f32_16x16x32_bf16 v[36:39], v[208:211], v[224:227], v[36:39]
	v_mfma_f32_16x16x32_bf16 v[28:31], v[200:203], v[232:235], v[28:31]
	v_mfma_f32_16x16x32_bf16 v[20:23], v[208:211], v[232:235], v[20:23]
	v_mfma_f32_16x16x32_bf16 v[12:15], v[200:203], v[240:243], v[12:15]
	v_mfma_f32_16x16x32_bf16 v[4:7], v[208:211], v[240:243], v[4:7]
	v_mfma_f32_16x16x32_bf16 v[60:63], v[204:207], v[220:223], v[60:63]
	v_mfma_f32_16x16x32_bf16 v[52:55], v[212:215], v[220:223], v[52:55]
	v_mfma_f32_16x16x32_bf16 v[44:47], v[204:207], v[228:231], v[44:47]
	v_mfma_f32_16x16x32_bf16 v[36:39], v[212:215], v[228:231], v[36:39]
	v_mfma_f32_16x16x32_bf16 v[28:31], v[204:207], v[236:239], v[28:31]
	v_mfma_f32_16x16x32_bf16 v[20:23], v[212:215], v[236:239], v[20:23]
	v_mfma_f32_16x16x32_bf16 v[12:15], v[204:207], v[244:247], v[12:15]
	v_mfma_f32_16x16x32_bf16 v[4:7], v[212:215], v[244:247], v[4:7]
	s_barrier
	s_setprio 0
	s_add_i32 s51, s51, 2
	s_add_u32 s18, s18, 0x100
	s_addc_u32 s19, s19, 0
	s_add_u32 s45, s45, 0x100
	s_addc_u32 s50, s50, 0
	s_cmp_gt_u32 s51, 29
.LBB0_85:
	s_add_u32 s20, s18, 0xfff80080
	s_addc_u32 s21, s19, -1
	s_add_i32 s56, 0, 0x10000
	s_cmp_eq_u32 s51, 28
	s_cselect_b32 s23, s11, s21
	s_cselect_b32 s22, s42, s20
	s_cselect_b32 s21, s9, s50
	s_cselect_b32 s20, s44, s45
	s_add_i32 s63, 0, 0x14000
	ds_read_b128 v[184:187], v166
	ds_read_b128 v[188:191], v166 offset:1024
	ds_read_b128 v[192:195], v166 offset:2048
	ds_read_b128 v[196:199], v166 offset:3072
	ds_read_b128 v[200:203], v167
	ds_read_b128 v[204:207], v167 offset:1024
	ds_read_b128 v[208:211], v167 offset:2048
	ds_read_b128 v[212:215], v167 offset:3072
	s_add_i32 m0, s27, 0xc000
	ds_read_b128 v[216:219], v155
	ds_read_b128 v[220:223], v155 offset:1024
	ds_read_b128 v[224:227], v155 offset:2048
	ds_read_b128 v[228:231], v155 offset:3072
	ds_read_b128 v[232:235], v155 offset:4096
	ds_read_b128 v[236:239], v155 offset:5120
	ds_read_b128 v[240:243], v155 offset:6144
	ds_read_b128 v[244:247], v155 offset:7168
	global_load_lds_dwordx4 v136, s[18:19]
	s_add_i32 m0, s27, 0xe000
	s_nop 0
	global_load_lds_dwordx4 v138, s[18:19]
	s_waitcnt vmcnt(8)
	s_waitcnt lgkmcnt(0)
	s_setprio 1
	s_barrier
; #define PG8_STAGE(bufoff, gbase, voff) do { _Pragma("unroll") for (int _i = 0; _i < 2; ++_i) \
;         __builtin_amdgcn_global_load_lds((const unsigned*)((const char*)(gbase) + (voff)[_i]), (PG8_LAS unsigned*)(lds + (bufoff) + ldsw + _i * 8192), 16, 0, 0); } while (0)
; #define PG8_LDA(dst, b, h) do { _Pragma("unroll") for (int m = 0; m < 4; ++m) _Pragma("unroll") for (int k = 0; k < 2; ++k) dst[m][k] = *(const PG8_LAS bf16x8*)(lds + PG8_SA(b, h) + aoff + m * 2048 + k * 1024); } while (0)
; #define PG8_LDB(dst, b, h) do { _Pragma("unroll") for (int n = 0; n < 2; ++n) _Pragma("unroll") for (int k = 0; k < 2; ++k) dst[n][k] = *(const PG8_LAS bf16x8*)(lds + PG8_SB(b, h) + boff + n * 2048 + k * 1024); } while (0)
; #define PG8_MMA(ai, bj, At, Bt) do { __builtin_amdgcn_s_setprio(1); _Pragma("unroll") for (int m = 0; m < 4; ++m) _Pragma("unroll") for (int n = 0; n < 2; ++n) _Pragma("unroll") for (int k = 0; k < 2; ++k) \
;         acc[ai][bj][m][n] = __builtin_amdgcn_mfma_f32_16x16x32_bf16(Bt[n][k], At[m][k], acc[ai][bj][m][n], 0, 0, 0); __builtin_amdgcn_s_setprio(0); } while (0)
; #define PG8_WAIT_V(n) asm volatile("s_waitcnt vmcnt(" #n ")" ::: "memory")
; #define PG8_WAIT_L(n) asm volatile("s_waitcnt lgkmcnt(" #n ")" ::: "memory")
; #define PG8_BAR __builtin_amdgcn_s_barrier()
; #define PG8_SCHED __builtin_amdgcn_sched_barrier(0)
; template <class Epi, class Sched, bool ALIGN_EPI = false, bool SP2 = false>
; __device__ __forceinline__ void gemm_phase(PG8_LAS unsigned char* lds, const Gemm g, const Sched& S, const Epi& E) {
;     ...
;             PG8_WAIT_V(8); PG8_WAIT_L(0); PG8_BAR; PG8_MMA(0, 0, At, B0); PG8_MMA(0, 1, At, B1); PG8_BAR; PG8_SCHED;
;             PG8_LDA(At, 0, 1); PG8_STAGE(PG8_SB(0, 0), b2, voffB); PG8_STAGE(PG8_SB(0, 1), b2 + hstep, voffB); PG8_STAGE(PG8_SA(0, 0), a2, voffA);
;             PG8_WAIT_V(8); PG8_WAIT_L(0); PG8_BAR; PG8_MMA(1, 0, At, B0); PG8_MMA(1, 1, At, B1); PG8_BAR; PG8_SCHED;
;             PG8_LDB(B0, 1, 0); PG8_LDB(B1, 1, 1); PG8_SCHED; PG8_LDA(At, 1, 0); PG8_STAGE(PG8_SA(0, 1), a2 + hstep, voffA);
;             PG8_WAIT_V(8); PG8_WAIT_L(0); PG8_BAR; PG8_MMA(0, 0, At, B0); PG8_MMA(0, 1, At, B1); PG8_BAR; PG8_SCHED;
	v_mfma_f32_16x16x32_bf16 v[128:131], v[184:187], v[216:219], v[128:131]
	v_mfma_f32_16x16x32_bf16 v[120:123], v[192:195], v[216:219], v[120:123]
	v_mfma_f32_16x16x32_bf16 v[112:115], v[184:187], v[224:227], v[112:115]
	v_mfma_f32_16x16x32_bf16 v[104:107], v[192:195], v[224:227], v[104:107]
	v_mfma_f32_16x16x32_bf16 v[96:99], v[184:187], v[232:235], v[96:99]
	v_mfma_f32_16x16x32_bf16 v[88:91], v[192:195], v[232:235], v[88:91]
	v_mfma_f32_16x16x32_bf16 v[80:83], v[184:187], v[240:243], v[80:83]
	v_mfma_f32_16x16x32_bf16 v[72:75], v[192:195], v[240:243], v[72:75]
	v_mfma_f32_16x16x32_bf16 v[128:131], v[188:191], v[220:223], v[128:131]
	v_mfma_f32_16x16x32_bf16 v[120:123], v[196:199], v[220:223], v[120:123]
	v_mfma_f32_16x16x32_bf16 v[112:115], v[188:191], v[228:231], v[112:115]
	v_mfma_f32_16x16x32_bf16 v[104:107], v[196:199], v[228:231], v[104:107]
	v_mfma_f32_16x16x32_bf16 v[96:99], v[188:191], v[236:239], v[96:99]
	v_mfma_f32_16x16x32_bf16 v[88:91], v[196:199], v[236:239], v[88:91]
	v_mfma_f32_16x16x32_bf16 v[80:83], v[188:191], v[244:247], v[80:83]
	v_mfma_f32_16x16x32_bf16 v[72:75], v[196:199], v[244:247], v[72:75]
	v_mfma_f32_16x16x32_bf16 v[124:127], v[200:203], v[216:219], v[124:127]
	v_mfma_f32_16x16x32_bf16 v[116:119], v[208:211], v[216:219], v[116:119]
	v_mfma_f32_16x16x32_bf16 v[108:111], v[200:203], v[224:227], v[108:111]
	v_mfma_f32_16x16x32_bf16 v[100:103], v[208:211], v[224:227], v[100:103]
	v_mfma_f32_16x16x32_bf16 v[92:95], v[200:203], v[232:235], v[92:95]
	v_mfma_f32_16x16x32_bf16 v[84:87], v[208:211], v[232:235], v[84:87]
	v_mfma_f32_16x16x32_bf16 v[76:79], v[200:203], v[240:243], v[76:79]
	v_mfma_f32_16x16x32_bf16 v[68:71], v[208:211], v[240:243], v[68:71]
	v_mfma_f32_16x16x32_bf16 v[124:127], v[204:207], v[220:223], v[124:127]
	v_mfma_f32_16x16x32_bf16 v[116:119], v[212:215], v[220:223], v[116:119]
	v_mfma_f32_16x16x32_bf16 v[108:111], v[204:207], v[228:231], v[108:111]
	v_mfma_f32_16x16x32_bf16 v[100:103], v[212:215], v[228:231], v[100:103]
	v_mfma_f32_16x16x32_bf16 v[92:95], v[204:207], v[236:239], v[92:95]
	v_mfma_f32_16x16x32_bf16 v[84:87], v[212:215], v[236:239], v[84:87]
	v_mfma_f32_16x16x32_bf16 v[76:79], v[204:207], v[244:247], v[76:79]
	v_mfma_f32_16x16x32_bf16 v[68:71], v[212:215], v[244:247], v[68:71]
	s_barrier
	s_setprio 0
	s_add_i32 s56, s56, s25
	s_mov_b32 m0, s56
	ds_read_b128 v[216:219], v155 offset:16384
	ds_read_b128 v[220:223], v155 offset:17408
	ds_read_b128 v[224:227], v155 offset:18432
	ds_read_b128 v[228:231], v155 offset:19456
	ds_read_b128 v[232:235], v155 offset:20480
	ds_read_b128 v[236:239], v155 offset:21504
	ds_read_b128 v[240:243], v155 offset:22528
	ds_read_b128 v[244:247], v155 offset:23552
	global_load_lds_dwordx4 v2, s[20:21]
	s_add_i32 m0, s56, 0x2000
	s_add_u32 s56, s20, 0x80000
	s_addc_u32 s57, s21, 0
	s_add_i32 s63, s63, s25
	global_load_lds_dwordx4 v0, s[20:21]
	s_mov_b32 m0, s63
	v_lshl_add_u64 v[252:253], s[22:23], 0, v[132:133]
	global_load_lds_dwordx4 v2, s[56:57]
	s_add_i32 m0, s63, 0x2000
	s_nop 0
	global_load_lds_dwordx4 v0, s[56:57]
	v_lshl_add_u64 v[250:251], s[22:23], 0, v[134:135]
	s_mov_b32 m0, s27
	s_nop 0
	global_load_lds_dwordx4 v[250:251], off
	s_mov_b32 m0, s28
	s_nop 0
	global_load_lds_dwordx4 v[252:253], off
	s_waitcnt vmcnt(8)
	s_waitcnt lgkmcnt(0)
	s_setprio 1
	s_barrier
	v_mfma_f32_16x16x32_bf16 v[64:67], v[184:187], v[216:219], v[64:67]
	v_mfma_f32_16x16x32_bf16 v[56:59], v[192:195], v[216:219], v[56:59]
	v_mfma_f32_16x16x32_bf16 v[48:51], v[184:187], v[224:227], v[48:51]
	v_mfma_f32_16x16x32_bf16 v[40:43], v[192:195], v[224:227], v[40:43]
	v_mfma_f32_16x16x32_bf16 v[32:35], v[184:187], v[232:235], v[32:35]
	v_mfma_f32_16x16x32_bf16 v[24:27], v[192:195], v[232:235], v[24:27]
	v_mfma_f32_16x16x32_bf16 v[16:19], v[184:187], v[240:243], v[16:19]
	v_mfma_f32_16x16x32_bf16 v[8:11], v[192:195], v[240:243], v[8:11]
	v_mfma_f32_16x16x32_bf16 v[64:67], v[188:191], v[220:223], v[64:67]
	v_mfma_f32_16x16x32_bf16 v[56:59], v[196:199], v[220:223], v[56:59]
	v_mfma_f32_16x16x32_bf16 v[48:51], v[188:191], v[228:231], v[48:51]
	v_mfma_f32_16x16x32_bf16 v[40:43], v[196:199], v[228:231], v[40:43]
	v_mfma_f32_16x16x32_bf16 v[32:35], v[188:191], v[236:239], v[32:35]
	v_mfma_f32_16x16x32_bf16 v[24:27], v[196:199], v[236:239], v[24:27]
	v_mfma_f32_16x16x32_bf16 v[16:19], v[188:191], v[244:247], v[16:19]
	v_mfma_f32_16x16x32_bf16 v[8:11], v[196:199], v[244:247], v[8:11]
	v_mfma_f32_16x16x32_bf16 v[60:63], v[200:203], v[216:219], v[60:63]
	v_mfma_f32_16x16x32_bf16 v[52:55], v[208:211], v[216:219], v[52:55]
	v_mfma_f32_16x16x32_bf16 v[44:47], v[200:203], v[224:227], v[44:47]
	v_mfma_f32_16x16x32_bf16 v[36:39], v[208:211], v[224:227], v[36:39]
	v_mfma_f32_16x16x32_bf16 v[28:31], v[200:203], v[232:235], v[28:31]
	v_mfma_f32_16x16x32_bf16 v[20:23], v[208:211], v[232:235], v[20:23]
	v_mfma_f32_16x16x32_bf16 v[12:15], v[200:203], v[240:243], v[12:15]
	v_mfma_f32_16x16x32_bf16 v[4:7], v[208:211], v[240:243], v[4:7]
	v_mfma_f32_16x16x32_bf16 v[60:63], v[204:207], v[220:223], v[60:63]
	v_mfma_f32_16x16x32_bf16 v[52:55], v[212:215], v[220:223], v[52:55]
	v_mfma_f32_16x16x32_bf16 v[44:47], v[204:207], v[228:231], v[44:47]
	v_mfma_f32_16x16x32_bf16 v[36:39], v[212:215], v[228:231], v[36:39]
	v_mfma_f32_16x16x32_bf16 v[28:31], v[204:207], v[236:239], v[28:31]
	v_mfma_f32_16x16x32_bf16 v[20:23], v[212:215], v[236:239], v[20:23]
	v_mfma_f32_16x16x32_bf16 v[12:15], v[204:207], v[244:247], v[12:15]
	v_mfma_f32_16x16x32_bf16 v[4:7], v[212:215], v[244:247], v[4:7]
	s_barrier
; #define PG8_STAGE(bufoff, gbase, voff) do { _Pragma("unroll") for (int _i = 0; _i < 2; ++_i) \
;         __builtin_amdgcn_global_load_lds((const unsigned*)((const char*)(gbase) + (voff)[_i]), (PG8_LAS unsigned*)(lds + (bufoff) + ldsw + _i * 8192), 16, 0, 0); } while (0)
; #define PG8_LDA(dst, b, h) do { _Pragma("unroll") for (int m = 0; m < 4; ++m) _Pragma("unroll") for (int k = 0; k < 2; ++k) dst[m][k] = *(const PG8_LAS bf16x8*)(lds + PG8_SA(b, h) + aoff + m * 2048 + k * 1024); } while (0)
; #define PG8_LDB(dst, b, h) do { _Pragma("unroll") for (int n = 0; n < 2; ++n) _Pragma("unroll") for (int k = 0; k < 2; ++k) dst[n][k] = *(const PG8_LAS bf16x8*)(lds + PG8_SB(b, h) + boff + n * 2048 + k * 1024); } while (0)
; #define PG8_MMA(ai, bj, At, Bt) do { __builtin_amdgcn_s_setprio(1); _Pragma("unroll") for (int m = 0; m < 4; ++m) _Pragma("unroll") for (int n = 0; n < 2; ++n) _Pragma("unroll") for (int k = 0; k < 2; ++k) \
;         acc[ai][bj][m][n] = __builtin_amdgcn_mfma_f32_16x16x32_bf16(Bt[n][k], At[m][k], acc[ai][bj][m][n], 0, 0, 0); __builtin_amdgcn_s_setprio(0); } while (0)
; #define PG8_WAIT_V(n) asm volatile("s_waitcnt vmcnt(" #n ")" ::: "memory")
; #define PG8_WAIT_L(n) asm volatile("s_waitcnt lgkmcnt(" #n ")" ::: "memory")
; #define PG8_BAR __builtin_amdgcn_s_barrier()
; #define PG8_SCHED __builtin_amdgcn_sched_barrier(0)
; template <class Epi, class Sched, bool ALIGN_EPI = false, bool SP2 = false>
; __device__ __forceinline__ void gemm_phase(PG8_LAS unsigned char* lds, const Gemm g, const Sched& S, const Epi& E) {
;     ...
;             PG8_LDB(B0, 1, 0); PG8_LDB(B1, 1, 1); PG8_SCHED; PG8_LDA(At, 1, 0); PG8_STAGE(PG8_SA(0, 1), a2 + hstep, voffA);
;             PG8_WAIT_V(8); PG8_WAIT_L(0); PG8_BAR; PG8_MMA(0, 0, At, B0); PG8_MMA(0, 1, At, B1); PG8_BAR; PG8_SCHED;
;             PG8_LDA(At, 1, 1); PG8_STAGE(PG8_SB(1, 0), b3, voffB); PG8_STAGE(PG8_SB(1, 1), b3 + hstep, voffB); PG8_STAGE(PG8_SA(1, 0), a3, voffA);
;             PG8_WAIT_V(8); PG8_WAIT_L(0); PG8_BAR; PG8_MMA(1, 0, At, B0); PG8_MMA(1, 1, At, B1); PG8_BAR; PG8_SCHED;
;     ...
;         if constexpr (ALIGN_EPI) { if (wr == 0) PG8_BAR; }
	s_setprio 0
	s_add_i32 s56, 0, 0x18000
	s_add_i32 s57, 0, 0x1c000
	ds_read_b128 v[184:187], v248
	ds_read_b128 v[188:191], v248 offset:1024
	ds_read_b128 v[192:195], v248 offset:2048
	ds_read_b128 v[196:199], v248 offset:3072
	ds_read_b128 v[200:203], v249
	ds_read_b128 v[204:207], v249 offset:1024
	ds_read_b128 v[208:211], v249 offset:2048
	ds_read_b128 v[212:215], v249 offset:3072
	s_add_u32 s22, s22, 0x80000
	s_addc_u32 s23, s23, 0
	s_mov_b32 m0, s29
	ds_read_b128 v[216:219], v155 offset:32768
	ds_read_b128 v[220:223], v155 offset:33792
	ds_read_b128 v[224:227], v155 offset:34816
	ds_read_b128 v[228:231], v155 offset:35840
	ds_read_b128 v[232:235], v155 offset:36864
	ds_read_b128 v[236:239], v155 offset:37888
	ds_read_b128 v[240:243], v155 offset:38912
	ds_read_b128 v[244:247], v155 offset:39936
	global_load_lds_dwordx4 v134, s[22:23]
	s_mov_b32 m0, s30
	s_nop 0
	global_load_lds_dwordx4 v132, s[22:23]
	s_waitcnt vmcnt(8)
	s_waitcnt lgkmcnt(0)
	s_setprio 1
	s_barrier
	v_mfma_f32_16x16x32_bf16 v[128:131], v[184:187], v[216:219], v[128:131]
	v_mfma_f32_16x16x32_bf16 v[120:123], v[192:195], v[216:219], v[120:123]
	v_mfma_f32_16x16x32_bf16 v[112:115], v[184:187], v[224:227], v[112:115]
	v_mfma_f32_16x16x32_bf16 v[104:107], v[192:195], v[224:227], v[104:107]
	v_mfma_f32_16x16x32_bf16 v[96:99], v[184:187], v[232:235], v[96:99]
	v_mfma_f32_16x16x32_bf16 v[88:91], v[192:195], v[232:235], v[88:91]
	v_mfma_f32_16x16x32_bf16 v[80:83], v[184:187], v[240:243], v[80:83]
	v_mfma_f32_16x16x32_bf16 v[72:75], v[192:195], v[240:243], v[72:75]
	v_mfma_f32_16x16x32_bf16 v[128:131], v[188:191], v[220:223], v[128:131]
	v_mfma_f32_16x16x32_bf16 v[120:123], v[196:199], v[220:223], v[120:123]
	v_mfma_f32_16x16x32_bf16 v[112:115], v[188:191], v[228:231], v[112:115]
	v_mfma_f32_16x16x32_bf16 v[104:107], v[196:199], v[228:231], v[104:107]
	v_mfma_f32_16x16x32_bf16 v[96:99], v[188:191], v[236:239], v[96:99]
	v_mfma_f32_16x16x32_bf16 v[88:91], v[196:199], v[236:239], v[88:91]
	v_mfma_f32_16x16x32_bf16 v[80:83], v[188:191], v[244:247], v[80:83]
	v_mfma_f32_16x16x32_bf16 v[72:75], v[196:199], v[244:247], v[72:75]
	v_mfma_f32_16x16x32_bf16 v[124:127], v[200:203], v[216:219], v[124:127]
	v_mfma_f32_16x16x32_bf16 v[116:119], v[208:211], v[216:219], v[116:119]
	v_mfma_f32_16x16x32_bf16 v[108:111], v[200:203], v[224:227], v[108:111]
	v_mfma_f32_16x16x32_bf16 v[100:103], v[208:211], v[224:227], v[100:103]
	v_mfma_f32_16x16x32_bf16 v[92:95], v[200:203], v[232:235], v[92:95]
	v_mfma_f32_16x16x32_bf16 v[84:87], v[208:211], v[232:235], v[84:87]
	v_mfma_f32_16x16x32_bf16 v[76:79], v[200:203], v[240:243], v[76:79]
	v_mfma_f32_16x16x32_bf16 v[68:71], v[208:211], v[240:243], v[68:71]
	v_mfma_f32_16x16x32_bf16 v[124:127], v[204:207], v[220:223], v[124:127]
	v_mfma_f32_16x16x32_bf16 v[116:119], v[212:215], v[220:223], v[116:119]
	v_mfma_f32_16x16x32_bf16 v[108:111], v[204:207], v[228:231], v[108:111]
	v_mfma_f32_16x16x32_bf16 v[100:103], v[212:215], v[228:231], v[100:103]
	v_mfma_f32_16x16x32_bf16 v[92:95], v[204:207], v[236:239], v[92:95]
	v_mfma_f32_16x16x32_bf16 v[84:87], v[212:215], v[236:239], v[84:87]
	v_mfma_f32_16x16x32_bf16 v[76:79], v[204:207], v[244:247], v[76:79]
	v_mfma_f32_16x16x32_bf16 v[68:71], v[212:215], v[244:247], v[68:71]
	s_barrier
	s_setprio 0
	s_add_i32 s22, s56, s25
	s_mov_b32 m0, s22
	ds_read_b128 v[216:219], v155 offset:49152
	ds_read_b128 v[220:223], v155 offset:50176
	ds_read_b128 v[224:227], v155 offset:51200
	ds_read_b128 v[228:231], v155 offset:52224
	ds_read_b128 v[232:235], v155 offset:53248
	ds_read_b128 v[236:239], v155 offset:54272
	ds_read_b128 v[240:243], v155 offset:55296
	ds_read_b128 v[244:247], v155 offset:56320
	s_add_u32 vcc_lo, s20, 0x80
	s_addc_u32 vcc_hi, s21, 0
	global_load_lds_dwordx4 v2, vcc
	s_add_i32 m0, s22, 0x2000
	s_add_u32 s20, s20, 0x80080
	s_addc_u32 s21, s21, 0
	s_add_i32 s22, s57, s25
	s_add_u32 vcc_lo, s20, 0xfff80000
	s_addc_u32 vcc_hi, s21, -1
	global_load_lds_dwordx4 v0, vcc
	s_mov_b32 m0, s22
	s_nop 0
	global_load_lds_dwordx4 v2, s[20:21]
	s_add_i32 m0, s22, 0x2000
	s_nop 0
	global_load_lds_dwordx4 v0, s[20:21]
	v_lshl_add_u64 v[150:151], v[250:251], 0, s[36:37]
	s_mov_b32 m0, s31
	s_nop 0
	global_load_lds_dwordx4 v[150:151], off
	v_lshl_add_u64 v[150:151], v[252:253], 0, s[36:37]
	s_mov_b32 m0, s34
	s_nop 0
	global_load_lds_dwordx4 v[150:151], off
	s_waitcnt vmcnt(8)
	s_waitcnt lgkmcnt(0)
	s_setprio 1
	s_barrier
	v_mfma_f32_16x16x32_bf16 v[64:67], v[184:187], v[216:219], v[64:67]
	v_mfma_f32_16x16x32_bf16 v[56:59], v[192:195], v[216:219], v[56:59]
	v_mfma_f32_16x16x32_bf16 v[48:51], v[184:187], v[224:227], v[48:51]
	v_mfma_f32_16x16x32_bf16 v[40:43], v[192:195], v[224:227], v[40:43]
	v_mfma_f32_16x16x32_bf16 v[32:35], v[184:187], v[232:235], v[32:35]
	v_mfma_f32_16x16x32_bf16 v[24:27], v[192:195], v[232:235], v[24:27]
	v_mfma_f32_16x16x32_bf16 v[16:19], v[184:187], v[240:243], v[16:19]
	v_mfma_f32_16x16x32_bf16 v[8:11], v[192:195], v[240:243], v[8:11]
	v_mfma_f32_16x16x32_bf16 v[64:67], v[188:191], v[220:223], v[64:67]
	v_mfma_f32_16x16x32_bf16 v[56:59], v[196:199], v[220:223], v[56:59]
	v_mfma_f32_16x16x32_bf16 v[48:51], v[188:191], v[228:231], v[48:51]
	v_mfma_f32_16x16x32_bf16 v[40:43], v[196:199], v[228:231], v[40:43]
	v_mfma_f32_16x16x32_bf16 v[32:35], v[188:191], v[236:239], v[32:35]
	v_mfma_f32_16x16x32_bf16 v[24:27], v[196:199], v[236:239], v[24:27]
	v_mfma_f32_16x16x32_bf16 v[16:19], v[188:191], v[244:247], v[16:19]
	v_mfma_f32_16x16x32_bf16 v[8:11], v[196:199], v[244:247], v[8:11]
	v_mfma_f32_16x16x32_bf16 v[60:63], v[200:203], v[216:219], v[60:63]
	v_mfma_f32_16x16x32_bf16 v[52:55], v[208:211], v[216:219], v[52:55]
	v_mfma_f32_16x16x32_bf16 v[44:47], v[200:203], v[224:227], v[44:47]
	v_mfma_f32_16x16x32_bf16 v[36:39], v[208:211], v[224:227], v[36:39]
	v_mfma_f32_16x16x32_bf16 v[28:31], v[200:203], v[232:235], v[28:31]
	v_mfma_f32_16x16x32_bf16 v[20:23], v[208:211], v[232:235], v[20:23]
	v_mfma_f32_16x16x32_bf16 v[12:15], v[200:203], v[240:243], v[12:15]
	v_mfma_f32_16x16x32_bf16 v[4:7], v[208:211], v[240:243], v[4:7]
	v_mfma_f32_16x16x32_bf16 v[60:63], v[204:207], v[220:223], v[60:63]
	v_mfma_f32_16x16x32_bf16 v[52:55], v[212:215], v[220:223], v[52:55]
	v_mfma_f32_16x16x32_bf16 v[44:47], v[204:207], v[228:231], v[44:47]
	v_mfma_f32_16x16x32_bf16 v[36:39], v[212:215], v[228:231], v[36:39]
	v_mfma_f32_16x16x32_bf16 v[28:31], v[204:207], v[236:239], v[28:31]
	v_mfma_f32_16x16x32_bf16 v[20:23], v[212:215], v[236:239], v[20:23]
	v_mfma_f32_16x16x32_bf16 v[12:15], v[204:207], v[244:247], v[12:15]
	v_mfma_f32_16x16x32_bf16 v[4:7], v[212:215], v[244:247], v[4:7]
	s_barrier
	s_setprio 0
	s_add_i32 s51, s51, 2
	s_add_u32 s18, s18, 0x100
	s_addc_u32 s19, s19, 0
	s_add_u32 s45, s45, 0x100
	s_addc_u32 s50, s50, 0
	s_cmp_gt_u32 s51, 29
	s_cbranch_scc0 .LBB0_85
	s_and_b64 vcc, exec, s[6:7]
	s_cbranch_vccz .LBB0_88
	s_barrier

; #define PG8_STAGE(bufoff, gbase, voff) do { _Pragma("unroll") for (int _i = 0; _i < 2; ++_i) \
;         __builtin_amdgcn_global_load_lds((const unsigned*)((const char*)(gbase) + (voff)[_i]), (PG8_LAS unsigned*)(lds + (bufoff) + ldsw + _i * 8192), 16, 0, 0); } while (0)
; #define PG8_LDA(dst, b, h) do { _Pragma("unroll") for (int m = 0; m < 4; ++m) _Pragma("unroll") for (int k = 0; k < 2; ++k) dst[m][k] = *(const PG8_LAS bf16x8*)(lds + PG8_SA(b, h) + aoff + m * 2048 + k * 1024); } while (0)
; #define PG8_LDB(dst, b, h) do { _Pragma("unroll") for (int n = 0; n < 2; ++n) _Pragma("unroll") for (int k = 0; k < 2; ++k) dst[n][k] = *(const PG8_LAS bf16x8*)(lds + PG8_SB(b, h) + boff + n * 2048 + k * 1024); } while (0)
; #define PG8_MMA(ai, bj, At, Bt) do { __builtin_amdgcn_s_setprio(1); _Pragma("unroll") for (int m = 0; m < 4; ++m) _Pragma("unroll") for (int n = 0; n < 2; ++n) _Pragma("unroll") for (int k = 0; k < 2; ++k) \
;         acc[ai][bj][m][n] = __builtin_amdgcn_mfma_f32_16x16x32_bf16(Bt[n][k], At[m][k], acc[ai][bj][m][n], 0, 0, 0); __builtin_amdgcn_s_setprio(0); } while (0)
; #define PG8_WAIT_V(n) asm volatile("s_waitcnt vmcnt(" #n ")" ::: "memory")
; #define PG8_WAIT_L(n) asm volatile("s_waitcnt lgkmcnt(" #n ")" ::: "memory")
; #define PG8_BAR __builtin_amdgcn_s_barrier()
; #define PG8_SCHED __builtin_amdgcn_sched_barrier(0)
; template <class Epi, class Sched, bool ALIGN_EPI = false, bool SP2 = false>
; __device__ __forceinline__ void gemm_phase(PG8_LAS unsigned char* lds, const Gemm g, const Sched& S, const Epi& E) {
;     ...
;             PG8_LDB(B0, 0, 0); PG8_LDB(B1, 0, 1); PG8_SCHED; PG8_LDA(At, 0, 0); PG8_STAGE(PG8_SA(1, 1), a1 + hstep, voffA);
;             PG8_WAIT_V(8); PG8_WAIT_L(0); PG8_BAR; PG8_MMA(0, 0, At, B0); PG8_MMA(0, 1, At, B1); PG8_BAR; PG8_SCHED;
;             PG8_LDA(At, 0, 1); PG8_STAGE(PG8_SB(0, 0), b2, voffB); PG8_STAGE(PG8_SB(0, 1), b2 + hstep, voffB); PG8_STAGE(PG8_SA(0, 0), a2, voffA);
;             PG8_WAIT_V(8); PG8_WAIT_L(0); PG8_BAR; PG8_MMA(1, 0, At, B0); PG8_MMA(1, 1, At, B1); PG8_BAR; PG8_SCHED;
.LBB0_166:
	s_add_u32 s51, s16, 0x100
	s_addc_u32 s56, s17, 0
	s_mov_b32 s57, -2
	s_waitcnt lgkmcnt(0)
	v_add_u32_e32 v238, 0x10000, v185
	v_add_u32_e32 v239, 0x14000, v185
	v_add_u32_e32 v240, 0x18000, v185
	v_add_u32_e32 v241, 0x1c000, v185
	s_add_u32 s16, s14, 0x100
	s_addc_u32 s17, s15, 0
	s_add_i32 s63, 0, 0x10000
	s_cmpk_eq_i32 s57, 0x54
	s_cselect_b32 s21, s7, s17
	s_cselect_b32 s20, s6, s16
	s_cselect_b32 s19, s13, s56
	s_cselect_b32 s18, s12, s51
	s_add_i32 s64, 0, 0x14000
	ds_read_b128 v[132:135], v238
	ds_read_b128 v[136:139], v238 offset:1024
	ds_read_b128 v[158:161], v238 offset:2048
	ds_read_b128 v[162:165], v238 offset:3072
	ds_read_b128 v[188:191], v239
	ds_read_b128 v[192:195], v239 offset:1024
	ds_read_b128 v[196:199], v239 offset:2048
	ds_read_b128 v[200:203], v239 offset:3072
	s_add_i32 m0, s26, 0xc000
	ds_read_b128 v[204:207], v187
	ds_read_b128 v[208:211], v187 offset:1024
	ds_read_b128 v[212:215], v187 offset:2048
	ds_read_b128 v[216:219], v187 offset:3072
	ds_read_b128 v[220:223], v187 offset:4096
	ds_read_b128 v[224:227], v187 offset:5120
	ds_read_b128 v[228:231], v187 offset:6144
	ds_read_b128 v[232:235], v187 offset:7168
	global_load_lds_dwordx4 v154, s[14:15]
	s_add_i32 m0, s26, 0xe000
	s_nop 0
	global_load_lds_dwordx4 v156, s[14:15]
	s_waitcnt vmcnt(8)
	s_waitcnt lgkmcnt(0)
	s_setprio 1
	s_barrier
	v_mfma_f32_16x16x32_bf16 v[128:131], v[132:135], v[204:207], 0
	v_mfma_f32_16x16x32_bf16 v[124:127], v[158:161], v[204:207], 0
	v_mfma_f32_16x16x32_bf16 v[112:115], v[132:135], v[212:215], 0
	v_mfma_f32_16x16x32_bf16 v[108:111], v[158:161], v[212:215], 0
	v_mfma_f32_16x16x32_bf16 v[96:99], v[132:135], v[220:223], 0
	v_mfma_f32_16x16x32_bf16 v[92:95], v[158:161], v[220:223], 0
	v_mfma_f32_16x16x32_bf16 v[80:83], v[132:135], v[228:231], 0
	v_mfma_f32_16x16x32_bf16 v[76:79], v[158:161], v[228:231], 0
	v_mfma_f32_16x16x32_bf16 v[128:131], v[136:139], v[208:211], v[128:131]
	v_mfma_f32_16x16x32_bf16 v[124:127], v[162:165], v[208:211], v[124:127]
	v_mfma_f32_16x16x32_bf16 v[112:115], v[136:139], v[216:219], v[112:115]
	v_mfma_f32_16x16x32_bf16 v[108:111], v[162:165], v[216:219], v[108:111]
	v_mfma_f32_16x16x32_bf16 v[96:99], v[136:139], v[224:227], v[96:99]
	v_mfma_f32_16x16x32_bf16 v[92:95], v[162:165], v[224:227], v[92:95]
	v_mfma_f32_16x16x32_bf16 v[80:83], v[136:139], v[232:235], v[80:83]
	v_mfma_f32_16x16x32_bf16 v[76:79], v[162:165], v[232:235], v[76:79]
	v_mfma_f32_16x16x32_bf16 v[120:123], v[188:191], v[204:207], 0
	v_mfma_f32_16x16x32_bf16 v[116:119], v[196:199], v[204:207], 0
	v_mfma_f32_16x16x32_bf16 v[104:107], v[188:191], v[212:215], 0
	v_mfma_f32_16x16x32_bf16 v[100:103], v[196:199], v[212:215], 0
	v_mfma_f32_16x16x32_bf16 v[88:91], v[188:191], v[220:223], 0
	v_mfma_f32_16x16x32_bf16 v[84:87], v[196:199], v[220:223], 0
	v_mfma_f32_16x16x32_bf16 v[72:75], v[188:191], v[228:231], 0
	v_mfma_f32_16x16x32_bf16 v[68:71], v[196:199], v[228:231], 0
	v_mfma_f32_16x16x32_bf16 v[120:123], v[192:195], v[208:211], v[120:123]
	v_mfma_f32_16x16x32_bf16 v[116:119], v[200:203], v[208:211], v[116:119]
	v_mfma_f32_16x16x32_bf16 v[104:107], v[192:195], v[216:219], v[104:107]
	v_mfma_f32_16x16x32_bf16 v[100:103], v[200:203], v[216:219], v[100:103]
	v_mfma_f32_16x16x32_bf16 v[88:91], v[192:195], v[224:227], v[88:91]
	v_mfma_f32_16x16x32_bf16 v[84:87], v[200:203], v[224:227], v[84:87]
	v_mfma_f32_16x16x32_bf16 v[72:75], v[192:195], v[232:235], v[72:75]
	v_mfma_f32_16x16x32_bf16 v[68:71], v[200:203], v[232:235], v[68:71]
	s_barrier
	s_setprio 0
	s_add_i32 s14, s63, s25
	s_mov_b32 m0, s14
	ds_read_b128 v[204:207], v187 offset:16384
	ds_read_b128 v[208:211], v187 offset:17408
	ds_read_b128 v[212:215], v187 offset:18432
	ds_read_b128 v[216:219], v187 offset:19456
	ds_read_b128 v[220:223], v187 offset:20480
	ds_read_b128 v[224:227], v187 offset:21504
	ds_read_b128 v[228:231], v187 offset:22528
	ds_read_b128 v[232:235], v187 offset:23552
	global_load_lds_dwordx4 v2, s[18:19]
	s_add_i32 m0, s14, 0x2000
	s_add_u32 s14, s18, 0x160000
	v_lshl_add_u64 v[236:237], s[18:19], 0, v[152:153]
	s_addc_u32 s15, s19, 0
	s_add_i32 s63, s64, s25
	global_load_lds_dwordx4 v[236:237], off
	s_mov_b32 m0, s63
	s_nop 0
	global_load_lds_dwordx4 v2, s[14:15]
	s_add_i32 m0, s63, 0x2000
	s_nop 0
	global_load_lds_dwordx4 v152, s[14:15]
	s_mov_b32 m0, s26
	s_nop 0
	global_load_lds_dwordx4 v0, s[20:21]
	s_mov_b32 m0, s27
	s_nop 0
	global_load_lds_dwordx4 v150, s[20:21]
	s_waitcnt vmcnt(8)
	s_waitcnt lgkmcnt(0)
	s_setprio 1
	s_barrier
	v_mfma_f32_16x16x32_bf16 v[64:67], v[132:135], v[204:207], 0
	v_mfma_f32_16x16x32_bf16 v[60:63], v[158:161], v[204:207], 0
	v_mfma_f32_16x16x32_bf16 v[48:51], v[132:135], v[212:215], 0
	v_mfma_f32_16x16x32_bf16 v[44:47], v[158:161], v[212:215], 0
	v_mfma_f32_16x16x32_bf16 v[32:35], v[132:135], v[220:223], 0
	v_mfma_f32_16x16x32_bf16 v[28:31], v[158:161], v[220:223], 0
	v_mfma_f32_16x16x32_bf16 v[16:19], v[132:135], v[228:231], 0
	v_mfma_f32_16x16x32_bf16 v[12:15], v[158:161], v[228:231], 0
	v_mfma_f32_16x16x32_bf16 v[64:67], v[136:139], v[208:211], v[64:67]
	v_mfma_f32_16x16x32_bf16 v[60:63], v[162:165], v[208:211], v[60:63]
	v_mfma_f32_16x16x32_bf16 v[48:51], v[136:139], v[216:219], v[48:51]
	v_mfma_f32_16x16x32_bf16 v[44:47], v[162:165], v[216:219], v[44:47]
	v_mfma_f32_16x16x32_bf16 v[32:35], v[136:139], v[224:227], v[32:35]
	v_mfma_f32_16x16x32_bf16 v[28:31], v[162:165], v[224:227], v[28:31]
	v_mfma_f32_16x16x32_bf16 v[16:19], v[136:139], v[232:235], v[16:19]
	v_mfma_f32_16x16x32_bf16 v[12:15], v[162:165], v[232:235], v[12:15]
	v_mfma_f32_16x16x32_bf16 v[56:59], v[188:191], v[204:207], 0
	v_mfma_f32_16x16x32_bf16 v[52:55], v[196:199], v[204:207], 0
	v_mfma_f32_16x16x32_bf16 v[40:43], v[188:191], v[212:215], 0
	v_mfma_f32_16x16x32_bf16 v[36:39], v[196:199], v[212:215], 0
	v_mfma_f32_16x16x32_bf16 v[24:27], v[188:191], v[220:223], 0
	v_mfma_f32_16x16x32_bf16 v[20:23], v[196:199], v[220:223], 0
	v_mfma_f32_16x16x32_bf16 v[8:11], v[188:191], v[228:231], 0
	v_mfma_f32_16x16x32_bf16 v[4:7], v[196:199], v[228:231], 0
	v_mfma_f32_16x16x32_bf16 v[56:59], v[192:195], v[208:211], v[56:59]
	v_mfma_f32_16x16x32_bf16 v[52:55], v[200:203], v[208:211], v[52:55]
	v_mfma_f32_16x16x32_bf16 v[40:43], v[192:195], v[216:219], v[40:43]
	v_mfma_f32_16x16x32_bf16 v[36:39], v[200:203], v[216:219], v[36:39]
	v_mfma_f32_16x16x32_bf16 v[24:27], v[192:195], v[224:227], v[24:27]
	v_mfma_f32_16x16x32_bf16 v[20:23], v[200:203], v[224:227], v[20:23]
	v_mfma_f32_16x16x32_bf16 v[8:11], v[192:195], v[232:235], v[8:11]
	v_mfma_f32_16x16x32_bf16 v[4:7], v[200:203], v[232:235], v[4:7]
	s_barrier
; #define PG8_STAGE(bufoff, gbase, voff) do { _Pragma("unroll") for (int _i = 0; _i < 2; ++_i) \
;         __builtin_amdgcn_global_load_lds((const unsigned*)((const char*)(gbase) + (voff)[_i]), (PG8_LAS unsigned*)(lds + (bufoff) + ldsw + _i * 8192), 16, 0, 0); } while (0)
; #define PG8_LDA(dst, b, h) do { _Pragma("unroll") for (int m = 0; m < 4; ++m) _Pragma("unroll") for (int k = 0; k < 2; ++k) dst[m][k] = *(const PG8_LAS bf16x8*)(lds + PG8_SA(b, h) + aoff + m * 2048 + k * 1024); } while (0)
; #define PG8_LDB(dst, b, h) do { _Pragma("unroll") for (int n = 0; n < 2; ++n) _Pragma("unroll") for (int k = 0; k < 2; ++k) dst[n][k] = *(const PG8_LAS bf16x8*)(lds + PG8_SB(b, h) + boff + n * 2048 + k * 1024); } while (0)
; #define PG8_MMA(ai, bj, At, Bt) do { __builtin_amdgcn_s_setprio(1); _Pragma("unroll") for (int m = 0; m < 4; ++m) _Pragma("unroll") for (int n = 0; n < 2; ++n) _Pragma("unroll") for (int k = 0; k < 2; ++k) \
;         acc[ai][bj][m][n] = __builtin_amdgcn_mfma_f32_16x16x32_bf16(Bt[n][k], At[m][k], acc[ai][bj][m][n], 0, 0, 0); __builtin_amdgcn_s_setprio(0); } while (0)
; #define PG8_WAIT_V(n) asm volatile("s_waitcnt vmcnt(" #n ")" ::: "memory")
; #define PG8_WAIT_L(n) asm volatile("s_waitcnt lgkmcnt(" #n ")" ::: "memory")
; #define PG8_BAR __builtin_amdgcn_s_barrier()
; #define PG8_SCHED __builtin_amdgcn_sched_barrier(0)
; template <class Epi, class Sched, bool ALIGN_EPI = false, bool SP2 = false>
; __device__ __forceinline__ void gemm_phase(PG8_LAS unsigned char* lds, const Gemm g, const Sched& S, const Epi& E) {
;     ...
;             PG8_LDB(B0, 1, 0); PG8_LDB(B1, 1, 1); PG8_SCHED; PG8_LDA(At, 1, 0); PG8_STAGE(PG8_SA(0, 1), a2 + hstep, voffA);
;             PG8_WAIT_V(8); PG8_WAIT_L(0); PG8_BAR; PG8_MMA(0, 0, At, B0); PG8_MMA(0, 1, At, B1); PG8_BAR; PG8_SCHED;
;             PG8_LDA(At, 1, 1); PG8_STAGE(PG8_SB(1, 0), b3, voffB); PG8_STAGE(PG8_SB(1, 1), b3 + hstep, voffB); PG8_STAGE(PG8_SA(1, 0), a3, voffA);
;             PG8_WAIT_V(8); PG8_WAIT_L(0); PG8_BAR; PG8_MMA(1, 0, At, B0); PG8_MMA(1, 1, At, B1); PG8_BAR; PG8_SCHED;
	s_setprio 0
	s_add_i32 s63, 0, 0x18000
	s_add_i32 s64, 0, 0x1c000
	ds_read_b128 v[132:135], v240
	ds_read_b128 v[136:139], v240 offset:1024
	ds_read_b128 v[158:161], v240 offset:2048
	ds_read_b128 v[162:165], v240 offset:3072
	ds_read_b128 v[188:191], v241
	ds_read_b128 v[192:195], v241 offset:1024
	ds_read_b128 v[196:199], v241 offset:2048
	ds_read_b128 v[200:203], v241 offset:3072
	s_add_u32 s14, s20, 0x160000
	s_addc_u32 s15, s21, 0
	s_mov_b32 m0, s28
	ds_read_b128 v[204:207], v187 offset:32768
	ds_read_b128 v[208:211], v187 offset:33792
	ds_read_b128 v[212:215], v187 offset:34816
	ds_read_b128 v[216:219], v187 offset:35840
	ds_read_b128 v[220:223], v187 offset:36864
	ds_read_b128 v[224:227], v187 offset:37888
	ds_read_b128 v[228:231], v187 offset:38912
	ds_read_b128 v[232:235], v187 offset:39936
	global_load_lds_dwordx4 v0, s[14:15]
	s_mov_b32 m0, s29
	s_nop 0
	global_load_lds_dwordx4 v150, s[14:15]
	s_waitcnt vmcnt(8)
	s_waitcnt lgkmcnt(0)
	s_setprio 1
	s_barrier
	v_mfma_f32_16x16x32_bf16 v[128:131], v[132:135], v[204:207], v[128:131]
	v_mfma_f32_16x16x32_bf16 v[124:127], v[158:161], v[204:207], v[124:127]
	v_mfma_f32_16x16x32_bf16 v[112:115], v[132:135], v[212:215], v[112:115]
	v_mfma_f32_16x16x32_bf16 v[108:111], v[158:161], v[212:215], v[108:111]
	v_mfma_f32_16x16x32_bf16 v[96:99], v[132:135], v[220:223], v[96:99]
	v_mfma_f32_16x16x32_bf16 v[92:95], v[158:161], v[220:223], v[92:95]
	v_mfma_f32_16x16x32_bf16 v[80:83], v[132:135], v[228:231], v[80:83]
	v_mfma_f32_16x16x32_bf16 v[76:79], v[158:161], v[228:231], v[76:79]
	v_mfma_f32_16x16x32_bf16 v[128:131], v[136:139], v[208:211], v[128:131]
	v_mfma_f32_16x16x32_bf16 v[124:127], v[162:165], v[208:211], v[124:127]
	v_mfma_f32_16x16x32_bf16 v[112:115], v[136:139], v[216:219], v[112:115]
	v_mfma_f32_16x16x32_bf16 v[108:111], v[162:165], v[216:219], v[108:111]
	v_mfma_f32_16x16x32_bf16 v[96:99], v[136:139], v[224:227], v[96:99]
	v_mfma_f32_16x16x32_bf16 v[92:95], v[162:165], v[224:227], v[92:95]
	v_mfma_f32_16x16x32_bf16 v[80:83], v[136:139], v[232:235], v[80:83]
	v_mfma_f32_16x16x32_bf16 v[76:79], v[162:165], v[232:235], v[76:79]
	v_mfma_f32_16x16x32_bf16 v[120:123], v[188:191], v[204:207], v[120:123]
	v_mfma_f32_16x16x32_bf16 v[116:119], v[196:199], v[204:207], v[116:119]
	v_mfma_f32_16x16x32_bf16 v[104:107], v[188:191], v[212:215], v[104:107]
	v_mfma_f32_16x16x32_bf16 v[100:103], v[196:199], v[212:215], v[100:103]
	v_mfma_f32_16x16x32_bf16 v[88:91], v[188:191], v[220:223], v[88:91]
	v_mfma_f32_16x16x32_bf16 v[84:87], v[196:199], v[220:223], v[84:87]
	v_mfma_f32_16x16x32_bf16 v[72:75], v[188:191], v[228:231], v[72:75]
	v_mfma_f32_16x16x32_bf16 v[68:71], v[196:199], v[228:231], v[68:71]
	v_mfma_f32_16x16x32_bf16 v[120:123], v[192:195], v[208:211], v[120:123]
	v_mfma_f32_16x16x32_bf16 v[116:119], v[200:203], v[208:211], v[116:119]
	v_mfma_f32_16x16x32_bf16 v[104:107], v[192:195], v[216:219], v[104:107]
	v_mfma_f32_16x16x32_bf16 v[100:103], v[200:203], v[216:219], v[100:103]
	v_mfma_f32_16x16x32_bf16 v[88:91], v[192:195], v[224:227], v[88:91]
	v_mfma_f32_16x16x32_bf16 v[84:87], v[200:203], v[224:227], v[84:87]
	v_mfma_f32_16x16x32_bf16 v[72:75], v[192:195], v[232:235], v[72:75]
	v_mfma_f32_16x16x32_bf16 v[68:71], v[200:203], v[232:235], v[68:71]
	s_barrier
	s_setprio 0
	s_add_i32 s14, s63, s25
	s_mov_b32 m0, s14
	ds_read_b128 v[204:207], v187 offset:49152
	ds_read_b128 v[208:211], v187 offset:50176
	ds_read_b128 v[212:215], v187 offset:51200
	ds_read_b128 v[216:219], v187 offset:52224
	ds_read_b128 v[220:223], v187 offset:53248
	ds_read_b128 v[224:227], v187 offset:54272
	ds_read_b128 v[228:231], v187 offset:55296
	ds_read_b128 v[232:235], v187 offset:56320
	s_add_u32 vcc_lo, s18, 0x80
	s_addc_u32 vcc_hi, s19, 0
	global_load_lds_dwordx4 v2, vcc
	s_add_i32 m0, s14, 0x2000
	s_add_u32 s14, s18, 0x160080
	v_lshl_add_u64 v[166:167], v[236:237], 0, s[36:37]
	s_addc_u32 s15, s19, 0
	s_add_i32 s18, s64, s25
	global_load_lds_dwordx4 v[166:167], off
	s_mov_b32 m0, s18
	s_nop 0
	global_load_lds_dwordx4 v2, s[14:15]
	v_lshl_add_u64 v[166:167], s[14:15], 0, v[152:153]
	s_add_i32 m0, s18, 0x2000
	s_nop 0
	global_load_lds_dwordx4 v[166:167], off
	s_mov_b32 m0, s30
	s_nop 0
	s_add_u32 vcc_lo, s20, 0x80
	s_addc_u32 vcc_hi, s21, 0
	global_load_lds_dwordx4 v0, vcc
	s_mov_b32 m0, s31
	s_nop 0
	s_add_u32 vcc_lo, s20, 0x80
	s_addc_u32 vcc_hi, s21, 0
	global_load_lds_dwordx4 v150, vcc
	s_waitcnt vmcnt(8)
	s_waitcnt lgkmcnt(0)
	s_setprio 1
	s_barrier
	v_mfma_f32_16x16x32_bf16 v[64:67], v[132:135], v[204:207], v[64:67]
	v_mfma_f32_16x16x32_bf16 v[60:63], v[158:161], v[204:207], v[60:63]
	v_mfma_f32_16x16x32_bf16 v[48:51], v[132:135], v[212:215], v[48:51]
	v_mfma_f32_16x16x32_bf16 v[44:47], v[158:161], v[212:215], v[44:47]
	v_mfma_f32_16x16x32_bf16 v[32:35], v[132:135], v[220:223], v[32:35]
	v_mfma_f32_16x16x32_bf16 v[28:31], v[158:161], v[220:223], v[28:31]
	v_mfma_f32_16x16x32_bf16 v[16:19], v[132:135], v[228:231], v[16:19]
	v_mfma_f32_16x16x32_bf16 v[12:15], v[158:161], v[228:231], v[12:15]
	v_mfma_f32_16x16x32_bf16 v[64:67], v[136:139], v[208:211], v[64:67]
	v_mfma_f32_16x16x32_bf16 v[60:63], v[162:165], v[208:211], v[60:63]
	v_mfma_f32_16x16x32_bf16 v[48:51], v[136:139], v[216:219], v[48:51]
	v_mfma_f32_16x16x32_bf16 v[44:47], v[162:165], v[216:219], v[44:47]
	v_mfma_f32_16x16x32_bf16 v[32:35], v[136:139], v[224:227], v[32:35]
	v_mfma_f32_16x16x32_bf16 v[28:31], v[162:165], v[224:227], v[28:31]
	v_mfma_f32_16x16x32_bf16 v[16:19], v[136:139], v[232:235], v[16:19]
	v_mfma_f32_16x16x32_bf16 v[12:15], v[162:165], v[232:235], v[12:15]
	v_mfma_f32_16x16x32_bf16 v[56:59], v[188:191], v[204:207], v[56:59]
	v_mfma_f32_16x16x32_bf16 v[52:55], v[196:199], v[204:207], v[52:55]
	v_mfma_f32_16x16x32_bf16 v[40:43], v[188:191], v[212:215], v[40:43]
	v_mfma_f32_16x16x32_bf16 v[36:39], v[196:199], v[212:215], v[36:39]
	v_mfma_f32_16x16x32_bf16 v[24:27], v[188:191], v[220:223], v[24:27]
	v_mfma_f32_16x16x32_bf16 v[20:23], v[196:199], v[220:223], v[20:23]
	v_mfma_f32_16x16x32_bf16 v[8:11], v[188:191], v[228:231], v[8:11]
	v_mfma_f32_16x16x32_bf16 v[4:7], v[196:199], v[228:231], v[4:7]
	v_mfma_f32_16x16x32_bf16 v[56:59], v[192:195], v[208:211], v[56:59]
	v_mfma_f32_16x16x32_bf16 v[52:55], v[200:203], v[208:211], v[52:55]
	v_mfma_f32_16x16x32_bf16 v[40:43], v[192:195], v[216:219], v[40:43]
	v_mfma_f32_16x16x32_bf16 v[36:39], v[200:203], v[216:219], v[36:39]
	v_mfma_f32_16x16x32_bf16 v[24:27], v[192:195], v[224:227], v[24:27]
	v_mfma_f32_16x16x32_bf16 v[20:23], v[200:203], v[224:227], v[20:23]
	v_mfma_f32_16x16x32_bf16 v[8:11], v[192:195], v[232:235], v[8:11]
	v_mfma_f32_16x16x32_bf16 v[4:7], v[200:203], v[232:235], v[4:7]
	s_barrier
	s_setprio 0
	s_add_i32 s57, s57, 2
	s_add_u32 s51, s51, 0x100
	s_addc_u32 s56, s56, 0
	s_cmpk_gt_u32 s57, 0x55
	s_mov_b64 s[14:15], s[16:17]
; #define PG8_STAGE(bufoff, gbase, voff) do { _Pragma("unroll") for (int _i = 0; _i < 2; ++_i) \
;         __builtin_amdgcn_global_load_lds((const unsigned*)((const char*)(gbase) + (voff)[_i]), (PG8_LAS unsigned*)(lds + (bufoff) + ldsw + _i * 8192), 16, 0, 0); } while (0)
; #define PG8_LDA(dst, b, h) do { _Pragma("unroll") for (int m = 0; m < 4; ++m) _Pragma("unroll") for (int k = 0; k < 2; ++k) dst[m][k] = *(const PG8_LAS bf16x8*)(lds + PG8_SA(b, h) + aoff + m * 2048 + k * 1024); } while (0)
; #define PG8_LDB(dst, b, h) do { _Pragma("unroll") for (int n = 0; n < 2; ++n) _Pragma("unroll") for (int k = 0; k < 2; ++k) dst[n][k] = *(const PG8_LAS bf16x8*)(lds + PG8_SB(b, h) + boff + n * 2048 + k * 1024); } while (0)
; #define PG8_MMA(ai, bj, At, Bt) do { __builtin_amdgcn_s_setprio(1); _Pragma("unroll") for (int m = 0; m < 4; ++m) _Pragma("unroll") for (int n = 0; n < 2; ++n) _Pragma("unroll") for (int k = 0; k < 2; ++k) \
;         acc[ai][bj][m][n] = __builtin_amdgcn_mfma_f32_16x16x32_bf16(Bt[n][k], At[m][k], acc[ai][bj][m][n], 0, 0, 0); __builtin_amdgcn_s_setprio(0); } while (0)
; #define PG8_WAIT_V(n) asm volatile("s_waitcnt vmcnt(" #n ")" ::: "memory")
; #define PG8_BAR __builtin_amdgcn_s_barrier()
; template <class Epi, class Sched, bool ALIGN_EPI = false, bool SP2 = false>
; __device__ __forceinline__ void gemm_phase(PG8_LAS unsigned char* lds, const Gemm g, const Sched& S, const Epi& E) {
;     ...
;         for (int t = 0; t < nt; t += 2) {
;             const bool last = (t == nt - 2);
;             const char* a1 = cA + (size_t)(t + 1) * kstep;
;             const char* a2 = last ? nA : cA + (size_t)(t + 2) * kstep; const char* b2 = last ? nB : cB + (size_t)(t + 2) * kstep;
;             const char* a3 = a2 + kstep; const char* b3 = b2 + kstep;
;             if (last && has_next) S.a_ready(nxt);
;             if constexpr (SP2) {
;             PG8_LDB(B0, 0, 0); PG8_LDB(B1, 0, 1); PG8_SCHED; PG8_LDA(At, 0, 0); PG8_STAGE(PG8_SA(1, 1), a1 + hstep, voffA);
;             PG8_WAIT_V(8); PG8_WAIT_L(0); PG8_BAR; PG8_MMA(0, 0, At, B0); PG8_MMA(0, 1, At, B1); PG8_BAR; PG8_SCHED;
;             PG8_LDA(At, 0, 1); PG8_STAGE(PG8_SB(0, 0), b2, voffB); PG8_STAGE(PG8_SB(0, 1), b2 + hstep, voffB); PG8_STAGE(PG8_SA(0, 0), a2, voffA);
;             PG8_WAIT_V(8); PG8_WAIT_L(0); PG8_BAR; PG8_MMA(1, 0, At, B0); PG8_MMA(1, 1, At, B1); PG8_BAR; PG8_SCHED;
.LBB0_167:
	s_add_u32 s16, s14, 0x100
	s_addc_u32 s17, s15, 0
	s_add_i32 s63, 0, 0x10000
	s_cmpk_eq_i32 s57, 0x54
	s_cselect_b32 s21, s7, s17
	s_cselect_b32 s20, s6, s16
	s_cselect_b32 s19, s13, s56
	s_cselect_b32 s18, s12, s51
	s_add_i32 s64, 0, 0x14000
	ds_read_b128 v[132:135], v238
	ds_read_b128 v[136:139], v238 offset:1024
	ds_read_b128 v[158:161], v238 offset:2048
	ds_read_b128 v[162:165], v238 offset:3072
	ds_read_b128 v[188:191], v239
	ds_read_b128 v[192:195], v239 offset:1024
	ds_read_b128 v[196:199], v239 offset:2048
	ds_read_b128 v[200:203], v239 offset:3072
	s_add_i32 m0, s26, 0xc000
	ds_read_b128 v[204:207], v187
	ds_read_b128 v[208:211], v187 offset:1024
	ds_read_b128 v[212:215], v187 offset:2048
	ds_read_b128 v[216:219], v187 offset:3072
	ds_read_b128 v[220:223], v187 offset:4096
	ds_read_b128 v[224:227], v187 offset:5120
	ds_read_b128 v[228:231], v187 offset:6144
	ds_read_b128 v[232:235], v187 offset:7168
	global_load_lds_dwordx4 v154, s[14:15]
	s_add_i32 m0, s26, 0xe000
	s_nop 0
	global_load_lds_dwordx4 v156, s[14:15]
	s_waitcnt vmcnt(8)
	s_waitcnt lgkmcnt(0)
	s_setprio 1
	s_barrier
	v_mfma_f32_16x16x32_bf16 v[128:131], v[132:135], v[204:207], v[128:131]
	v_mfma_f32_16x16x32_bf16 v[124:127], v[158:161], v[204:207], v[124:127]
	v_mfma_f32_16x16x32_bf16 v[112:115], v[132:135], v[212:215], v[112:115]
	v_mfma_f32_16x16x32_bf16 v[108:111], v[158:161], v[212:215], v[108:111]
	v_mfma_f32_16x16x32_bf16 v[96:99], v[132:135], v[220:223], v[96:99]
	v_mfma_f32_16x16x32_bf16 v[92:95], v[158:161], v[220:223], v[92:95]
	v_mfma_f32_16x16x32_bf16 v[80:83], v[132:135], v[228:231], v[80:83]
	v_mfma_f32_16x16x32_bf16 v[76:79], v[158:161], v[228:231], v[76:79]
	v_mfma_f32_16x16x32_bf16 v[128:131], v[136:139], v[208:211], v[128:131]
	v_mfma_f32_16x16x32_bf16 v[124:127], v[162:165], v[208:211], v[124:127]
	v_mfma_f32_16x16x32_bf16 v[112:115], v[136:139], v[216:219], v[112:115]
	v_mfma_f32_16x16x32_bf16 v[108:111], v[162:165], v[216:219], v[108:111]
	v_mfma_f32_16x16x32_bf16 v[96:99], v[136:139], v[224:227], v[96:99]
	v_mfma_f32_16x16x32_bf16 v[92:95], v[162:165], v[224:227], v[92:95]
	v_mfma_f32_16x16x32_bf16 v[80:83], v[136:139], v[232:235], v[80:83]
	v_mfma_f32_16x16x32_bf16 v[76:79], v[162:165], v[232:235], v[76:79]
	v_mfma_f32_16x16x32_bf16 v[120:123], v[188:191], v[204:207], v[120:123]
	v_mfma_f32_16x16x32_bf16 v[116:119], v[196:199], v[204:207], v[116:119]
	v_mfma_f32_16x16x32_bf16 v[104:107], v[188:191], v[212:215], v[104:107]
	v_mfma_f32_16x16x32_bf16 v[100:103], v[196:199], v[212:215], v[100:103]
	v_mfma_f32_16x16x32_bf16 v[88:91], v[188:191], v[220:223], v[88:91]
	v_mfma_f32_16x16x32_bf16 v[84:87], v[196:199], v[220:223], v[84:87]
	v_mfma_f32_16x16x32_bf16 v[72:75], v[188:191], v[228:231], v[72:75]
	v_mfma_f32_16x16x32_bf16 v[68:71], v[196:199], v[228:231], v[68:71]
	v_mfma_f32_16x16x32_bf16 v[120:123], v[192:195], v[208:211], v[120:123]
	v_mfma_f32_16x16x32_bf16 v[116:119], v[200:203], v[208:211], v[116:119]
	v_mfma_f32_16x16x32_bf16 v[104:107], v[192:195], v[216:219], v[104:107]
	v_mfma_f32_16x16x32_bf16 v[100:103], v[200:203], v[216:219], v[100:103]
	v_mfma_f32_16x16x32_bf16 v[88:91], v[192:195], v[224:227], v[88:91]
	v_mfma_f32_16x16x32_bf16 v[84:87], v[200:203], v[224:227], v[84:87]
	v_mfma_f32_16x16x32_bf16 v[72:75], v[192:195], v[232:235], v[72:75]
	v_mfma_f32_16x16x32_bf16 v[68:71], v[200:203], v[232:235], v[68:71]
	s_barrier
	s_setprio 0
	s_add_i32 s14, s63, s25
	s_mov_b32 m0, s14
	ds_read_b128 v[204:207], v187 offset:16384
	ds_read_b128 v[208:211], v187 offset:17408
	ds_read_b128 v[212:215], v187 offset:18432
	ds_read_b128 v[216:219], v187 offset:19456
	ds_read_b128 v[220:223], v187 offset:20480
	ds_read_b128 v[224:227], v187 offset:21504
	ds_read_b128 v[228:231], v187 offset:22528
	ds_read_b128 v[232:235], v187 offset:23552
	global_load_lds_dwordx4 v2, s[18:19]
	s_add_i32 m0, s14, 0x2000
	s_add_u32 s14, s18, 0x160000
	v_lshl_add_u64 v[236:237], s[18:19], 0, v[152:153]
	s_addc_u32 s15, s19, 0
	s_add_i32 s63, s64, s25
	global_load_lds_dwordx4 v[236:237], off
	s_mov_b32 m0, s63
	s_nop 0
	global_load_lds_dwordx4 v2, s[14:15]
	s_add_i32 m0, s63, 0x2000
	s_nop 0
	global_load_lds_dwordx4 v152, s[14:15]
	s_mov_b32 m0, s26
	s_nop 0
	global_load_lds_dwordx4 v0, s[20:21]
	s_mov_b32 m0, s27
	s_nop 0
	global_load_lds_dwordx4 v150, s[20:21]
	s_waitcnt vmcnt(8)
	s_waitcnt lgkmcnt(0)
	s_setprio 1
	s_barrier
	v_mfma_f32_16x16x32_bf16 v[64:67], v[132:135], v[204:207], v[64:67]
	v_mfma_f32_16x16x32_bf16 v[60:63], v[158:161], v[204:207], v[60:63]
	v_mfma_f32_16x16x32_bf16 v[48:51], v[132:135], v[212:215], v[48:51]
	v_mfma_f32_16x16x32_bf16 v[44:47], v[158:161], v[212:215], v[44:47]
	v_mfma_f32_16x16x32_bf16 v[32:35], v[132:135], v[220:223], v[32:35]
	v_mfma_f32_16x16x32_bf16 v[28:31], v[158:161], v[220:223], v[28:31]
	v_mfma_f32_16x16x32_bf16 v[16:19], v[132:135], v[228:231], v[16:19]
	v_mfma_f32_16x16x32_bf16 v[12:15], v[158:161], v[228:231], v[12:15]
	v_mfma_f32_16x16x32_bf16 v[64:67], v[136:139], v[208:211], v[64:67]
	v_mfma_f32_16x16x32_bf16 v[60:63], v[162:165], v[208:211], v[60:63]
	v_mfma_f32_16x16x32_bf16 v[48:51], v[136:139], v[216:219], v[48:51]
	v_mfma_f32_16x16x32_bf16 v[44:47], v[162:165], v[216:219], v[44:47]
	v_mfma_f32_16x16x32_bf16 v[32:35], v[136:139], v[224:227], v[32:35]
	v_mfma_f32_16x16x32_bf16 v[28:31], v[162:165], v[224:227], v[28:31]
	v_mfma_f32_16x16x32_bf16 v[16:19], v[136:139], v[232:235], v[16:19]
	v_mfma_f32_16x16x32_bf16 v[12:15], v[162:165], v[232:235], v[12:15]
	v_mfma_f32_16x16x32_bf16 v[56:59], v[188:191], v[204:207], v[56:59]
	v_mfma_f32_16x16x32_bf16 v[52:55], v[196:199], v[204:207], v[52:55]
	v_mfma_f32_16x16x32_bf16 v[40:43], v[188:191], v[212:215], v[40:43]
	v_mfma_f32_16x16x32_bf16 v[36:39], v[196:199], v[212:215], v[36:39]
	v_mfma_f32_16x16x32_bf16 v[24:27], v[188:191], v[220:223], v[24:27]
	v_mfma_f32_16x16x32_bf16 v[20:23], v[196:199], v[220:223], v[20:23]
	v_mfma_f32_16x16x32_bf16 v[8:11], v[188:191], v[228:231], v[8:11]
	v_mfma_f32_16x16x32_bf16 v[4:7], v[196:199], v[228:231], v[4:7]
	v_mfma_f32_16x16x32_bf16 v[56:59], v[192:195], v[208:211], v[56:59]
	v_mfma_f32_16x16x32_bf16 v[52:55], v[200:203], v[208:211], v[52:55]
	v_mfma_f32_16x16x32_bf16 v[40:43], v[192:195], v[216:219], v[40:43]
	v_mfma_f32_16x16x32_bf16 v[36:39], v[200:203], v[216:219], v[36:39]
	v_mfma_f32_16x16x32_bf16 v[24:27], v[192:195], v[224:227], v[24:27]
	v_mfma_f32_16x16x32_bf16 v[20:23], v[200:203], v[224:227], v[20:23]
	v_mfma_f32_16x16x32_bf16 v[8:11], v[192:195], v[232:235], v[8:11]
	v_mfma_f32_16x16x32_bf16 v[4:7], v[200:203], v[232:235], v[4:7]
	s_barrier
; #define PG8_STAGE(bufoff, gbase, voff) do { _Pragma("unroll") for (int _i = 0; _i < 2; ++_i) \
;         __builtin_amdgcn_global_load_lds((const unsigned*)((const char*)(gbase) + (voff)[_i]), (PG8_LAS unsigned*)(lds + (bufoff) + ldsw + _i * 8192), 16, 0, 0); } while (0)
; #define PG8_LDA(dst, b, h) do { _Pragma("unroll") for (int m = 0; m < 4; ++m) _Pragma("unroll") for (int k = 0; k < 2; ++k) dst[m][k] = *(const PG8_LAS bf16x8*)(lds + PG8_SA(b, h) + aoff + m * 2048 + k * 1024); } while (0)
; #define PG8_LDB(dst, b, h) do { _Pragma("unroll") for (int n = 0; n < 2; ++n) _Pragma("unroll") for (int k = 0; k < 2; ++k) dst[n][k] = *(const PG8_LAS bf16x8*)(lds + PG8_SB(b, h) + boff + n * 2048 + k * 1024); } while (0)
; #define PG8_MMA(ai, bj, At, Bt) do { __builtin_amdgcn_s_setprio(1); _Pragma("unroll") for (int m = 0; m < 4; ++m) _Pragma("unroll") for (int n = 0; n < 2; ++n) _Pragma("unroll") for (int k = 0; k < 2; ++k) \
;         acc[ai][bj][m][n] = __builtin_amdgcn_mfma_f32_16x16x32_bf16(Bt[n][k], At[m][k], acc[ai][bj][m][n], 0, 0, 0); __builtin_amdgcn_s_setprio(0); } while (0)
; #define PG8_WAIT_V(n) asm volatile("s_waitcnt vmcnt(" #n ")" ::: "memory")
; #define PG8_WAIT_L(n) asm volatile("s_waitcnt lgkmcnt(" #n ")" ::: "memory")
; #define PG8_BAR __builtin_amdgcn_s_barrier()
; #define PG8_SCHED __builtin_amdgcn_sched_barrier(0)
; template <class Epi, class Sched, bool ALIGN_EPI = false, bool SP2 = false>
; __device__ __forceinline__ void gemm_phase(PG8_LAS unsigned char* lds, const Gemm g, const Sched& S, const Epi& E) {
;     ...
;             PG8_LDB(B0, 1, 0); PG8_LDB(B1, 1, 1); PG8_SCHED; PG8_LDA(At, 1, 0); PG8_STAGE(PG8_SA(0, 1), a2 + hstep, voffA);
;             PG8_WAIT_V(8); PG8_WAIT_L(0); PG8_BAR; PG8_MMA(0, 0, At, B0); PG8_MMA(0, 1, At, B1); PG8_BAR; PG8_SCHED;
;             PG8_LDA(At, 1, 1); PG8_STAGE(PG8_SB(1, 0), b3, voffB); PG8_STAGE(PG8_SB(1, 1), b3 + hstep, voffB); PG8_STAGE(PG8_SA(1, 0), a3, voffA);
;             PG8_WAIT_V(8); PG8_WAIT_L(0); PG8_BAR; PG8_MMA(1, 0, At, B0); PG8_MMA(1, 1, At, B1); PG8_BAR; PG8_SCHED;
;     ...
;         if constexpr (ALIGN_EPI) { if (wr == 0) PG8_BAR; }
	s_setprio 0
	s_add_i32 s63, 0, 0x18000
	s_add_i32 s64, 0, 0x1c000
	ds_read_b128 v[132:135], v240
	ds_read_b128 v[136:139], v240 offset:1024
	ds_read_b128 v[158:161], v240 offset:2048
	ds_read_b128 v[162:165], v240 offset:3072
	ds_read_b128 v[188:191], v241
	ds_read_b128 v[192:195], v241 offset:1024
	ds_read_b128 v[196:199], v241 offset:2048
	ds_read_b128 v[200:203], v241 offset:3072
	s_add_u32 s14, s20, 0x160000
	s_addc_u32 s15, s21, 0
	s_mov_b32 m0, s28
	ds_read_b128 v[204:207], v187 offset:32768
	ds_read_b128 v[208:211], v187 offset:33792
	ds_read_b128 v[212:215], v187 offset:34816
	ds_read_b128 v[216:219], v187 offset:35840
	ds_read_b128 v[220:223], v187 offset:36864
	ds_read_b128 v[224:227], v187 offset:37888
	ds_read_b128 v[228:231], v187 offset:38912
	ds_read_b128 v[232:235], v187 offset:39936
	global_load_lds_dwordx4 v0, s[14:15]
	s_mov_b32 m0, s29
	s_nop 0
	global_load_lds_dwordx4 v150, s[14:15]
	s_waitcnt vmcnt(8)
	s_waitcnt lgkmcnt(0)
	s_setprio 1
	s_barrier
	v_mfma_f32_16x16x32_bf16 v[128:131], v[132:135], v[204:207], v[128:131]
	v_mfma_f32_16x16x32_bf16 v[124:127], v[158:161], v[204:207], v[124:127]
	v_mfma_f32_16x16x32_bf16 v[112:115], v[132:135], v[212:215], v[112:115]
	v_mfma_f32_16x16x32_bf16 v[108:111], v[158:161], v[212:215], v[108:111]
	v_mfma_f32_16x16x32_bf16 v[96:99], v[132:135], v[220:223], v[96:99]
	v_mfma_f32_16x16x32_bf16 v[92:95], v[158:161], v[220:223], v[92:95]
	v_mfma_f32_16x16x32_bf16 v[80:83], v[132:135], v[228:231], v[80:83]
	v_mfma_f32_16x16x32_bf16 v[76:79], v[158:161], v[228:231], v[76:79]
	v_mfma_f32_16x16x32_bf16 v[128:131], v[136:139], v[208:211], v[128:131]
	v_mfma_f32_16x16x32_bf16 v[124:127], v[162:165], v[208:211], v[124:127]
	v_mfma_f32_16x16x32_bf16 v[112:115], v[136:139], v[216:219], v[112:115]
	v_mfma_f32_16x16x32_bf16 v[108:111], v[162:165], v[216:219], v[108:111]
	v_mfma_f32_16x16x32_bf16 v[96:99], v[136:139], v[224:227], v[96:99]
	v_mfma_f32_16x16x32_bf16 v[92:95], v[162:165], v[224:227], v[92:95]
	v_mfma_f32_16x16x32_bf16 v[80:83], v[136:139], v[232:235], v[80:83]
	v_mfma_f32_16x16x32_bf16 v[76:79], v[162:165], v[232:235], v[76:79]
	v_mfma_f32_16x16x32_bf16 v[120:123], v[188:191], v[204:207], v[120:123]
	v_mfma_f32_16x16x32_bf16 v[116:119], v[196:199], v[204:207], v[116:119]
	v_mfma_f32_16x16x32_bf16 v[104:107], v[188:191], v[212:215], v[104:107]
	v_mfma_f32_16x16x32_bf16 v[100:103], v[196:199], v[212:215], v[100:103]
	v_mfma_f32_16x16x32_bf16 v[88:91], v[188:191], v[220:223], v[88:91]
	v_mfma_f32_16x16x32_bf16 v[84:87], v[196:199], v[220:223], v[84:87]
	v_mfma_f32_16x16x32_bf16 v[72:75], v[188:191], v[228:231], v[72:75]
	v_mfma_f32_16x16x32_bf16 v[68:71], v[196:199], v[228:231], v[68:71]
	v_mfma_f32_16x16x32_bf16 v[120:123], v[192:195], v[208:211], v[120:123]
	v_mfma_f32_16x16x32_bf16 v[116:119], v[200:203], v[208:211], v[116:119]
	v_mfma_f32_16x16x32_bf16 v[104:107], v[192:195], v[216:219], v[104:107]
	v_mfma_f32_16x16x32_bf16 v[100:103], v[200:203], v[216:219], v[100:103]
	v_mfma_f32_16x16x32_bf16 v[88:91], v[192:195], v[224:227], v[88:91]
	v_mfma_f32_16x16x32_bf16 v[84:87], v[200:203], v[224:227], v[84:87]
	v_mfma_f32_16x16x32_bf16 v[72:75], v[192:195], v[232:235], v[72:75]
	v_mfma_f32_16x16x32_bf16 v[68:71], v[200:203], v[232:235], v[68:71]
	s_barrier
	s_setprio 0
	s_add_i32 s14, s63, s25
	s_mov_b32 m0, s14
	ds_read_b128 v[204:207], v187 offset:49152
	ds_read_b128 v[208:211], v187 offset:50176
	ds_read_b128 v[212:215], v187 offset:51200
	ds_read_b128 v[216:219], v187 offset:52224
	ds_read_b128 v[220:223], v187 offset:53248
	ds_read_b128 v[224:227], v187 offset:54272
	ds_read_b128 v[228:231], v187 offset:55296
	ds_read_b128 v[232:235], v187 offset:56320
	s_add_u32 vcc_lo, s18, 0x80
	s_addc_u32 vcc_hi, s19, 0
	global_load_lds_dwordx4 v2, vcc
	s_add_i32 m0, s14, 0x2000
	s_add_u32 s14, s18, 0x160080
	v_lshl_add_u64 v[166:167], v[236:237], 0, s[36:37]
	s_addc_u32 s15, s19, 0
	s_add_i32 s18, s64, s25
	global_load_lds_dwordx4 v[166:167], off
	s_mov_b32 m0, s18
	s_nop 0
	global_load_lds_dwordx4 v2, s[14:15]
	v_lshl_add_u64 v[166:167], s[14:15], 0, v[152:153]
	s_add_i32 m0, s18, 0x2000
	s_nop 0
	global_load_lds_dwordx4 v[166:167], off
	s_mov_b32 m0, s30
	s_nop 0
	s_add_u32 vcc_lo, s20, 0x80
	s_addc_u32 vcc_hi, s21, 0
	global_load_lds_dwordx4 v0, vcc
	s_mov_b32 m0, s31
	s_nop 0
	s_add_u32 vcc_lo, s20, 0x80
	s_addc_u32 vcc_hi, s21, 0
	global_load_lds_dwordx4 v150, vcc
	s_waitcnt vmcnt(8)
	s_waitcnt lgkmcnt(0)
	s_setprio 1
	s_barrier
	v_mfma_f32_16x16x32_bf16 v[64:67], v[132:135], v[204:207], v[64:67]
	v_mfma_f32_16x16x32_bf16 v[60:63], v[158:161], v[204:207], v[60:63]
	v_mfma_f32_16x16x32_bf16 v[48:51], v[132:135], v[212:215], v[48:51]
	v_mfma_f32_16x16x32_bf16 v[44:47], v[158:161], v[212:215], v[44:47]
	v_mfma_f32_16x16x32_bf16 v[32:35], v[132:135], v[220:223], v[32:35]
	v_mfma_f32_16x16x32_bf16 v[28:31], v[158:161], v[220:223], v[28:31]
	v_mfma_f32_16x16x32_bf16 v[16:19], v[132:135], v[228:231], v[16:19]
	v_mfma_f32_16x16x32_bf16 v[12:15], v[158:161], v[228:231], v[12:15]
	v_mfma_f32_16x16x32_bf16 v[64:67], v[136:139], v[208:211], v[64:67]
	v_mfma_f32_16x16x32_bf16 v[60:63], v[162:165], v[208:211], v[60:63]
	v_mfma_f32_16x16x32_bf16 v[48:51], v[136:139], v[216:219], v[48:51]
	v_mfma_f32_16x16x32_bf16 v[44:47], v[162:165], v[216:219], v[44:47]
	v_mfma_f32_16x16x32_bf16 v[32:35], v[136:139], v[224:227], v[32:35]
	v_mfma_f32_16x16x32_bf16 v[28:31], v[162:165], v[224:227], v[28:31]
	v_mfma_f32_16x16x32_bf16 v[16:19], v[136:139], v[232:235], v[16:19]
	v_mfma_f32_16x16x32_bf16 v[12:15], v[162:165], v[232:235], v[12:15]
	v_mfma_f32_16x16x32_bf16 v[56:59], v[188:191], v[204:207], v[56:59]
	v_mfma_f32_16x16x32_bf16 v[52:55], v[196:199], v[204:207], v[52:55]
	v_mfma_f32_16x16x32_bf16 v[40:43], v[188:191], v[212:215], v[40:43]
	v_mfma_f32_16x16x32_bf16 v[36:39], v[196:199], v[212:215], v[36:39]
	v_mfma_f32_16x16x32_bf16 v[24:27], v[188:191], v[220:223], v[24:27]
	v_mfma_f32_16x16x32_bf16 v[20:23], v[196:199], v[220:223], v[20:23]
	v_mfma_f32_16x16x32_bf16 v[8:11], v[188:191], v[228:231], v[8:11]
	v_mfma_f32_16x16x32_bf16 v[4:7], v[196:199], v[228:231], v[4:7]
	v_mfma_f32_16x16x32_bf16 v[56:59], v[192:195], v[208:211], v[56:59]
	v_mfma_f32_16x16x32_bf16 v[52:55], v[200:203], v[208:211], v[52:55]
	v_mfma_f32_16x16x32_bf16 v[40:43], v[192:195], v[216:219], v[40:43]
	v_mfma_f32_16x16x32_bf16 v[36:39], v[200:203], v[216:219], v[36:39]
	v_mfma_f32_16x16x32_bf16 v[24:27], v[192:195], v[224:227], v[24:27]
	v_mfma_f32_16x16x32_bf16 v[20:23], v[200:203], v[224:227], v[20:23]
	v_mfma_f32_16x16x32_bf16 v[8:11], v[192:195], v[232:235], v[8:11]
	v_mfma_f32_16x16x32_bf16 v[4:7], v[200:203], v[232:235], v[4:7]
	s_barrier
	s_setprio 0
	s_add_i32 s57, s57, 2
	s_add_u32 s51, s51, 0x100
	s_addc_u32 s56, s56, 0
	s_cmpk_gt_u32 s57, 0x55
	s_mov_b64 s[14:15], s[16:17]
	s_cbranch_scc0 .LBB0_167
	s_and_b64 vcc, exec, s[10:11]
	s_cbranch_vccz .LBB0_170
	s_barrier

; #define PG8_STAGE(bufoff, gbase, voff) do { _Pragma("unroll") for (int _i = 0; _i < 2; ++_i) \
;         __builtin_amdgcn_global_load_lds((const unsigned*)((const char*)(gbase) + (voff)[_i]), (PG8_LAS unsigned*)(lds + (bufoff) + ldsw + _i * 8192), 16, 0, 0); } while (0)
; #define PG8_LDA(dst, b, h) do { _Pragma("unroll") for (int m = 0; m < 4; ++m) _Pragma("unroll") for (int k = 0; k < 2; ++k) dst[m][k] = *(const PG8_LAS bf16x8*)(lds + PG8_SA(b, h) + aoff + m * 2048 + k * 1024); } while (0)
; #define PG8_LDB(dst, b, h) do { _Pragma("unroll") for (int n = 0; n < 2; ++n) _Pragma("unroll") for (int k = 0; k < 2; ++k) dst[n][k] = *(const PG8_LAS bf16x8*)(lds + PG8_SB(b, h) + boff + n * 2048 + k * 1024); } while (0)
; #define PG8_WAIT_V(n) asm volatile("s_waitcnt vmcnt(" #n ")" ::: "memory")
; #define PG8_WAIT_L(n) asm volatile("s_waitcnt lgkmcnt(" #n ")" ::: "memory")
; #define PG8_BAR __builtin_amdgcn_s_barrier()
; #define PG8_SCHED __builtin_amdgcn_sched_barrier(0)
; template <class Epi, class Sched, bool ALIGN_EPI = false, bool SP2 = false>
; __device__ __forceinline__ void gemm_phase(PG8_LAS unsigned char* lds, const Gemm g, const Sched& S, const Epi& E) {
;     ...
;         const bool has_next = S.next(ui + 1, nxt);
;         const char* nA = has_next ? (const char*)g.A + (size_t)nxt.pm * tstep : cA; const char* nB = has_next ? (const char*)g.Bt + (size_t)nxt.pn * tstep : cB;
;         for (int t = 0; t < nt; t += 2) {
;             const bool last = (t == nt - 2);
;             const char* a1 = cA + (size_t)(t + 1) * kstep;
;             const char* a2 = last ? nA : cA + (size_t)(t + 2) * kstep; const char* b2 = last ? nB : cB + (size_t)(t + 2) * kstep;
;             const char* a3 = a2 + kstep; const char* b3 = b2 + kstep;
;             if (last && has_next) S.a_ready(nxt);
;             if constexpr (SP2) {
;             PG8_LDB(B0, 0, 0); PG8_LDB(B1, 0, 1); PG8_SCHED; PG8_LDA(At, 0, 0); PG8_STAGE(PG8_SA(1, 1), a1 + hstep, voffA);
;             PG8_WAIT_V(8); PG8_WAIT_L(0); PG8_BAR; PG8_MMA(0, 0, At, B0); PG8_MMA(0, 1, At, B1); PG8_BAR; PG8_SCHED;
;             PG8_LDA(At, 0, 1); PG8_STAGE(PG8_SB(0, 0), b2, voffB); PG8_STAGE(PG8_SB(0, 1), b2 + hstep, voffB); PG8_STAGE(PG8_SA(0, 0), a2, voffA);
;             PG8_WAIT_V(8); PG8_WAIT_L(0); PG8_BAR; PG8_MMA(1, 0, At, B0); PG8_MMA(1, 1, At, B1); PG8_BAR; PG8_SCHED;
.LBB0_250:
	s_ashr_i32 s11, s10, 31
	s_lshl_b64 s[12:13], s[10:11], 20
	s_add_u32 s12, s46, s12
	s_addc_u32 s13, s47, s13
	s_and_b64 s[14:15], s[2:3], exec
	s_cselect_b32 s11, s13, s19
	s_cselect_b32 s45, s12, s18
	s_ashr_i32 s7, s6, 31
	s_lshl_b64 s[14:15], s[6:7], 20
	s_add_u32 s14, s25, s14
	s_addc_u32 s15, s26, s15
	s_and_b64 s[22:23], s[2:3], exec
	s_cselect_b32 s7, s15, s21
	s_cselect_b32 s50, s14, s20
	s_add_u32 s18, s18, 0x80080
	s_addc_u32 s19, s19, 0
	s_add_u32 s51, s20, 0x100
	s_addc_u32 s56, s21, 0
	s_mov_b32 s57, -2
	v_add_u32_e32 v166, 0x10000, v156
	v_add_u32_e32 v167, 0x14000, v156
	v_add_u32_e32 v252, 0x18000, v156
	v_add_u32_e32 v253, 0x1c000, v156
	s_add_u32 s20, s18, 0xfff80080
	s_addc_u32 s21, s19, -1
	s_add_i32 s63, 0, 0x10000
	s_cmp_eq_u32 s57, 28
	s_cselect_b32 s23, s11, s21
	s_cselect_b32 s22, s45, s20
	s_cselect_b32 s21, s7, s56
	s_cselect_b32 s20, s50, s51
	s_add_i32 s66, 0, 0x14000
	ds_read_b128 v[184:187], v166
	ds_read_b128 v[188:191], v166 offset:1024
	ds_read_b128 v[192:195], v166 offset:2048
	ds_read_b128 v[196:199], v166 offset:3072
	ds_read_b128 v[200:203], v167
	ds_read_b128 v[204:207], v167 offset:1024
	ds_read_b128 v[208:211], v167 offset:2048
	ds_read_b128 v[212:215], v167 offset:3072
	s_add_i32 m0, s17, 0xc000
	ds_read_b128 v[216:219], v160
	ds_read_b128 v[220:223], v160 offset:1024
	ds_read_b128 v[224:227], v160 offset:2048
	ds_read_b128 v[228:231], v160 offset:3072
	ds_read_b128 v[232:235], v160 offset:4096
	ds_read_b128 v[236:239], v160 offset:5120
	ds_read_b128 v[240:243], v160 offset:6144
	ds_read_b128 v[244:247], v160 offset:7168
	global_load_lds_dwordx4 v136, s[18:19]
	s_add_i32 m0, s17, 0xe000
	s_nop 0
	global_load_lds_dwordx4 v138, s[18:19]
	s_waitcnt vmcnt(8)
	s_waitcnt lgkmcnt(0)
	s_setprio 1
	s_barrier
	v_mfma_f32_16x16x32_bf16 v[128:131], v[184:187], v[216:219], 0
	v_mfma_f32_16x16x32_bf16 v[124:127], v[192:195], v[216:219], 0
	v_mfma_f32_16x16x32_bf16 v[112:115], v[184:187], v[224:227], 0
	v_mfma_f32_16x16x32_bf16 v[108:111], v[192:195], v[224:227], 0
	v_mfma_f32_16x16x32_bf16 v[96:99], v[184:187], v[232:235], 0
	v_mfma_f32_16x16x32_bf16 v[92:95], v[192:195], v[232:235], 0
	v_mfma_f32_16x16x32_bf16 v[80:83], v[184:187], v[240:243], 0
	v_mfma_f32_16x16x32_bf16 v[76:79], v[192:195], v[240:243], 0
	v_mfma_f32_16x16x32_bf16 v[128:131], v[188:191], v[220:223], v[128:131]
	v_mfma_f32_16x16x32_bf16 v[124:127], v[196:199], v[220:223], v[124:127]
	v_mfma_f32_16x16x32_bf16 v[112:115], v[188:191], v[228:231], v[112:115]
	v_mfma_f32_16x16x32_bf16 v[108:111], v[196:199], v[228:231], v[108:111]
	v_mfma_f32_16x16x32_bf16 v[96:99], v[188:191], v[236:239], v[96:99]
	v_mfma_f32_16x16x32_bf16 v[92:95], v[196:199], v[236:239], v[92:95]
	v_mfma_f32_16x16x32_bf16 v[80:83], v[188:191], v[244:247], v[80:83]
	v_mfma_f32_16x16x32_bf16 v[76:79], v[196:199], v[244:247], v[76:79]
	v_mfma_f32_16x16x32_bf16 v[120:123], v[200:203], v[216:219], 0
	v_mfma_f32_16x16x32_bf16 v[116:119], v[208:211], v[216:219], 0
	v_mfma_f32_16x16x32_bf16 v[104:107], v[200:203], v[224:227], 0
	v_mfma_f32_16x16x32_bf16 v[100:103], v[208:211], v[224:227], 0
	v_mfma_f32_16x16x32_bf16 v[88:91], v[200:203], v[232:235], 0
	v_mfma_f32_16x16x32_bf16 v[84:87], v[208:211], v[232:235], 0
	v_mfma_f32_16x16x32_bf16 v[72:75], v[200:203], v[240:243], 0
	v_mfma_f32_16x16x32_bf16 v[68:71], v[208:211], v[240:243], 0
	v_mfma_f32_16x16x32_bf16 v[120:123], v[204:207], v[220:223], v[120:123]
	v_mfma_f32_16x16x32_bf16 v[116:119], v[212:215], v[220:223], v[116:119]
	v_mfma_f32_16x16x32_bf16 v[104:107], v[204:207], v[228:231], v[104:107]
	v_mfma_f32_16x16x32_bf16 v[100:103], v[212:215], v[228:231], v[100:103]
	v_mfma_f32_16x16x32_bf16 v[88:91], v[204:207], v[236:239], v[88:91]
	v_mfma_f32_16x16x32_bf16 v[84:87], v[212:215], v[236:239], v[84:87]
	v_mfma_f32_16x16x32_bf16 v[72:75], v[204:207], v[244:247], v[72:75]
	v_mfma_f32_16x16x32_bf16 v[68:71], v[212:215], v[244:247], v[68:71]
	s_barrier
	s_setprio 0
	s_add_i32 s63, s63, s27
	s_mov_b32 m0, s63
	ds_read_b128 v[216:219], v160 offset:16384
	ds_read_b128 v[220:223], v160 offset:17408
	ds_read_b128 v[224:227], v160 offset:18432
	ds_read_b128 v[228:231], v160 offset:19456
	ds_read_b128 v[232:235], v160 offset:20480
	ds_read_b128 v[236:239], v160 offset:21504
	ds_read_b128 v[240:243], v160 offset:22528
	ds_read_b128 v[244:247], v160 offset:23552
	global_load_lds_dwordx4 v2, s[20:21]
	s_add_i32 m0, s63, 0x2000
	s_add_u32 s64, s20, 0x80000
	s_addc_u32 s65, s21, 0
	s_add_i32 s63, s66, s27
	global_load_lds_dwordx4 v0, s[20:21]
	s_mov_b32 m0, s63
	v_lshl_add_u64 v[250:251], s[22:23], 0, v[132:133]
	global_load_lds_dwordx4 v2, s[64:65]
	s_add_i32 m0, s63, 0x2000
	s_nop 0
	global_load_lds_dwordx4 v0, s[64:65]
	v_lshl_add_u64 v[248:249], s[22:23], 0, v[134:135]
	s_mov_b32 m0, s17
	s_nop 0
	global_load_lds_dwordx4 v[248:249], off
	s_mov_b32 m0, s29
	s_nop 0
	global_load_lds_dwordx4 v[250:251], off
	s_waitcnt vmcnt(8)
	s_waitcnt lgkmcnt(0)
	s_setprio 1
	s_barrier
; #define PG8_STAGE(bufoff, gbase, voff) do { _Pragma("unroll") for (int _i = 0; _i < 2; ++_i) \
;         __builtin_amdgcn_global_load_lds((const unsigned*)((const char*)(gbase) + (voff)[_i]), (PG8_LAS unsigned*)(lds + (bufoff) + ldsw + _i * 8192), 16, 0, 0); } while (0)
; #define PG8_LDA(dst, b, h) do { _Pragma("unroll") for (int m = 0; m < 4; ++m) _Pragma("unroll") for (int k = 0; k < 2; ++k) dst[m][k] = *(const PG8_LAS bf16x8*)(lds + PG8_SA(b, h) + aoff + m * 2048 + k * 1024); } while (0)
; #define PG8_LDB(dst, b, h) do { _Pragma("unroll") for (int n = 0; n < 2; ++n) _Pragma("unroll") for (int k = 0; k < 2; ++k) dst[n][k] = *(const PG8_LAS bf16x8*)(lds + PG8_SB(b, h) + boff + n * 2048 + k * 1024); } while (0)
; #define PG8_MMA(ai, bj, At, Bt) do { __builtin_amdgcn_s_setprio(1); _Pragma("unroll") for (int m = 0; m < 4; ++m) _Pragma("unroll") for (int n = 0; n < 2; ++n) _Pragma("unroll") for (int k = 0; k < 2; ++k) \
;         acc[ai][bj][m][n] = __builtin_amdgcn_mfma_f32_16x16x32_bf16(Bt[n][k], At[m][k], acc[ai][bj][m][n], 0, 0, 0); __builtin_amdgcn_s_setprio(0); } while (0)
; #define PG8_WAIT_V(n) asm volatile("s_waitcnt vmcnt(" #n ")" ::: "memory")
; #define PG8_WAIT_L(n) asm volatile("s_waitcnt lgkmcnt(" #n ")" ::: "memory")
; #define PG8_BAR __builtin_amdgcn_s_barrier()
; #define PG8_SCHED __builtin_amdgcn_sched_barrier(0)
; template <class Epi, class Sched, bool ALIGN_EPI = false, bool SP2 = false>
; __device__ __forceinline__ void gemm_phase(PG8_LAS unsigned char* lds, const Gemm g, const Sched& S, const Epi& E) {
;     ...
;             PG8_WAIT_V(8); PG8_WAIT_L(0); PG8_BAR; PG8_MMA(1, 0, At, B0); PG8_MMA(1, 1, At, B1); PG8_BAR; PG8_SCHED;
;             PG8_LDB(B0, 1, 0); PG8_LDB(B1, 1, 1); PG8_SCHED; PG8_LDA(At, 1, 0); PG8_STAGE(PG8_SA(0, 1), a2 + hstep, voffA);
;             PG8_WAIT_V(8); PG8_WAIT_L(0); PG8_BAR; PG8_MMA(0, 0, At, B0); PG8_MMA(0, 1, At, B1); PG8_BAR; PG8_SCHED;
	v_mfma_f32_16x16x32_bf16 v[64:67], v[184:187], v[216:219], 0
	v_mfma_f32_16x16x32_bf16 v[60:63], v[192:195], v[216:219], 0
	v_mfma_f32_16x16x32_bf16 v[48:51], v[184:187], v[224:227], 0
	v_mfma_f32_16x16x32_bf16 v[44:47], v[192:195], v[224:227], 0
	v_mfma_f32_16x16x32_bf16 v[32:35], v[184:187], v[232:235], 0
	v_mfma_f32_16x16x32_bf16 v[28:31], v[192:195], v[232:235], 0
	v_mfma_f32_16x16x32_bf16 v[16:19], v[184:187], v[240:243], 0
	v_mfma_f32_16x16x32_bf16 v[12:15], v[192:195], v[240:243], 0
	v_mfma_f32_16x16x32_bf16 v[64:67], v[188:191], v[220:223], v[64:67]
	v_mfma_f32_16x16x32_bf16 v[60:63], v[196:199], v[220:223], v[60:63]
	v_mfma_f32_16x16x32_bf16 v[48:51], v[188:191], v[228:231], v[48:51]
	v_mfma_f32_16x16x32_bf16 v[44:47], v[196:199], v[228:231], v[44:47]
	v_mfma_f32_16x16x32_bf16 v[32:35], v[188:191], v[236:239], v[32:35]
	v_mfma_f32_16x16x32_bf16 v[28:31], v[196:199], v[236:239], v[28:31]
	v_mfma_f32_16x16x32_bf16 v[16:19], v[188:191], v[244:247], v[16:19]
	v_mfma_f32_16x16x32_bf16 v[12:15], v[196:199], v[244:247], v[12:15]
	v_mfma_f32_16x16x32_bf16 v[56:59], v[200:203], v[216:219], 0
	v_mfma_f32_16x16x32_bf16 v[52:55], v[208:211], v[216:219], 0
	v_mfma_f32_16x16x32_bf16 v[40:43], v[200:203], v[224:227], 0
	v_mfma_f32_16x16x32_bf16 v[36:39], v[208:211], v[224:227], 0
	v_mfma_f32_16x16x32_bf16 v[24:27], v[200:203], v[232:235], 0
	v_mfma_f32_16x16x32_bf16 v[20:23], v[208:211], v[232:235], 0
	v_mfma_f32_16x16x32_bf16 v[8:11], v[200:203], v[240:243], 0
	v_mfma_f32_16x16x32_bf16 v[4:7], v[208:211], v[240:243], 0
	v_mfma_f32_16x16x32_bf16 v[56:59], v[204:207], v[220:223], v[56:59]
	v_mfma_f32_16x16x32_bf16 v[52:55], v[212:215], v[220:223], v[52:55]
	v_mfma_f32_16x16x32_bf16 v[40:43], v[204:207], v[228:231], v[40:43]
	v_mfma_f32_16x16x32_bf16 v[36:39], v[212:215], v[228:231], v[36:39]
	v_mfma_f32_16x16x32_bf16 v[24:27], v[204:207], v[236:239], v[24:27]
	v_mfma_f32_16x16x32_bf16 v[20:23], v[212:215], v[236:239], v[20:23]
	v_mfma_f32_16x16x32_bf16 v[8:11], v[204:207], v[244:247], v[8:11]
	v_mfma_f32_16x16x32_bf16 v[4:7], v[212:215], v[244:247], v[4:7]
	s_barrier
	s_setprio 0
	s_add_i32 s63, 0, 0x18000
	s_add_i32 s64, 0, 0x1c000
	ds_read_b128 v[184:187], v252
	ds_read_b128 v[188:191], v252 offset:1024
	ds_read_b128 v[192:195], v252 offset:2048
	ds_read_b128 v[196:199], v252 offset:3072
	ds_read_b128 v[200:203], v253
	ds_read_b128 v[204:207], v253 offset:1024
	ds_read_b128 v[208:211], v253 offset:2048
	ds_read_b128 v[212:215], v253 offset:3072
	s_add_u32 s22, s22, 0x80000
	s_addc_u32 s23, s23, 0
	s_mov_b32 m0, s30
	ds_read_b128 v[216:219], v160 offset:32768
	ds_read_b128 v[220:223], v160 offset:33792
	ds_read_b128 v[224:227], v160 offset:34816
	ds_read_b128 v[228:231], v160 offset:35840
	ds_read_b128 v[232:235], v160 offset:36864
	ds_read_b128 v[236:239], v160 offset:37888
	ds_read_b128 v[240:243], v160 offset:38912
	ds_read_b128 v[244:247], v160 offset:39936
	global_load_lds_dwordx4 v134, s[22:23]
	s_mov_b32 m0, s31
	s_nop 0
	global_load_lds_dwordx4 v132, s[22:23]
	s_waitcnt vmcnt(8)
	s_waitcnt lgkmcnt(0)
	s_setprio 1
	s_barrier
	v_mfma_f32_16x16x32_bf16 v[128:131], v[184:187], v[216:219], v[128:131]
	v_mfma_f32_16x16x32_bf16 v[124:127], v[192:195], v[216:219], v[124:127]
	v_mfma_f32_16x16x32_bf16 v[112:115], v[184:187], v[224:227], v[112:115]
	v_mfma_f32_16x16x32_bf16 v[108:111], v[192:195], v[224:227], v[108:111]
	v_mfma_f32_16x16x32_bf16 v[96:99], v[184:187], v[232:235], v[96:99]
	v_mfma_f32_16x16x32_bf16 v[92:95], v[192:195], v[232:235], v[92:95]
	v_mfma_f32_16x16x32_bf16 v[80:83], v[184:187], v[240:243], v[80:83]
	v_mfma_f32_16x16x32_bf16 v[76:79], v[192:195], v[240:243], v[76:79]
	v_mfma_f32_16x16x32_bf16 v[128:131], v[188:191], v[220:223], v[128:131]
	v_mfma_f32_16x16x32_bf16 v[124:127], v[196:199], v[220:223], v[124:127]
	v_mfma_f32_16x16x32_bf16 v[112:115], v[188:191], v[228:231], v[112:115]
	v_mfma_f32_16x16x32_bf16 v[108:111], v[196:199], v[228:231], v[108:111]
	v_mfma_f32_16x16x32_bf16 v[96:99], v[188:191], v[236:239], v[96:99]
	v_mfma_f32_16x16x32_bf16 v[92:95], v[196:199], v[236:239], v[92:95]
	v_mfma_f32_16x16x32_bf16 v[80:83], v[188:191], v[244:247], v[80:83]
	v_mfma_f32_16x16x32_bf16 v[76:79], v[196:199], v[244:247], v[76:79]
	v_mfma_f32_16x16x32_bf16 v[120:123], v[200:203], v[216:219], v[120:123]
	v_mfma_f32_16x16x32_bf16 v[116:119], v[208:211], v[216:219], v[116:119]
	v_mfma_f32_16x16x32_bf16 v[104:107], v[200:203], v[224:227], v[104:107]
	v_mfma_f32_16x16x32_bf16 v[100:103], v[208:211], v[224:227], v[100:103]
	v_mfma_f32_16x16x32_bf16 v[88:91], v[200:203], v[232:235], v[88:91]
	v_mfma_f32_16x16x32_bf16 v[84:87], v[208:211], v[232:235], v[84:87]
	v_mfma_f32_16x16x32_bf16 v[72:75], v[200:203], v[240:243], v[72:75]
	v_mfma_f32_16x16x32_bf16 v[68:71], v[208:211], v[240:243], v[68:71]
	v_mfma_f32_16x16x32_bf16 v[120:123], v[204:207], v[220:223], v[120:123]
	v_mfma_f32_16x16x32_bf16 v[116:119], v[212:215], v[220:223], v[116:119]
	v_mfma_f32_16x16x32_bf16 v[104:107], v[204:207], v[228:231], v[104:107]
	v_mfma_f32_16x16x32_bf16 v[100:103], v[212:215], v[228:231], v[100:103]
	v_mfma_f32_16x16x32_bf16 v[88:91], v[204:207], v[236:239], v[88:91]
	v_mfma_f32_16x16x32_bf16 v[84:87], v[212:215], v[236:239], v[84:87]
	v_mfma_f32_16x16x32_bf16 v[72:75], v[204:207], v[244:247], v[72:75]
	v_mfma_f32_16x16x32_bf16 v[68:71], v[212:215], v[244:247], v[68:71]
	s_barrier
; #define PG8_STAGE(bufoff, gbase, voff) do { _Pragma("unroll") for (int _i = 0; _i < 2; ++_i) \
;         __builtin_amdgcn_global_load_lds((const unsigned*)((const char*)(gbase) + (voff)[_i]), (PG8_LAS unsigned*)(lds + (bufoff) + ldsw + _i * 8192), 16, 0, 0); } while (0)
; #define PG8_LDA(dst, b, h) do { _Pragma("unroll") for (int m = 0; m < 4; ++m) _Pragma("unroll") for (int k = 0; k < 2; ++k) dst[m][k] = *(const PG8_LAS bf16x8*)(lds + PG8_SA(b, h) + aoff + m * 2048 + k * 1024); } while (0)
; #define PG8_LDB(dst, b, h) do { _Pragma("unroll") for (int n = 0; n < 2; ++n) _Pragma("unroll") for (int k = 0; k < 2; ++k) dst[n][k] = *(const PG8_LAS bf16x8*)(lds + PG8_SB(b, h) + boff + n * 2048 + k * 1024); } while (0)
; #define PG8_MMA(ai, bj, At, Bt) do { __builtin_amdgcn_s_setprio(1); _Pragma("unroll") for (int m = 0; m < 4; ++m) _Pragma("unroll") for (int n = 0; n < 2; ++n) _Pragma("unroll") for (int k = 0; k < 2; ++k) \
;         acc[ai][bj][m][n] = __builtin_amdgcn_mfma_f32_16x16x32_bf16(Bt[n][k], At[m][k], acc[ai][bj][m][n], 0, 0, 0); __builtin_amdgcn_s_setprio(0); } while (0)
; #define PG8_WAIT_V(n) asm volatile("s_waitcnt vmcnt(" #n ")" ::: "memory")
; #define PG8_WAIT_L(n) asm volatile("s_waitcnt lgkmcnt(" #n ")" ::: "memory")
; template <class Epi, class Sched, bool ALIGN_EPI = false, bool SP2 = false>
; __device__ __forceinline__ void gemm_phase(PG8_LAS unsigned char* lds, const Gemm g, const Sched& S, const Epi& E) {
;     ...
;             const bool last = (t == nt - 2);
;             const char* a1 = cA + (size_t)(t + 1) * kstep;
;             const char* a2 = last ? nA : cA + (size_t)(t + 2) * kstep; const char* b2 = last ? nB : cB + (size_t)(t + 2) * kstep;
;             const char* a3 = a2 + kstep; const char* b3 = b2 + kstep;
;             if (last && has_next) S.a_ready(nxt);
;             if constexpr (SP2) {
;             PG8_LDB(B0, 0, 0); PG8_LDB(B1, 0, 1); PG8_SCHED; PG8_LDA(At, 0, 0); PG8_STAGE(PG8_SA(1, 1), a1 + hstep, voffA);
;             PG8_WAIT_V(8); PG8_WAIT_L(0); PG8_BAR; PG8_MMA(0, 0, At, B0); PG8_MMA(0, 1, At, B1); PG8_BAR; PG8_SCHED;
;     ...
;             PG8_LDA(At, 1, 1); PG8_STAGE(PG8_SB(1, 0), b3, voffB); PG8_STAGE(PG8_SB(1, 1), b3 + hstep, voffB); PG8_STAGE(PG8_SA(1, 0), a3, voffA);
;             PG8_WAIT_V(8); PG8_WAIT_L(0); PG8_BAR; PG8_MMA(1, 0, At, B0); PG8_MMA(1, 1, At, B1); PG8_BAR; PG8_SCHED;
	s_setprio 0
	s_add_i32 s22, s63, s27
	s_mov_b32 m0, s22
	ds_read_b128 v[216:219], v160 offset:49152
	ds_read_b128 v[220:223], v160 offset:50176
	ds_read_b128 v[224:227], v160 offset:51200
	ds_read_b128 v[228:231], v160 offset:52224
	ds_read_b128 v[232:235], v160 offset:53248
	ds_read_b128 v[236:239], v160 offset:54272
	ds_read_b128 v[240:243], v160 offset:55296
	ds_read_b128 v[244:247], v160 offset:56320
	s_add_u32 vcc_lo, s20, 0x80
	s_addc_u32 vcc_hi, s21, 0
	global_load_lds_dwordx4 v2, vcc
	s_add_i32 m0, s22, 0x2000
	s_add_u32 s20, s20, 0x80080
	s_addc_u32 s21, s21, 0
	s_add_i32 s22, s64, s27
	s_add_u32 vcc_lo, s20, 0xfff80000
	s_addc_u32 vcc_hi, s21, -1
	global_load_lds_dwordx4 v0, vcc
	s_mov_b32 m0, s22
	s_nop 0
	global_load_lds_dwordx4 v2, s[20:21]
	s_add_i32 m0, s22, 0x2000
	s_nop 0
	global_load_lds_dwordx4 v0, s[20:21]
	v_lshl_add_u64 v[152:153], v[248:249], 0, s[36:37]
	s_mov_b32 m0, s34
	s_nop 0
	global_load_lds_dwordx4 v[152:153], off
	v_lshl_add_u64 v[152:153], v[250:251], 0, s[36:37]
	s_mov_b32 m0, s35
	s_nop 0
	global_load_lds_dwordx4 v[152:153], off
	s_waitcnt vmcnt(8)
	s_waitcnt lgkmcnt(0)
	s_setprio 1
	s_barrier
	v_mfma_f32_16x16x32_bf16 v[64:67], v[184:187], v[216:219], v[64:67]
	v_mfma_f32_16x16x32_bf16 v[60:63], v[192:195], v[216:219], v[60:63]
	v_mfma_f32_16x16x32_bf16 v[48:51], v[184:187], v[224:227], v[48:51]
	v_mfma_f32_16x16x32_bf16 v[44:47], v[192:195], v[224:227], v[44:47]
	v_mfma_f32_16x16x32_bf16 v[32:35], v[184:187], v[232:235], v[32:35]
	v_mfma_f32_16x16x32_bf16 v[28:31], v[192:195], v[232:235], v[28:31]
	v_mfma_f32_16x16x32_bf16 v[16:19], v[184:187], v[240:243], v[16:19]
	v_mfma_f32_16x16x32_bf16 v[12:15], v[192:195], v[240:243], v[12:15]
	v_mfma_f32_16x16x32_bf16 v[64:67], v[188:191], v[220:223], v[64:67]
	v_mfma_f32_16x16x32_bf16 v[60:63], v[196:199], v[220:223], v[60:63]
	v_mfma_f32_16x16x32_bf16 v[48:51], v[188:191], v[228:231], v[48:51]
	v_mfma_f32_16x16x32_bf16 v[44:47], v[196:199], v[228:231], v[44:47]
	v_mfma_f32_16x16x32_bf16 v[32:35], v[188:191], v[236:239], v[32:35]
	v_mfma_f32_16x16x32_bf16 v[28:31], v[196:199], v[236:239], v[28:31]
	v_mfma_f32_16x16x32_bf16 v[16:19], v[188:191], v[244:247], v[16:19]
	v_mfma_f32_16x16x32_bf16 v[12:15], v[196:199], v[244:247], v[12:15]
	v_mfma_f32_16x16x32_bf16 v[56:59], v[200:203], v[216:219], v[56:59]
	v_mfma_f32_16x16x32_bf16 v[52:55], v[208:211], v[216:219], v[52:55]
	v_mfma_f32_16x16x32_bf16 v[40:43], v[200:203], v[224:227], v[40:43]
	v_mfma_f32_16x16x32_bf16 v[36:39], v[208:211], v[224:227], v[36:39]
	v_mfma_f32_16x16x32_bf16 v[24:27], v[200:203], v[232:235], v[24:27]
	v_mfma_f32_16x16x32_bf16 v[20:23], v[208:211], v[232:235], v[20:23]
	v_mfma_f32_16x16x32_bf16 v[8:11], v[200:203], v[240:243], v[8:11]
	v_mfma_f32_16x16x32_bf16 v[4:7], v[208:211], v[240:243], v[4:7]
	v_mfma_f32_16x16x32_bf16 v[56:59], v[204:207], v[220:223], v[56:59]
	v_mfma_f32_16x16x32_bf16 v[52:55], v[212:215], v[220:223], v[52:55]
	v_mfma_f32_16x16x32_bf16 v[40:43], v[204:207], v[228:231], v[40:43]
	v_mfma_f32_16x16x32_bf16 v[36:39], v[212:215], v[228:231], v[36:39]
	v_mfma_f32_16x16x32_bf16 v[24:27], v[204:207], v[236:239], v[24:27]
	v_mfma_f32_16x16x32_bf16 v[20:23], v[212:215], v[236:239], v[20:23]
	v_mfma_f32_16x16x32_bf16 v[8:11], v[204:207], v[244:247], v[8:11]
	v_mfma_f32_16x16x32_bf16 v[4:7], v[212:215], v[244:247], v[4:7]
	s_barrier
	s_setprio 0
	s_add_i32 s57, s57, 2
	s_add_u32 s18, s18, 0x100
	s_addc_u32 s19, s19, 0
	s_add_u32 s51, s51, 0x100
	s_addc_u32 s56, s56, 0
	s_cmp_gt_u32 s57, 29
.LBB0_251:
	s_add_u32 s20, s18, 0xfff80080
	s_addc_u32 s21, s19, -1
	s_add_i32 s63, 0, 0x10000
	s_cmp_eq_u32 s57, 28
	s_cselect_b32 s23, s11, s21
	s_cselect_b32 s22, s45, s20
	s_cselect_b32 s21, s7, s56
	s_cselect_b32 s20, s50, s51
	s_add_i32 s66, 0, 0x14000
	ds_read_b128 v[184:187], v166
	ds_read_b128 v[188:191], v166 offset:1024
	ds_read_b128 v[192:195], v166 offset:2048
	ds_read_b128 v[196:199], v166 offset:3072
	ds_read_b128 v[200:203], v167
	ds_read_b128 v[204:207], v167 offset:1024
	ds_read_b128 v[208:211], v167 offset:2048
	ds_read_b128 v[212:215], v167 offset:3072
	s_add_i32 m0, s17, 0xc000
	ds_read_b128 v[216:219], v160
	ds_read_b128 v[220:223], v160 offset:1024
	ds_read_b128 v[224:227], v160 offset:2048
	ds_read_b128 v[228:231], v160 offset:3072
	ds_read_b128 v[232:235], v160 offset:4096
	ds_read_b128 v[236:239], v160 offset:5120
	ds_read_b128 v[240:243], v160 offset:6144
	ds_read_b128 v[244:247], v160 offset:7168
	global_load_lds_dwordx4 v136, s[18:19]
	s_add_i32 m0, s17, 0xe000
	s_nop 0
	global_load_lds_dwordx4 v138, s[18:19]
	s_waitcnt vmcnt(8)
	s_waitcnt lgkmcnt(0)
	s_setprio 1
	s_barrier
; #define PG8_STAGE(bufoff, gbase, voff) do { _Pragma("unroll") for (int _i = 0; _i < 2; ++_i) \
;         __builtin_amdgcn_global_load_lds((const unsigned*)((const char*)(gbase) + (voff)[_i]), (PG8_LAS unsigned*)(lds + (bufoff) + ldsw + _i * 8192), 16, 0, 0); } while (0)
; #define PG8_LDA(dst, b, h) do { _Pragma("unroll") for (int m = 0; m < 4; ++m) _Pragma("unroll") for (int k = 0; k < 2; ++k) dst[m][k] = *(const PG8_LAS bf16x8*)(lds + PG8_SA(b, h) + aoff + m * 2048 + k * 1024); } while (0)
; #define PG8_MMA(ai, bj, At, Bt) do { __builtin_amdgcn_s_setprio(1); _Pragma("unroll") for (int m = 0; m < 4; ++m) _Pragma("unroll") for (int n = 0; n < 2; ++n) _Pragma("unroll") for (int k = 0; k < 2; ++k) \
;         acc[ai][bj][m][n] = __builtin_amdgcn_mfma_f32_16x16x32_bf16(Bt[n][k], At[m][k], acc[ai][bj][m][n], 0, 0, 0); __builtin_amdgcn_s_setprio(0); } while (0)
; #define PG8_WAIT_V(n) asm volatile("s_waitcnt vmcnt(" #n ")" ::: "memory")
; #define PG8_WAIT_L(n) asm volatile("s_waitcnt lgkmcnt(" #n ")" ::: "memory")
; #define PG8_BAR __builtin_amdgcn_s_barrier()
; #define PG8_SCHED __builtin_amdgcn_sched_barrier(0)
; template <class Epi, class Sched, bool ALIGN_EPI = false, bool SP2 = false>
; __device__ __forceinline__ void gemm_phase(PG8_LAS unsigned char* lds, const Gemm g, const Sched& S, const Epi& E) {
;     ...
;             PG8_WAIT_V(8); PG8_WAIT_L(0); PG8_BAR; PG8_MMA(0, 0, At, B0); PG8_MMA(0, 1, At, B1); PG8_BAR; PG8_SCHED;
;             PG8_LDA(At, 0, 1); PG8_STAGE(PG8_SB(0, 0), b2, voffB); PG8_STAGE(PG8_SB(0, 1), b2 + hstep, voffB); PG8_STAGE(PG8_SA(0, 0), a2, voffA);
;             PG8_WAIT_V(8); PG8_WAIT_L(0); PG8_BAR; PG8_MMA(1, 0, At, B0); PG8_MMA(1, 1, At, B1); PG8_BAR; PG8_SCHED;
	v_mfma_f32_16x16x32_bf16 v[128:131], v[184:187], v[216:219], v[128:131]
	v_mfma_f32_16x16x32_bf16 v[124:127], v[192:195], v[216:219], v[124:127]
	v_mfma_f32_16x16x32_bf16 v[112:115], v[184:187], v[224:227], v[112:115]
	v_mfma_f32_16x16x32_bf16 v[108:111], v[192:195], v[224:227], v[108:111]
	v_mfma_f32_16x16x32_bf16 v[96:99], v[184:187], v[232:235], v[96:99]
	v_mfma_f32_16x16x32_bf16 v[92:95], v[192:195], v[232:235], v[92:95]
	v_mfma_f32_16x16x32_bf16 v[80:83], v[184:187], v[240:243], v[80:83]
	v_mfma_f32_16x16x32_bf16 v[76:79], v[192:195], v[240:243], v[76:79]
	v_mfma_f32_16x16x32_bf16 v[128:131], v[188:191], v[220:223], v[128:131]
	v_mfma_f32_16x16x32_bf16 v[124:127], v[196:199], v[220:223], v[124:127]
	v_mfma_f32_16x16x32_bf16 v[112:115], v[188:191], v[228:231], v[112:115]
	v_mfma_f32_16x16x32_bf16 v[108:111], v[196:199], v[228:231], v[108:111]
	v_mfma_f32_16x16x32_bf16 v[96:99], v[188:191], v[236:239], v[96:99]
	v_mfma_f32_16x16x32_bf16 v[92:95], v[196:199], v[236:239], v[92:95]
	v_mfma_f32_16x16x32_bf16 v[80:83], v[188:191], v[244:247], v[80:83]
	v_mfma_f32_16x16x32_bf16 v[76:79], v[196:199], v[244:247], v[76:79]
	v_mfma_f32_16x16x32_bf16 v[120:123], v[200:203], v[216:219], v[120:123]
	v_mfma_f32_16x16x32_bf16 v[116:119], v[208:211], v[216:219], v[116:119]
	v_mfma_f32_16x16x32_bf16 v[104:107], v[200:203], v[224:227], v[104:107]
	v_mfma_f32_16x16x32_bf16 v[100:103], v[208:211], v[224:227], v[100:103]
	v_mfma_f32_16x16x32_bf16 v[88:91], v[200:203], v[232:235], v[88:91]
	v_mfma_f32_16x16x32_bf16 v[84:87], v[208:211], v[232:235], v[84:87]
	v_mfma_f32_16x16x32_bf16 v[72:75], v[200:203], v[240:243], v[72:75]
	v_mfma_f32_16x16x32_bf16 v[68:71], v[208:211], v[240:243], v[68:71]
	v_mfma_f32_16x16x32_bf16 v[120:123], v[204:207], v[220:223], v[120:123]
	v_mfma_f32_16x16x32_bf16 v[116:119], v[212:215], v[220:223], v[116:119]
	v_mfma_f32_16x16x32_bf16 v[104:107], v[204:207], v[228:231], v[104:107]
	v_mfma_f32_16x16x32_bf16 v[100:103], v[212:215], v[228:231], v[100:103]
	v_mfma_f32_16x16x32_bf16 v[88:91], v[204:207], v[236:239], v[88:91]
	v_mfma_f32_16x16x32_bf16 v[84:87], v[212:215], v[236:239], v[84:87]
	v_mfma_f32_16x16x32_bf16 v[72:75], v[204:207], v[244:247], v[72:75]
	v_mfma_f32_16x16x32_bf16 v[68:71], v[212:215], v[244:247], v[68:71]
	s_barrier
	s_setprio 0
	s_add_i32 s63, s63, s27
	s_mov_b32 m0, s63
	ds_read_b128 v[216:219], v160 offset:16384
	ds_read_b128 v[220:223], v160 offset:17408
	ds_read_b128 v[224:227], v160 offset:18432
	ds_read_b128 v[228:231], v160 offset:19456
	ds_read_b128 v[232:235], v160 offset:20480
	ds_read_b128 v[236:239], v160 offset:21504
	ds_read_b128 v[240:243], v160 offset:22528
	ds_read_b128 v[244:247], v160 offset:23552
	global_load_lds_dwordx4 v2, s[20:21]
	s_add_i32 m0, s63, 0x2000
	s_add_u32 s64, s20, 0x80000
	s_addc_u32 s65, s21, 0
	s_add_i32 s63, s66, s27
	global_load_lds_dwordx4 v0, s[20:21]
	s_mov_b32 m0, s63
	v_lshl_add_u64 v[250:251], s[22:23], 0, v[132:133]
	global_load_lds_dwordx4 v2, s[64:65]
	s_add_i32 m0, s63, 0x2000
	s_nop 0
	global_load_lds_dwordx4 v0, s[64:65]
	v_lshl_add_u64 v[248:249], s[22:23], 0, v[134:135]
	s_mov_b32 m0, s17
	s_nop 0
	global_load_lds_dwordx4 v[248:249], off
	s_mov_b32 m0, s29
	s_nop 0
	global_load_lds_dwordx4 v[250:251], off
	s_waitcnt vmcnt(8)
	s_waitcnt lgkmcnt(0)
	s_setprio 1
	s_barrier
	v_mfma_f32_16x16x32_bf16 v[64:67], v[184:187], v[216:219], v[64:67]
	v_mfma_f32_16x16x32_bf16 v[60:63], v[192:195], v[216:219], v[60:63]
	v_mfma_f32_16x16x32_bf16 v[48:51], v[184:187], v[224:227], v[48:51]
	v_mfma_f32_16x16x32_bf16 v[44:47], v[192:195], v[224:227], v[44:47]
	v_mfma_f32_16x16x32_bf16 v[32:35], v[184:187], v[232:235], v[32:35]
	v_mfma_f32_16x16x32_bf16 v[28:31], v[192:195], v[232:235], v[28:31]
	v_mfma_f32_16x16x32_bf16 v[16:19], v[184:187], v[240:243], v[16:19]
	v_mfma_f32_16x16x32_bf16 v[12:15], v[192:195], v[240:243], v[12:15]
	v_mfma_f32_16x16x32_bf16 v[64:67], v[188:191], v[220:223], v[64:67]
	v_mfma_f32_16x16x32_bf16 v[60:63], v[196:199], v[220:223], v[60:63]
	v_mfma_f32_16x16x32_bf16 v[48:51], v[188:191], v[228:231], v[48:51]
	v_mfma_f32_16x16x32_bf16 v[44:47], v[196:199], v[228:231], v[44:47]
	v_mfma_f32_16x16x32_bf16 v[32:35], v[188:191], v[236:239], v[32:35]
	v_mfma_f32_16x16x32_bf16 v[28:31], v[196:199], v[236:239], v[28:31]
	v_mfma_f32_16x16x32_bf16 v[16:19], v[188:191], v[244:247], v[16:19]
	v_mfma_f32_16x16x32_bf16 v[12:15], v[196:199], v[244:247], v[12:15]
	v_mfma_f32_16x16x32_bf16 v[56:59], v[200:203], v[216:219], v[56:59]
	v_mfma_f32_16x16x32_bf16 v[52:55], v[208:211], v[216:219], v[52:55]
	v_mfma_f32_16x16x32_bf16 v[40:43], v[200:203], v[224:227], v[40:43]
	v_mfma_f32_16x16x32_bf16 v[36:39], v[208:211], v[224:227], v[36:39]
	v_mfma_f32_16x16x32_bf16 v[24:27], v[200:203], v[232:235], v[24:27]
	v_mfma_f32_16x16x32_bf16 v[20:23], v[208:211], v[232:235], v[20:23]
	v_mfma_f32_16x16x32_bf16 v[8:11], v[200:203], v[240:243], v[8:11]
	v_mfma_f32_16x16x32_bf16 v[4:7], v[208:211], v[240:243], v[4:7]
	v_mfma_f32_16x16x32_bf16 v[56:59], v[204:207], v[220:223], v[56:59]
	v_mfma_f32_16x16x32_bf16 v[52:55], v[212:215], v[220:223], v[52:55]
	v_mfma_f32_16x16x32_bf16 v[40:43], v[204:207], v[228:231], v[40:43]
	v_mfma_f32_16x16x32_bf16 v[36:39], v[212:215], v[228:231], v[36:39]
	v_mfma_f32_16x16x32_bf16 v[24:27], v[204:207], v[236:239], v[24:27]
	v_mfma_f32_16x16x32_bf16 v[20:23], v[212:215], v[236:239], v[20:23]
	v_mfma_f32_16x16x32_bf16 v[8:11], v[204:207], v[244:247], v[8:11]
	v_mfma_f32_16x16x32_bf16 v[4:7], v[212:215], v[244:247], v[4:7]
	s_barrier
; #define PG8_STAGE(bufoff, gbase, voff) do { _Pragma("unroll") for (int _i = 0; _i < 2; ++_i) \
;         __builtin_amdgcn_global_load_lds((const unsigned*)((const char*)(gbase) + (voff)[_i]), (PG8_LAS unsigned*)(lds + (bufoff) + ldsw + _i * 8192), 16, 0, 0); } while (0)
; #define PG8_LDA(dst, b, h) do { _Pragma("unroll") for (int m = 0; m < 4; ++m) _Pragma("unroll") for (int k = 0; k < 2; ++k) dst[m][k] = *(const PG8_LAS bf16x8*)(lds + PG8_SA(b, h) + aoff + m * 2048 + k * 1024); } while (0)
; #define PG8_LDB(dst, b, h) do { _Pragma("unroll") for (int n = 0; n < 2; ++n) _Pragma("unroll") for (int k = 0; k < 2; ++k) dst[n][k] = *(const PG8_LAS bf16x8*)(lds + PG8_SB(b, h) + boff + n * 2048 + k * 1024); } while (0)
; #define PG8_MMA(ai, bj, At, Bt) do { __builtin_amdgcn_s_setprio(1); _Pragma("unroll") for (int m = 0; m < 4; ++m) _Pragma("unroll") for (int n = 0; n < 2; ++n) _Pragma("unroll") for (int k = 0; k < 2; ++k) \
;         acc[ai][bj][m][n] = __builtin_amdgcn_mfma_f32_16x16x32_bf16(Bt[n][k], At[m][k], acc[ai][bj][m][n], 0, 0, 0); __builtin_amdgcn_s_setprio(0); } while (0)
; #define PG8_WAIT_V(n) asm volatile("s_waitcnt vmcnt(" #n ")" ::: "memory")
; #define PG8_WAIT_L(n) asm volatile("s_waitcnt lgkmcnt(" #n ")" ::: "memory")
; #define PG8_BAR __builtin_amdgcn_s_barrier()
; #define PG8_SCHED __builtin_amdgcn_sched_barrier(0)
; template <class Epi, class Sched, bool ALIGN_EPI = false, bool SP2 = false>
; __device__ __forceinline__ void gemm_phase(PG8_LAS unsigned char* lds, const Gemm g, const Sched& S, const Epi& E) {
;     ...
;             PG8_LDB(B0, 1, 0); PG8_LDB(B1, 1, 1); PG8_SCHED; PG8_LDA(At, 1, 0); PG8_STAGE(PG8_SA(0, 1), a2 + hstep, voffA);
;             PG8_WAIT_V(8); PG8_WAIT_L(0); PG8_BAR; PG8_MMA(0, 0, At, B0); PG8_MMA(0, 1, At, B1); PG8_BAR; PG8_SCHED;
;             PG8_LDA(At, 1, 1); PG8_STAGE(PG8_SB(1, 0), b3, voffB); PG8_STAGE(PG8_SB(1, 1), b3 + hstep, voffB); PG8_STAGE(PG8_SA(1, 0), a3, voffA);
;             PG8_WAIT_V(8); PG8_WAIT_L(0); PG8_BAR; PG8_MMA(1, 0, At, B0); PG8_MMA(1, 1, At, B1); PG8_BAR; PG8_SCHED;
;     ...
;         if constexpr (ALIGN_EPI) { if (wr == 0) PG8_BAR; }
	s_setprio 0
	s_add_i32 s63, 0, 0x18000
	s_add_i32 s64, 0, 0x1c000
	ds_read_b128 v[184:187], v252
	ds_read_b128 v[188:191], v252 offset:1024
	ds_read_b128 v[192:195], v252 offset:2048
	ds_read_b128 v[196:199], v252 offset:3072
	ds_read_b128 v[200:203], v253
	ds_read_b128 v[204:207], v253 offset:1024
	ds_read_b128 v[208:211], v253 offset:2048
	ds_read_b128 v[212:215], v253 offset:3072
	s_add_u32 s22, s22, 0x80000
	s_addc_u32 s23, s23, 0
	s_mov_b32 m0, s30
	ds_read_b128 v[216:219], v160 offset:32768
	ds_read_b128 v[220:223], v160 offset:33792
	ds_read_b128 v[224:227], v160 offset:34816
	ds_read_b128 v[228:231], v160 offset:35840
	ds_read_b128 v[232:235], v160 offset:36864
	ds_read_b128 v[236:239], v160 offset:37888
	ds_read_b128 v[240:243], v160 offset:38912
	ds_read_b128 v[244:247], v160 offset:39936
	global_load_lds_dwordx4 v134, s[22:23]
	s_mov_b32 m0, s31
	s_nop 0
	global_load_lds_dwordx4 v132, s[22:23]
	s_waitcnt vmcnt(8)
	s_waitcnt lgkmcnt(0)
	s_setprio 1
	s_barrier
	v_mfma_f32_16x16x32_bf16 v[128:131], v[184:187], v[216:219], v[128:131]
	v_mfma_f32_16x16x32_bf16 v[124:127], v[192:195], v[216:219], v[124:127]
	v_mfma_f32_16x16x32_bf16 v[112:115], v[184:187], v[224:227], v[112:115]
	v_mfma_f32_16x16x32_bf16 v[108:111], v[192:195], v[224:227], v[108:111]
	v_mfma_f32_16x16x32_bf16 v[96:99], v[184:187], v[232:235], v[96:99]
	v_mfma_f32_16x16x32_bf16 v[92:95], v[192:195], v[232:235], v[92:95]
	v_mfma_f32_16x16x32_bf16 v[80:83], v[184:187], v[240:243], v[80:83]
	v_mfma_f32_16x16x32_bf16 v[76:79], v[192:195], v[240:243], v[76:79]
	v_mfma_f32_16x16x32_bf16 v[128:131], v[188:191], v[220:223], v[128:131]
	v_mfma_f32_16x16x32_bf16 v[124:127], v[196:199], v[220:223], v[124:127]
	v_mfma_f32_16x16x32_bf16 v[112:115], v[188:191], v[228:231], v[112:115]
	v_mfma_f32_16x16x32_bf16 v[108:111], v[196:199], v[228:231], v[108:111]
	v_mfma_f32_16x16x32_bf16 v[96:99], v[188:191], v[236:239], v[96:99]
	v_mfma_f32_16x16x32_bf16 v[92:95], v[196:199], v[236:239], v[92:95]
	v_mfma_f32_16x16x32_bf16 v[80:83], v[188:191], v[244:247], v[80:83]
	v_mfma_f32_16x16x32_bf16 v[76:79], v[196:199], v[244:247], v[76:79]
	v_mfma_f32_16x16x32_bf16 v[120:123], v[200:203], v[216:219], v[120:123]
	v_mfma_f32_16x16x32_bf16 v[116:119], v[208:211], v[216:219], v[116:119]
	v_mfma_f32_16x16x32_bf16 v[104:107], v[200:203], v[224:227], v[104:107]
	v_mfma_f32_16x16x32_bf16 v[100:103], v[208:211], v[224:227], v[100:103]
	v_mfma_f32_16x16x32_bf16 v[88:91], v[200:203], v[232:235], v[88:91]
	v_mfma_f32_16x16x32_bf16 v[84:87], v[208:211], v[232:235], v[84:87]
	v_mfma_f32_16x16x32_bf16 v[72:75], v[200:203], v[240:243], v[72:75]
	v_mfma_f32_16x16x32_bf16 v[68:71], v[208:211], v[240:243], v[68:71]
	v_mfma_f32_16x16x32_bf16 v[120:123], v[204:207], v[220:223], v[120:123]
	v_mfma_f32_16x16x32_bf16 v[116:119], v[212:215], v[220:223], v[116:119]
	v_mfma_f32_16x16x32_bf16 v[104:107], v[204:207], v[228:231], v[104:107]
	v_mfma_f32_16x16x32_bf16 v[100:103], v[212:215], v[228:231], v[100:103]
	v_mfma_f32_16x16x32_bf16 v[88:91], v[204:207], v[236:239], v[88:91]
	v_mfma_f32_16x16x32_bf16 v[84:87], v[212:215], v[236:239], v[84:87]
	v_mfma_f32_16x16x32_bf16 v[72:75], v[204:207], v[244:247], v[72:75]
	v_mfma_f32_16x16x32_bf16 v[68:71], v[212:215], v[244:247], v[68:71]
	s_barrier
	s_setprio 0
	s_add_i32 s22, s63, s27
	s_mov_b32 m0, s22
	ds_read_b128 v[216:219], v160 offset:49152
	ds_read_b128 v[220:223], v160 offset:50176
	ds_read_b128 v[224:227], v160 offset:51200
	ds_read_b128 v[228:231], v160 offset:52224
	ds_read_b128 v[232:235], v160 offset:53248
	ds_read_b128 v[236:239], v160 offset:54272
	ds_read_b128 v[240:243], v160 offset:55296
	ds_read_b128 v[244:247], v160 offset:56320
	s_add_u32 vcc_lo, s20, 0x80
	s_addc_u32 vcc_hi, s21, 0
	global_load_lds_dwordx4 v2, vcc
	s_add_i32 m0, s22, 0x2000
	s_add_u32 s20, s20, 0x80080
	s_addc_u32 s21, s21, 0
	s_add_i32 s22, s64, s27
	s_add_u32 vcc_lo, s20, 0xfff80000
	s_addc_u32 vcc_hi, s21, -1
	global_load_lds_dwordx4 v0, vcc
	s_mov_b32 m0, s22
	s_nop 0
	global_load_lds_dwordx4 v2, s[20:21]
	s_add_i32 m0, s22, 0x2000
	s_nop 0
	global_load_lds_dwordx4 v0, s[20:21]
	v_lshl_add_u64 v[152:153], v[248:249], 0, s[36:37]
	s_mov_b32 m0, s34
	s_nop 0
	global_load_lds_dwordx4 v[152:153], off
	v_lshl_add_u64 v[152:153], v[250:251], 0, s[36:37]
	s_mov_b32 m0, s35
	s_nop 0
	global_load_lds_dwordx4 v[152:153], off
	s_waitcnt vmcnt(8)
	s_waitcnt lgkmcnt(0)
	s_setprio 1
	s_barrier
	v_mfma_f32_16x16x32_bf16 v[64:67], v[184:187], v[216:219], v[64:67]
	v_mfma_f32_16x16x32_bf16 v[60:63], v[192:195], v[216:219], v[60:63]
	v_mfma_f32_16x16x32_bf16 v[48:51], v[184:187], v[224:227], v[48:51]
	v_mfma_f32_16x16x32_bf16 v[44:47], v[192:195], v[224:227], v[44:47]
	v_mfma_f32_16x16x32_bf16 v[32:35], v[184:187], v[232:235], v[32:35]
	v_mfma_f32_16x16x32_bf16 v[28:31], v[192:195], v[232:235], v[28:31]
	v_mfma_f32_16x16x32_bf16 v[16:19], v[184:187], v[240:243], v[16:19]
	v_mfma_f32_16x16x32_bf16 v[12:15], v[192:195], v[240:243], v[12:15]
	v_mfma_f32_16x16x32_bf16 v[64:67], v[188:191], v[220:223], v[64:67]
	v_mfma_f32_16x16x32_bf16 v[60:63], v[196:199], v[220:223], v[60:63]
	v_mfma_f32_16x16x32_bf16 v[48:51], v[188:191], v[228:231], v[48:51]
	v_mfma_f32_16x16x32_bf16 v[44:47], v[196:199], v[228:231], v[44:47]
	v_mfma_f32_16x16x32_bf16 v[32:35], v[188:191], v[236:239], v[32:35]
	v_mfma_f32_16x16x32_bf16 v[28:31], v[196:199], v[236:239], v[28:31]
	v_mfma_f32_16x16x32_bf16 v[16:19], v[188:191], v[244:247], v[16:19]
	v_mfma_f32_16x16x32_bf16 v[12:15], v[196:199], v[244:247], v[12:15]
	v_mfma_f32_16x16x32_bf16 v[56:59], v[200:203], v[216:219], v[56:59]
	v_mfma_f32_16x16x32_bf16 v[52:55], v[208:211], v[216:219], v[52:55]
	v_mfma_f32_16x16x32_bf16 v[40:43], v[200:203], v[224:227], v[40:43]
	v_mfma_f32_16x16x32_bf16 v[36:39], v[208:211], v[224:227], v[36:39]
	v_mfma_f32_16x16x32_bf16 v[24:27], v[200:203], v[232:235], v[24:27]
	v_mfma_f32_16x16x32_bf16 v[20:23], v[208:211], v[232:235], v[20:23]
	v_mfma_f32_16x16x32_bf16 v[8:11], v[200:203], v[240:243], v[8:11]
	v_mfma_f32_16x16x32_bf16 v[4:7], v[208:211], v[240:243], v[4:7]
	v_mfma_f32_16x16x32_bf16 v[56:59], v[204:207], v[220:223], v[56:59]
	v_mfma_f32_16x16x32_bf16 v[52:55], v[212:215], v[220:223], v[52:55]
	v_mfma_f32_16x16x32_bf16 v[40:43], v[204:207], v[228:231], v[40:43]
	v_mfma_f32_16x16x32_bf16 v[36:39], v[212:215], v[228:231], v[36:39]
	v_mfma_f32_16x16x32_bf16 v[24:27], v[204:207], v[236:239], v[24:27]
	v_mfma_f32_16x16x32_bf16 v[20:23], v[212:215], v[236:239], v[20:23]
	v_mfma_f32_16x16x32_bf16 v[8:11], v[204:207], v[244:247], v[8:11]
	v_mfma_f32_16x16x32_bf16 v[4:7], v[212:215], v[244:247], v[4:7]
	s_barrier
	s_setprio 0
	s_add_i32 s57, s57, 2
	s_add_u32 s18, s18, 0x100
	s_addc_u32 s19, s19, 0
	s_add_u32 s51, s51, 0x100
	s_addc_u32 s56, s56, 0
	s_cmp_gt_u32 s57, 29
	s_cbranch_scc0 .LBB0_251
	s_and_b64 vcc, exec, s[4:5]
	s_cbranch_vccz .LBB0_254
	s_barrier

; #define PG8_STAGE(bufoff, gbase, voff) do { _Pragma("unroll") for (int _i = 0; _i < 2; ++_i) \
;         __builtin_amdgcn_global_load_lds((const unsigned*)((const char*)(gbase) + (voff)[_i]), (PG8_LAS unsigned*)(lds + (bufoff) + ldsw + _i * 8192), 16, 0, 0); } while (0)
; #define PG8_LDA(dst, b, h) do { _Pragma("unroll") for (int m = 0; m < 4; ++m) _Pragma("unroll") for (int k = 0; k < 2; ++k) dst[m][k] = *(const PG8_LAS bf16x8*)(lds + PG8_SA(b, h) + aoff + m * 2048 + k * 1024); } while (0)
; #define PG8_LDB(dst, b, h) do { _Pragma("unroll") for (int n = 0; n < 2; ++n) _Pragma("unroll") for (int k = 0; k < 2; ++k) dst[n][k] = *(const PG8_LAS bf16x8*)(lds + PG8_SB(b, h) + boff + n * 2048 + k * 1024); } while (0)
; #define PG8_WAIT_V(n) asm volatile("s_waitcnt vmcnt(" #n ")" ::: "memory")
; #define PG8_WAIT_L(n) asm volatile("s_waitcnt lgkmcnt(" #n ")" ::: "memory")
; #define PG8_BAR __builtin_amdgcn_s_barrier()
; #define PG8_SCHED __builtin_amdgcn_sched_barrier(0)
; template <class Epi, class Sched, bool ALIGN_EPI = false, bool SP2 = false>
; __device__ __forceinline__ void gemm_phase(PG8_LAS unsigned char* lds, const Gemm g, const Sched& S, const Epi& E) {
;     ...
;         const bool has_next = S.next(ui + 1, nxt);
;         const char* nA = has_next ? (const char*)g.A + (size_t)nxt.pm * tstep : cA; const char* nB = has_next ? (const char*)g.Bt + (size_t)nxt.pn * tstep : cB;
;         for (int t = 0; t < nt; t += 2) {
;             const bool last = (t == nt - 2);
;             const char* a1 = cA + (size_t)(t + 1) * kstep;
;             const char* a2 = last ? nA : cA + (size_t)(t + 2) * kstep; const char* b2 = last ? nB : cB + (size_t)(t + 2) * kstep;
;             const char* a3 = a2 + kstep; const char* b3 = b2 + kstep;
;             if (last && has_next) S.a_ready(nxt);
;             if constexpr (SP2) {
;             PG8_LDB(B0, 0, 0); PG8_LDB(B1, 0, 1); PG8_SCHED; PG8_LDA(At, 0, 0); PG8_STAGE(PG8_SA(1, 1), a1 + hstep, voffA);
;             PG8_WAIT_V(8); PG8_WAIT_L(0); PG8_BAR; PG8_MMA(0, 0, At, B0); PG8_MMA(0, 1, At, B1); PG8_BAR; PG8_SCHED;
;             PG8_LDA(At, 0, 1); PG8_STAGE(PG8_SB(0, 0), b2, voffB); PG8_STAGE(PG8_SB(0, 1), b2 + hstep, voffB); PG8_STAGE(PG8_SA(0, 0), a2, voffA);
;             PG8_WAIT_V(8); PG8_WAIT_L(0); PG8_BAR; PG8_MMA(1, 0, At, B0); PG8_MMA(1, 1, At, B1); PG8_BAR; PG8_SCHED;
.LBB0_482:
	s_ashr_i32 s13, s12, 31
	s_lshl_b64 s[14:15], s[12:13], 20
	s_add_u32 s14, s54, s14
	s_addc_u32 s15, s55, s15
	s_and_b64 s[16:17], s[4:5], exec
	s_cselect_b32 s13, s15, s23
	s_cselect_b32 s19, s14, s22
	s_ashr_i32 s11, s10, 31
	s_lshl_b64 s[16:17], s[10:11], 20
	s_add_u32 s16, s29, s16
	s_addc_u32 s17, s30, s17
	s_and_b64 s[26:27], s[4:5], exec
	s_cselect_b32 s11, s17, s25
	s_cselect_b32 s56, s16, s24
	s_add_u32 s22, s22, 0x80080
	s_addc_u32 s23, s23, 0
	s_add_u32 s57, s24, 0x100
	s_addc_u32 s63, s25, 0
	s_mov_b32 s64, -2
	s_waitcnt lgkmcnt(0)
	v_add_u32_e32 v236, 0x10000, v185
	v_add_u32_e32 v237, 0x14000, v185
	v_add_u32_e32 v242, 0x18000, v185
	v_add_u32_e32 v243, 0x1c000, v185
	s_add_u32 s24, s22, 0xfff80080
	s_addc_u32 s25, s23, -1
	s_add_i32 s65, 0, 0x10000
	s_cmp_eq_u32 s64, 28
	s_cselect_b32 s27, s13, s25
	s_cselect_b32 s26, s19, s24
	s_cselect_b32 s25, s11, s63
	s_cselect_b32 s24, s56, s57
	s_add_i32 s76, 0, 0x14000
	ds_read_b128 v[132:135], v236
	ds_read_b128 v[136:139], v236 offset:1024
	ds_read_b128 v[158:161], v236 offset:2048
	ds_read_b128 v[162:165], v236 offset:3072
	ds_read_b128 v[188:191], v237
	ds_read_b128 v[192:195], v237 offset:1024
	ds_read_b128 v[196:199], v237 offset:2048
	ds_read_b128 v[200:203], v237 offset:3072
	s_add_i32 m0, s21, 0xc000
	ds_read_b128 v[204:207], v187
	ds_read_b128 v[208:211], v187 offset:1024
	ds_read_b128 v[212:215], v187 offset:2048
	ds_read_b128 v[216:219], v187 offset:3072
	ds_read_b128 v[220:223], v187 offset:4096
	ds_read_b128 v[224:227], v187 offset:5120
	ds_read_b128 v[228:231], v187 offset:6144
	ds_read_b128 v[232:235], v187 offset:7168
	global_load_lds_dwordx4 v154, s[22:23]
	s_add_i32 m0, s21, 0xe000
	s_nop 0
	global_load_lds_dwordx4 v156, s[22:23]
	s_waitcnt vmcnt(8)
	s_waitcnt lgkmcnt(0)
	s_setprio 1
	s_barrier
	v_mfma_f32_16x16x32_bf16 v[128:131], v[132:135], v[204:207], 0
	v_mfma_f32_16x16x32_bf16 v[124:127], v[158:161], v[204:207], 0
	v_mfma_f32_16x16x32_bf16 v[112:115], v[132:135], v[212:215], 0
	v_mfma_f32_16x16x32_bf16 v[108:111], v[158:161], v[212:215], 0
	v_mfma_f32_16x16x32_bf16 v[96:99], v[132:135], v[220:223], 0
	v_mfma_f32_16x16x32_bf16 v[92:95], v[158:161], v[220:223], 0
	v_mfma_f32_16x16x32_bf16 v[80:83], v[132:135], v[228:231], 0
	v_mfma_f32_16x16x32_bf16 v[76:79], v[158:161], v[228:231], 0
	v_mfma_f32_16x16x32_bf16 v[128:131], v[136:139], v[208:211], v[128:131]
	v_mfma_f32_16x16x32_bf16 v[124:127], v[162:165], v[208:211], v[124:127]
	v_mfma_f32_16x16x32_bf16 v[112:115], v[136:139], v[216:219], v[112:115]
	v_mfma_f32_16x16x32_bf16 v[108:111], v[162:165], v[216:219], v[108:111]
	v_mfma_f32_16x16x32_bf16 v[96:99], v[136:139], v[224:227], v[96:99]
	v_mfma_f32_16x16x32_bf16 v[92:95], v[162:165], v[224:227], v[92:95]
	v_mfma_f32_16x16x32_bf16 v[80:83], v[136:139], v[232:235], v[80:83]
	v_mfma_f32_16x16x32_bf16 v[76:79], v[162:165], v[232:235], v[76:79]
	v_mfma_f32_16x16x32_bf16 v[120:123], v[188:191], v[204:207], 0
	v_mfma_f32_16x16x32_bf16 v[116:119], v[196:199], v[204:207], 0
	v_mfma_f32_16x16x32_bf16 v[104:107], v[188:191], v[212:215], 0
	v_mfma_f32_16x16x32_bf16 v[100:103], v[196:199], v[212:215], 0
	v_mfma_f32_16x16x32_bf16 v[88:91], v[188:191], v[220:223], 0
	v_mfma_f32_16x16x32_bf16 v[84:87], v[196:199], v[220:223], 0
	v_mfma_f32_16x16x32_bf16 v[72:75], v[188:191], v[228:231], 0
	v_mfma_f32_16x16x32_bf16 v[68:71], v[196:199], v[228:231], 0
	v_mfma_f32_16x16x32_bf16 v[120:123], v[192:195], v[208:211], v[120:123]
	v_mfma_f32_16x16x32_bf16 v[116:119], v[200:203], v[208:211], v[116:119]
	v_mfma_f32_16x16x32_bf16 v[104:107], v[192:195], v[216:219], v[104:107]
	v_mfma_f32_16x16x32_bf16 v[100:103], v[200:203], v[216:219], v[100:103]
	v_mfma_f32_16x16x32_bf16 v[88:91], v[192:195], v[224:227], v[88:91]
	v_mfma_f32_16x16x32_bf16 v[84:87], v[200:203], v[224:227], v[84:87]
	v_mfma_f32_16x16x32_bf16 v[72:75], v[192:195], v[232:235], v[72:75]
	v_mfma_f32_16x16x32_bf16 v[68:71], v[200:203], v[232:235], v[68:71]
	s_barrier
	s_setprio 0
	s_add_i32 s65, s65, s31
	s_mov_b32 m0, s65
	ds_read_b128 v[204:207], v187 offset:16384
	ds_read_b128 v[208:211], v187 offset:17408
	ds_read_b128 v[212:215], v187 offset:18432
	ds_read_b128 v[216:219], v187 offset:19456
	ds_read_b128 v[220:223], v187 offset:20480
	ds_read_b128 v[224:227], v187 offset:21504
	ds_read_b128 v[228:231], v187 offset:22528
	ds_read_b128 v[232:235], v187 offset:23552
	global_load_lds_dwordx4 v2, s[24:25]
	s_add_i32 m0, s65, 0x2000
	s_add_u32 s66, s24, 0x80000
	s_addc_u32 s67, s25, 0
	s_add_i32 s65, s76, s31
	global_load_lds_dwordx4 v152, s[24:25]
	s_mov_b32 m0, s65
	v_lshl_add_u64 v[240:241], s[26:27], 0, v[150:151]
	global_load_lds_dwordx4 v2, s[66:67]
	s_add_i32 m0, s65, 0x2000
	s_nop 0
	global_load_lds_dwordx4 v152, s[66:67]
	v_lshl_add_u64 v[238:239], s[26:27], 0, v[0:1]
	s_mov_b32 m0, s21
	s_nop 0
	global_load_lds_dwordx4 v[238:239], off
	s_mov_b32 m0, s34
	s_nop 0
	global_load_lds_dwordx4 v[240:241], off
	s_waitcnt vmcnt(8)
	s_waitcnt lgkmcnt(0)
	s_setprio 1
	s_barrier
; #define PG8_STAGE(bufoff, gbase, voff) do { _Pragma("unroll") for (int _i = 0; _i < 2; ++_i) \
;         __builtin_amdgcn_global_load_lds((const unsigned*)((const char*)(gbase) + (voff)[_i]), (PG8_LAS unsigned*)(lds + (bufoff) + ldsw + _i * 8192), 16, 0, 0); } while (0)
; #define PG8_LDA(dst, b, h) do { _Pragma("unroll") for (int m = 0; m < 4; ++m) _Pragma("unroll") for (int k = 0; k < 2; ++k) dst[m][k] = *(const PG8_LAS bf16x8*)(lds + PG8_SA(b, h) + aoff + m * 2048 + k * 1024); } while (0)
; #define PG8_LDB(dst, b, h) do { _Pragma("unroll") for (int n = 0; n < 2; ++n) _Pragma("unroll") for (int k = 0; k < 2; ++k) dst[n][k] = *(const PG8_LAS bf16x8*)(lds + PG8_SB(b, h) + boff + n * 2048 + k * 1024); } while (0)
; #define PG8_MMA(ai, bj, At, Bt) do { __builtin_amdgcn_s_setprio(1); _Pragma("unroll") for (int m = 0; m < 4; ++m) _Pragma("unroll") for (int n = 0; n < 2; ++n) _Pragma("unroll") for (int k = 0; k < 2; ++k) \
;         acc[ai][bj][m][n] = __builtin_amdgcn_mfma_f32_16x16x32_bf16(Bt[n][k], At[m][k], acc[ai][bj][m][n], 0, 0, 0); __builtin_amdgcn_s_setprio(0); } while (0)
; #define PG8_WAIT_V(n) asm volatile("s_waitcnt vmcnt(" #n ")" ::: "memory")
; #define PG8_WAIT_L(n) asm volatile("s_waitcnt lgkmcnt(" #n ")" ::: "memory")
; #define PG8_BAR __builtin_amdgcn_s_barrier()
; #define PG8_SCHED __builtin_amdgcn_sched_barrier(0)
; template <class Epi, class Sched, bool ALIGN_EPI = false, bool SP2 = false>
; __device__ __forceinline__ void gemm_phase(PG8_LAS unsigned char* lds, const Gemm g, const Sched& S, const Epi& E) {
;     ...
;             PG8_WAIT_V(8); PG8_WAIT_L(0); PG8_BAR; PG8_MMA(1, 0, At, B0); PG8_MMA(1, 1, At, B1); PG8_BAR; PG8_SCHED;
;             PG8_LDB(B0, 1, 0); PG8_LDB(B1, 1, 1); PG8_SCHED; PG8_LDA(At, 1, 0); PG8_STAGE(PG8_SA(0, 1), a2 + hstep, voffA);
;             PG8_WAIT_V(8); PG8_WAIT_L(0); PG8_BAR; PG8_MMA(0, 0, At, B0); PG8_MMA(0, 1, At, B1); PG8_BAR; PG8_SCHED;
	v_mfma_f32_16x16x32_bf16 v[64:67], v[132:135], v[204:207], 0
	v_mfma_f32_16x16x32_bf16 v[60:63], v[158:161], v[204:207], 0
	v_mfma_f32_16x16x32_bf16 v[48:51], v[132:135], v[212:215], 0
	v_mfma_f32_16x16x32_bf16 v[44:47], v[158:161], v[212:215], 0
	v_mfma_f32_16x16x32_bf16 v[32:35], v[132:135], v[220:223], 0
	v_mfma_f32_16x16x32_bf16 v[28:31], v[158:161], v[220:223], 0
	v_mfma_f32_16x16x32_bf16 v[16:19], v[132:135], v[228:231], 0
	v_mfma_f32_16x16x32_bf16 v[12:15], v[158:161], v[228:231], 0
	v_mfma_f32_16x16x32_bf16 v[64:67], v[136:139], v[208:211], v[64:67]
	v_mfma_f32_16x16x32_bf16 v[60:63], v[162:165], v[208:211], v[60:63]
	v_mfma_f32_16x16x32_bf16 v[48:51], v[136:139], v[216:219], v[48:51]
	v_mfma_f32_16x16x32_bf16 v[44:47], v[162:165], v[216:219], v[44:47]
	v_mfma_f32_16x16x32_bf16 v[32:35], v[136:139], v[224:227], v[32:35]
	v_mfma_f32_16x16x32_bf16 v[28:31], v[162:165], v[224:227], v[28:31]
	v_mfma_f32_16x16x32_bf16 v[16:19], v[136:139], v[232:235], v[16:19]
	v_mfma_f32_16x16x32_bf16 v[12:15], v[162:165], v[232:235], v[12:15]
	v_mfma_f32_16x16x32_bf16 v[56:59], v[188:191], v[204:207], 0
	v_mfma_f32_16x16x32_bf16 v[52:55], v[196:199], v[204:207], 0
	v_mfma_f32_16x16x32_bf16 v[40:43], v[188:191], v[212:215], 0
	v_mfma_f32_16x16x32_bf16 v[36:39], v[196:199], v[212:215], 0
	v_mfma_f32_16x16x32_bf16 v[24:27], v[188:191], v[220:223], 0
	v_mfma_f32_16x16x32_bf16 v[20:23], v[196:199], v[220:223], 0
	v_mfma_f32_16x16x32_bf16 v[8:11], v[188:191], v[228:231], 0
	v_mfma_f32_16x16x32_bf16 v[4:7], v[196:199], v[228:231], 0
	v_mfma_f32_16x16x32_bf16 v[56:59], v[192:195], v[208:211], v[56:59]
	v_mfma_f32_16x16x32_bf16 v[52:55], v[200:203], v[208:211], v[52:55]
	v_mfma_f32_16x16x32_bf16 v[40:43], v[192:195], v[216:219], v[40:43]
	v_mfma_f32_16x16x32_bf16 v[36:39], v[200:203], v[216:219], v[36:39]
	v_mfma_f32_16x16x32_bf16 v[24:27], v[192:195], v[224:227], v[24:27]
	v_mfma_f32_16x16x32_bf16 v[20:23], v[200:203], v[224:227], v[20:23]
	v_mfma_f32_16x16x32_bf16 v[8:11], v[192:195], v[232:235], v[8:11]
	v_mfma_f32_16x16x32_bf16 v[4:7], v[200:203], v[232:235], v[4:7]
	s_barrier
	s_setprio 0
	s_add_i32 s65, 0, 0x18000
	s_add_i32 s66, 0, 0x1c000
	ds_read_b128 v[132:135], v242
	ds_read_b128 v[136:139], v242 offset:1024
	ds_read_b128 v[158:161], v242 offset:2048
	ds_read_b128 v[162:165], v242 offset:3072
	ds_read_b128 v[188:191], v243
	ds_read_b128 v[192:195], v243 offset:1024
	ds_read_b128 v[196:199], v243 offset:2048
	ds_read_b128 v[200:203], v243 offset:3072
	s_add_u32 s26, s26, 0x80000
	s_addc_u32 s27, s27, 0
	s_mov_b32 m0, s35
	ds_read_b128 v[204:207], v187 offset:32768
	ds_read_b128 v[208:211], v187 offset:33792
	ds_read_b128 v[212:215], v187 offset:34816
	ds_read_b128 v[216:219], v187 offset:35840
	ds_read_b128 v[220:223], v187 offset:36864
	ds_read_b128 v[224:227], v187 offset:37888
	ds_read_b128 v[228:231], v187 offset:38912
	ds_read_b128 v[232:235], v187 offset:39936
	global_load_lds_dwordx4 v0, s[26:27]
	s_mov_b32 m0, s42
	s_nop 0
	global_load_lds_dwordx4 v150, s[26:27]
	s_waitcnt vmcnt(8)
	s_waitcnt lgkmcnt(0)
	s_setprio 1
	s_barrier
	v_mfma_f32_16x16x32_bf16 v[128:131], v[132:135], v[204:207], v[128:131]
	v_mfma_f32_16x16x32_bf16 v[124:127], v[158:161], v[204:207], v[124:127]
	v_mfma_f32_16x16x32_bf16 v[112:115], v[132:135], v[212:215], v[112:115]
	v_mfma_f32_16x16x32_bf16 v[108:111], v[158:161], v[212:215], v[108:111]
	v_mfma_f32_16x16x32_bf16 v[96:99], v[132:135], v[220:223], v[96:99]
	v_mfma_f32_16x16x32_bf16 v[92:95], v[158:161], v[220:223], v[92:95]
	v_mfma_f32_16x16x32_bf16 v[80:83], v[132:135], v[228:231], v[80:83]
	v_mfma_f32_16x16x32_bf16 v[76:79], v[158:161], v[228:231], v[76:79]
	v_mfma_f32_16x16x32_bf16 v[128:131], v[136:139], v[208:211], v[128:131]
	v_mfma_f32_16x16x32_bf16 v[124:127], v[162:165], v[208:211], v[124:127]
	v_mfma_f32_16x16x32_bf16 v[112:115], v[136:139], v[216:219], v[112:115]
	v_mfma_f32_16x16x32_bf16 v[108:111], v[162:165], v[216:219], v[108:111]
	v_mfma_f32_16x16x32_bf16 v[96:99], v[136:139], v[224:227], v[96:99]
	v_mfma_f32_16x16x32_bf16 v[92:95], v[162:165], v[224:227], v[92:95]
	v_mfma_f32_16x16x32_bf16 v[80:83], v[136:139], v[232:235], v[80:83]
	v_mfma_f32_16x16x32_bf16 v[76:79], v[162:165], v[232:235], v[76:79]
	v_mfma_f32_16x16x32_bf16 v[120:123], v[188:191], v[204:207], v[120:123]
	v_mfma_f32_16x16x32_bf16 v[116:119], v[196:199], v[204:207], v[116:119]
	v_mfma_f32_16x16x32_bf16 v[104:107], v[188:191], v[212:215], v[104:107]
	v_mfma_f32_16x16x32_bf16 v[100:103], v[196:199], v[212:215], v[100:103]
	v_mfma_f32_16x16x32_bf16 v[88:91], v[188:191], v[220:223], v[88:91]
	v_mfma_f32_16x16x32_bf16 v[84:87], v[196:199], v[220:223], v[84:87]
	v_mfma_f32_16x16x32_bf16 v[72:75], v[188:191], v[228:231], v[72:75]
	v_mfma_f32_16x16x32_bf16 v[68:71], v[196:199], v[228:231], v[68:71]
	v_mfma_f32_16x16x32_bf16 v[120:123], v[192:195], v[208:211], v[120:123]
	v_mfma_f32_16x16x32_bf16 v[116:119], v[200:203], v[208:211], v[116:119]
	v_mfma_f32_16x16x32_bf16 v[104:107], v[192:195], v[216:219], v[104:107]
	v_mfma_f32_16x16x32_bf16 v[100:103], v[200:203], v[216:219], v[100:103]
	v_mfma_f32_16x16x32_bf16 v[88:91], v[192:195], v[224:227], v[88:91]
	v_mfma_f32_16x16x32_bf16 v[84:87], v[200:203], v[224:227], v[84:87]
	v_mfma_f32_16x16x32_bf16 v[72:75], v[192:195], v[232:235], v[72:75]
	v_mfma_f32_16x16x32_bf16 v[68:71], v[200:203], v[232:235], v[68:71]
	s_barrier
; #define PG8_STAGE(bufoff, gbase, voff) do { _Pragma("unroll") for (int _i = 0; _i < 2; ++_i) \
;         __builtin_amdgcn_global_load_lds((const unsigned*)((const char*)(gbase) + (voff)[_i]), (PG8_LAS unsigned*)(lds + (bufoff) + ldsw + _i * 8192), 16, 0, 0); } while (0)
; #define PG8_LDA(dst, b, h) do { _Pragma("unroll") for (int m = 0; m < 4; ++m) _Pragma("unroll") for (int k = 0; k < 2; ++k) dst[m][k] = *(const PG8_LAS bf16x8*)(lds + PG8_SA(b, h) + aoff + m * 2048 + k * 1024); } while (0)
; #define PG8_LDB(dst, b, h) do { _Pragma("unroll") for (int n = 0; n < 2; ++n) _Pragma("unroll") for (int k = 0; k < 2; ++k) dst[n][k] = *(const PG8_LAS bf16x8*)(lds + PG8_SB(b, h) + boff + n * 2048 + k * 1024); } while (0)
; #define PG8_MMA(ai, bj, At, Bt) do { __builtin_amdgcn_s_setprio(1); _Pragma("unroll") for (int m = 0; m < 4; ++m) _Pragma("unroll") for (int n = 0; n < 2; ++n) _Pragma("unroll") for (int k = 0; k < 2; ++k) \
;         acc[ai][bj][m][n] = __builtin_amdgcn_mfma_f32_16x16x32_bf16(Bt[n][k], At[m][k], acc[ai][bj][m][n], 0, 0, 0); __builtin_amdgcn_s_setprio(0); } while (0)
; #define PG8_WAIT_V(n) asm volatile("s_waitcnt vmcnt(" #n ")" ::: "memory")
; #define PG8_WAIT_L(n) asm volatile("s_waitcnt lgkmcnt(" #n ")" ::: "memory")
; template <class Epi, class Sched, bool ALIGN_EPI = false, bool SP2 = false>
; __device__ __forceinline__ void gemm_phase(PG8_LAS unsigned char* lds, const Gemm g, const Sched& S, const Epi& E) {
;     ...
;             const bool last = (t == nt - 2);
;             const char* a1 = cA + (size_t)(t + 1) * kstep;
;             const char* a2 = last ? nA : cA + (size_t)(t + 2) * kstep; const char* b2 = last ? nB : cB + (size_t)(t + 2) * kstep;
;             const char* a3 = a2 + kstep; const char* b3 = b2 + kstep;
;             if (last && has_next) S.a_ready(nxt);
;             if constexpr (SP2) {
;             PG8_LDB(B0, 0, 0); PG8_LDB(B1, 0, 1); PG8_SCHED; PG8_LDA(At, 0, 0); PG8_STAGE(PG8_SA(1, 1), a1 + hstep, voffA);
;             PG8_WAIT_V(8); PG8_WAIT_L(0); PG8_BAR; PG8_MMA(0, 0, At, B0); PG8_MMA(0, 1, At, B1); PG8_BAR; PG8_SCHED;
;     ...
;             PG8_LDA(At, 1, 1); PG8_STAGE(PG8_SB(1, 0), b3, voffB); PG8_STAGE(PG8_SB(1, 1), b3 + hstep, voffB); PG8_STAGE(PG8_SA(1, 0), a3, voffA);
;             PG8_WAIT_V(8); PG8_WAIT_L(0); PG8_BAR; PG8_MMA(1, 0, At, B0); PG8_MMA(1, 1, At, B1); PG8_BAR; PG8_SCHED;
	s_setprio 0
	s_add_i32 s26, s65, s31
	s_mov_b32 m0, s26
	ds_read_b128 v[204:207], v187 offset:49152
	ds_read_b128 v[208:211], v187 offset:50176
	ds_read_b128 v[212:215], v187 offset:51200
	ds_read_b128 v[216:219], v187 offset:52224
	ds_read_b128 v[220:223], v187 offset:53248
	ds_read_b128 v[224:227], v187 offset:54272
	ds_read_b128 v[228:231], v187 offset:55296
	ds_read_b128 v[232:235], v187 offset:56320
	s_add_u32 vcc_lo, s24, 0x80
	s_addc_u32 vcc_hi, s25, 0
	global_load_lds_dwordx4 v2, vcc
	s_add_i32 m0, s26, 0x2000
	s_add_u32 s24, s24, 0x80080
	s_addc_u32 s25, s25, 0
	s_add_i32 s26, s66, s31
	s_add_u32 vcc_lo, s24, 0xfff80000
	s_addc_u32 vcc_hi, s25, -1
	global_load_lds_dwordx4 v152, vcc
	s_mov_b32 m0, s26
	s_nop 0
	global_load_lds_dwordx4 v2, s[24:25]
	s_add_i32 m0, s26, 0x2000
	s_nop 0
	global_load_lds_dwordx4 v152, s[24:25]
	v_lshl_add_u64 v[166:167], v[238:239], 0, s[36:37]
	s_mov_b32 m0, s44
	s_nop 0
	global_load_lds_dwordx4 v[166:167], off
	v_lshl_add_u64 v[166:167], v[240:241], 0, s[36:37]
	s_mov_b32 m0, s45
	s_nop 0
	global_load_lds_dwordx4 v[166:167], off
	s_waitcnt vmcnt(8)
	s_waitcnt lgkmcnt(0)
	s_setprio 1
	s_barrier
	v_mfma_f32_16x16x32_bf16 v[64:67], v[132:135], v[204:207], v[64:67]
	v_mfma_f32_16x16x32_bf16 v[60:63], v[158:161], v[204:207], v[60:63]
	v_mfma_f32_16x16x32_bf16 v[48:51], v[132:135], v[212:215], v[48:51]
	v_mfma_f32_16x16x32_bf16 v[44:47], v[158:161], v[212:215], v[44:47]
	v_mfma_f32_16x16x32_bf16 v[32:35], v[132:135], v[220:223], v[32:35]
	v_mfma_f32_16x16x32_bf16 v[28:31], v[158:161], v[220:223], v[28:31]
	v_mfma_f32_16x16x32_bf16 v[16:19], v[132:135], v[228:231], v[16:19]
	v_mfma_f32_16x16x32_bf16 v[12:15], v[158:161], v[228:231], v[12:15]
	v_mfma_f32_16x16x32_bf16 v[64:67], v[136:139], v[208:211], v[64:67]
	v_mfma_f32_16x16x32_bf16 v[60:63], v[162:165], v[208:211], v[60:63]
	v_mfma_f32_16x16x32_bf16 v[48:51], v[136:139], v[216:219], v[48:51]
	v_mfma_f32_16x16x32_bf16 v[44:47], v[162:165], v[216:219], v[44:47]
	v_mfma_f32_16x16x32_bf16 v[32:35], v[136:139], v[224:227], v[32:35]
	v_mfma_f32_16x16x32_bf16 v[28:31], v[162:165], v[224:227], v[28:31]
	v_mfma_f32_16x16x32_bf16 v[16:19], v[136:139], v[232:235], v[16:19]
	v_mfma_f32_16x16x32_bf16 v[12:15], v[162:165], v[232:235], v[12:15]
	v_mfma_f32_16x16x32_bf16 v[56:59], v[188:191], v[204:207], v[56:59]
	v_mfma_f32_16x16x32_bf16 v[52:55], v[196:199], v[204:207], v[52:55]
	v_mfma_f32_16x16x32_bf16 v[40:43], v[188:191], v[212:215], v[40:43]
	v_mfma_f32_16x16x32_bf16 v[36:39], v[196:199], v[212:215], v[36:39]
	v_mfma_f32_16x16x32_bf16 v[24:27], v[188:191], v[220:223], v[24:27]
	v_mfma_f32_16x16x32_bf16 v[20:23], v[196:199], v[220:223], v[20:23]
	v_mfma_f32_16x16x32_bf16 v[8:11], v[188:191], v[228:231], v[8:11]
	v_mfma_f32_16x16x32_bf16 v[4:7], v[196:199], v[228:231], v[4:7]
	v_mfma_f32_16x16x32_bf16 v[56:59], v[192:195], v[208:211], v[56:59]
	v_mfma_f32_16x16x32_bf16 v[52:55], v[200:203], v[208:211], v[52:55]
	v_mfma_f32_16x16x32_bf16 v[40:43], v[192:195], v[216:219], v[40:43]
	v_mfma_f32_16x16x32_bf16 v[36:39], v[200:203], v[216:219], v[36:39]
	v_mfma_f32_16x16x32_bf16 v[24:27], v[192:195], v[224:227], v[24:27]
	v_mfma_f32_16x16x32_bf16 v[20:23], v[200:203], v[224:227], v[20:23]
	v_mfma_f32_16x16x32_bf16 v[8:11], v[192:195], v[232:235], v[8:11]
	v_mfma_f32_16x16x32_bf16 v[4:7], v[200:203], v[232:235], v[4:7]
	s_barrier
	s_setprio 0
	s_add_i32 s64, s64, 2
	s_add_u32 s22, s22, 0x100
	s_addc_u32 s23, s23, 0
	s_add_u32 s57, s57, 0x100
	s_addc_u32 s63, s63, 0
	s_cmp_gt_u32 s64, 29
.LBB0_483:
	s_add_u32 s24, s22, 0xfff80080
	s_addc_u32 s25, s23, -1
	s_add_i32 s65, 0, 0x10000
	s_cmp_eq_u32 s64, 28
	s_cselect_b32 s27, s13, s25
	s_cselect_b32 s26, s19, s24
	s_cselect_b32 s25, s11, s63
	s_cselect_b32 s24, s56, s57
	s_add_i32 s76, 0, 0x14000
	ds_read_b128 v[132:135], v236
	ds_read_b128 v[136:139], v236 offset:1024
	ds_read_b128 v[158:161], v236 offset:2048
	ds_read_b128 v[162:165], v236 offset:3072
	ds_read_b128 v[188:191], v237
	ds_read_b128 v[192:195], v237 offset:1024
	ds_read_b128 v[196:199], v237 offset:2048
	ds_read_b128 v[200:203], v237 offset:3072
	s_add_i32 m0, s21, 0xc000
	ds_read_b128 v[204:207], v187
	ds_read_b128 v[208:211], v187 offset:1024
	ds_read_b128 v[212:215], v187 offset:2048
	ds_read_b128 v[216:219], v187 offset:3072
	ds_read_b128 v[220:223], v187 offset:4096
	ds_read_b128 v[224:227], v187 offset:5120
	ds_read_b128 v[228:231], v187 offset:6144
	ds_read_b128 v[232:235], v187 offset:7168
	global_load_lds_dwordx4 v154, s[22:23]
	s_add_i32 m0, s21, 0xe000
	s_nop 0
	global_load_lds_dwordx4 v156, s[22:23]
	s_waitcnt vmcnt(8)
	s_waitcnt lgkmcnt(0)
	s_setprio 1
	s_barrier
; #define PG8_STAGE(bufoff, gbase, voff) do { _Pragma("unroll") for (int _i = 0; _i < 2; ++_i) \
;         __builtin_amdgcn_global_load_lds((const unsigned*)((const char*)(gbase) + (voff)[_i]), (PG8_LAS unsigned*)(lds + (bufoff) + ldsw + _i * 8192), 16, 0, 0); } while (0)
; #define PG8_LDA(dst, b, h) do { _Pragma("unroll") for (int m = 0; m < 4; ++m) _Pragma("unroll") for (int k = 0; k < 2; ++k) dst[m][k] = *(const PG8_LAS bf16x8*)(lds + PG8_SA(b, h) + aoff + m * 2048 + k * 1024); } while (0)
; #define PG8_MMA(ai, bj, At, Bt) do { __builtin_amdgcn_s_setprio(1); _Pragma("unroll") for (int m = 0; m < 4; ++m) _Pragma("unroll") for (int n = 0; n < 2; ++n) _Pragma("unroll") for (int k = 0; k < 2; ++k) \
;         acc[ai][bj][m][n] = __builtin_amdgcn_mfma_f32_16x16x32_bf16(Bt[n][k], At[m][k], acc[ai][bj][m][n], 0, 0, 0); __builtin_amdgcn_s_setprio(0); } while (0)
; #define PG8_WAIT_V(n) asm volatile("s_waitcnt vmcnt(" #n ")" ::: "memory")
; #define PG8_WAIT_L(n) asm volatile("s_waitcnt lgkmcnt(" #n ")" ::: "memory")
; #define PG8_BAR __builtin_amdgcn_s_barrier()
; #define PG8_SCHED __builtin_amdgcn_sched_barrier(0)
; template <class Epi, class Sched, bool ALIGN_EPI = false, bool SP2 = false>
; __device__ __forceinline__ void gemm_phase(PG8_LAS unsigned char* lds, const Gemm g, const Sched& S, const Epi& E) {
;     ...
;             PG8_WAIT_V(8); PG8_WAIT_L(0); PG8_BAR; PG8_MMA(0, 0, At, B0); PG8_MMA(0, 1, At, B1); PG8_BAR; PG8_SCHED;
;             PG8_LDA(At, 0, 1); PG8_STAGE(PG8_SB(0, 0), b2, voffB); PG8_STAGE(PG8_SB(0, 1), b2 + hstep, voffB); PG8_STAGE(PG8_SA(0, 0), a2, voffA);
;             PG8_WAIT_V(8); PG8_WAIT_L(0); PG8_BAR; PG8_MMA(1, 0, At, B0); PG8_MMA(1, 1, At, B1); PG8_BAR; PG8_SCHED;
	v_mfma_f32_16x16x32_bf16 v[128:131], v[132:135], v[204:207], v[128:131]
	v_mfma_f32_16x16x32_bf16 v[124:127], v[158:161], v[204:207], v[124:127]
	v_mfma_f32_16x16x32_bf16 v[112:115], v[132:135], v[212:215], v[112:115]
	v_mfma_f32_16x16x32_bf16 v[108:111], v[158:161], v[212:215], v[108:111]
	v_mfma_f32_16x16x32_bf16 v[96:99], v[132:135], v[220:223], v[96:99]
	v_mfma_f32_16x16x32_bf16 v[92:95], v[158:161], v[220:223], v[92:95]
	v_mfma_f32_16x16x32_bf16 v[80:83], v[132:135], v[228:231], v[80:83]
	v_mfma_f32_16x16x32_bf16 v[76:79], v[158:161], v[228:231], v[76:79]
	v_mfma_f32_16x16x32_bf16 v[128:131], v[136:139], v[208:211], v[128:131]
	v_mfma_f32_16x16x32_bf16 v[124:127], v[162:165], v[208:211], v[124:127]
	v_mfma_f32_16x16x32_bf16 v[112:115], v[136:139], v[216:219], v[112:115]
	v_mfma_f32_16x16x32_bf16 v[108:111], v[162:165], v[216:219], v[108:111]
	v_mfma_f32_16x16x32_bf16 v[96:99], v[136:139], v[224:227], v[96:99]
	v_mfma_f32_16x16x32_bf16 v[92:95], v[162:165], v[224:227], v[92:95]
	v_mfma_f32_16x16x32_bf16 v[80:83], v[136:139], v[232:235], v[80:83]
	v_mfma_f32_16x16x32_bf16 v[76:79], v[162:165], v[232:235], v[76:79]
	v_mfma_f32_16x16x32_bf16 v[120:123], v[188:191], v[204:207], v[120:123]
	v_mfma_f32_16x16x32_bf16 v[116:119], v[196:199], v[204:207], v[116:119]
	v_mfma_f32_16x16x32_bf16 v[104:107], v[188:191], v[212:215], v[104:107]
	v_mfma_f32_16x16x32_bf16 v[100:103], v[196:199], v[212:215], v[100:103]
	v_mfma_f32_16x16x32_bf16 v[88:91], v[188:191], v[220:223], v[88:91]
	v_mfma_f32_16x16x32_bf16 v[84:87], v[196:199], v[220:223], v[84:87]
	v_mfma_f32_16x16x32_bf16 v[72:75], v[188:191], v[228:231], v[72:75]
	v_mfma_f32_16x16x32_bf16 v[68:71], v[196:199], v[228:231], v[68:71]
	v_mfma_f32_16x16x32_bf16 v[120:123], v[192:195], v[208:211], v[120:123]
	v_mfma_f32_16x16x32_bf16 v[116:119], v[200:203], v[208:211], v[116:119]
	v_mfma_f32_16x16x32_bf16 v[104:107], v[192:195], v[216:219], v[104:107]
	v_mfma_f32_16x16x32_bf16 v[100:103], v[200:203], v[216:219], v[100:103]
	v_mfma_f32_16x16x32_bf16 v[88:91], v[192:195], v[224:227], v[88:91]
	v_mfma_f32_16x16x32_bf16 v[84:87], v[200:203], v[224:227], v[84:87]
	v_mfma_f32_16x16x32_bf16 v[72:75], v[192:195], v[232:235], v[72:75]
	v_mfma_f32_16x16x32_bf16 v[68:71], v[200:203], v[232:235], v[68:71]
	s_barrier
	s_setprio 0
	s_add_i32 s65, s65, s31
	s_mov_b32 m0, s65
	ds_read_b128 v[204:207], v187 offset:16384
	ds_read_b128 v[208:211], v187 offset:17408
	ds_read_b128 v[212:215], v187 offset:18432
	ds_read_b128 v[216:219], v187 offset:19456
	ds_read_b128 v[220:223], v187 offset:20480
	ds_read_b128 v[224:227], v187 offset:21504
	ds_read_b128 v[228:231], v187 offset:22528
	ds_read_b128 v[232:235], v187 offset:23552
	global_load_lds_dwordx4 v2, s[24:25]
	s_add_i32 m0, s65, 0x2000
	s_add_u32 s66, s24, 0x80000
	s_addc_u32 s67, s25, 0
	s_add_i32 s65, s76, s31
	global_load_lds_dwordx4 v152, s[24:25]
	s_mov_b32 m0, s65
	v_lshl_add_u64 v[240:241], s[26:27], 0, v[150:151]
	global_load_lds_dwordx4 v2, s[66:67]
	s_add_i32 m0, s65, 0x2000
	s_nop 0
	global_load_lds_dwordx4 v152, s[66:67]
	v_lshl_add_u64 v[238:239], s[26:27], 0, v[0:1]
	s_mov_b32 m0, s21
	s_nop 0
	global_load_lds_dwordx4 v[238:239], off
	s_mov_b32 m0, s34
	s_nop 0
	global_load_lds_dwordx4 v[240:241], off
	s_waitcnt vmcnt(8)
	s_waitcnt lgkmcnt(0)
	s_setprio 1
	s_barrier
	v_mfma_f32_16x16x32_bf16 v[64:67], v[132:135], v[204:207], v[64:67]
	v_mfma_f32_16x16x32_bf16 v[60:63], v[158:161], v[204:207], v[60:63]
	v_mfma_f32_16x16x32_bf16 v[48:51], v[132:135], v[212:215], v[48:51]
	v_mfma_f32_16x16x32_bf16 v[44:47], v[158:161], v[212:215], v[44:47]
	v_mfma_f32_16x16x32_bf16 v[32:35], v[132:135], v[220:223], v[32:35]
	v_mfma_f32_16x16x32_bf16 v[28:31], v[158:161], v[220:223], v[28:31]
	v_mfma_f32_16x16x32_bf16 v[16:19], v[132:135], v[228:231], v[16:19]
	v_mfma_f32_16x16x32_bf16 v[12:15], v[158:161], v[228:231], v[12:15]
	v_mfma_f32_16x16x32_bf16 v[64:67], v[136:139], v[208:211], v[64:67]
	v_mfma_f32_16x16x32_bf16 v[60:63], v[162:165], v[208:211], v[60:63]
	v_mfma_f32_16x16x32_bf16 v[48:51], v[136:139], v[216:219], v[48:51]
	v_mfma_f32_16x16x32_bf16 v[44:47], v[162:165], v[216:219], v[44:47]
	v_mfma_f32_16x16x32_bf16 v[32:35], v[136:139], v[224:227], v[32:35]
	v_mfma_f32_16x16x32_bf16 v[28:31], v[162:165], v[224:227], v[28:31]
	v_mfma_f32_16x16x32_bf16 v[16:19], v[136:139], v[232:235], v[16:19]
	v_mfma_f32_16x16x32_bf16 v[12:15], v[162:165], v[232:235], v[12:15]
	v_mfma_f32_16x16x32_bf16 v[56:59], v[188:191], v[204:207], v[56:59]
	v_mfma_f32_16x16x32_bf16 v[52:55], v[196:199], v[204:207], v[52:55]
	v_mfma_f32_16x16x32_bf16 v[40:43], v[188:191], v[212:215], v[40:43]
	v_mfma_f32_16x16x32_bf16 v[36:39], v[196:199], v[212:215], v[36:39]
	v_mfma_f32_16x16x32_bf16 v[24:27], v[188:191], v[220:223], v[24:27]
	v_mfma_f32_16x16x32_bf16 v[20:23], v[196:199], v[220:223], v[20:23]
	v_mfma_f32_16x16x32_bf16 v[8:11], v[188:191], v[228:231], v[8:11]
	v_mfma_f32_16x16x32_bf16 v[4:7], v[196:199], v[228:231], v[4:7]
	v_mfma_f32_16x16x32_bf16 v[56:59], v[192:195], v[208:211], v[56:59]
	v_mfma_f32_16x16x32_bf16 v[52:55], v[200:203], v[208:211], v[52:55]
	v_mfma_f32_16x16x32_bf16 v[40:43], v[192:195], v[216:219], v[40:43]
	v_mfma_f32_16x16x32_bf16 v[36:39], v[200:203], v[216:219], v[36:39]
	v_mfma_f32_16x16x32_bf16 v[24:27], v[192:195], v[224:227], v[24:27]
	v_mfma_f32_16x16x32_bf16 v[20:23], v[200:203], v[224:227], v[20:23]
	v_mfma_f32_16x16x32_bf16 v[8:11], v[192:195], v[232:235], v[8:11]
	v_mfma_f32_16x16x32_bf16 v[4:7], v[200:203], v[232:235], v[4:7]
	s_barrier
; #define PG8_STAGE(bufoff, gbase, voff) do { _Pragma("unroll") for (int _i = 0; _i < 2; ++_i) \
;         __builtin_amdgcn_global_load_lds((const unsigned*)((const char*)(gbase) + (voff)[_i]), (PG8_LAS unsigned*)(lds + (bufoff) + ldsw + _i * 8192), 16, 0, 0); } while (0)
; #define PG8_LDA(dst, b, h) do { _Pragma("unroll") for (int m = 0; m < 4; ++m) _Pragma("unroll") for (int k = 0; k < 2; ++k) dst[m][k] = *(const PG8_LAS bf16x8*)(lds + PG8_SA(b, h) + aoff + m * 2048 + k * 1024); } while (0)
; #define PG8_LDB(dst, b, h) do { _Pragma("unroll") for (int n = 0; n < 2; ++n) _Pragma("unroll") for (int k = 0; k < 2; ++k) dst[n][k] = *(const PG8_LAS bf16x8*)(lds + PG8_SB(b, h) + boff + n * 2048 + k * 1024); } while (0)
; #define PG8_MMA(ai, bj, At, Bt) do { __builtin_amdgcn_s_setprio(1); _Pragma("unroll") for (int m = 0; m < 4; ++m) _Pragma("unroll") for (int n = 0; n < 2; ++n) _Pragma("unroll") for (int k = 0; k < 2; ++k) \
;         acc[ai][bj][m][n] = __builtin_amdgcn_mfma_f32_16x16x32_bf16(Bt[n][k], At[m][k], acc[ai][bj][m][n], 0, 0, 0); __builtin_amdgcn_s_setprio(0); } while (0)
; #define PG8_WAIT_V(n) asm volatile("s_waitcnt vmcnt(" #n ")" ::: "memory")
; #define PG8_WAIT_L(n) asm volatile("s_waitcnt lgkmcnt(" #n ")" ::: "memory")
; #define PG8_BAR __builtin_amdgcn_s_barrier()
; #define PG8_SCHED __builtin_amdgcn_sched_barrier(0)
; template <class Epi, class Sched, bool ALIGN_EPI = false, bool SP2 = false>
; __device__ __forceinline__ void gemm_phase(PG8_LAS unsigned char* lds, const Gemm g, const Sched& S, const Epi& E) {
;     ...
;             PG8_LDB(B0, 1, 0); PG8_LDB(B1, 1, 1); PG8_SCHED; PG8_LDA(At, 1, 0); PG8_STAGE(PG8_SA(0, 1), a2 + hstep, voffA);
;             PG8_WAIT_V(8); PG8_WAIT_L(0); PG8_BAR; PG8_MMA(0, 0, At, B0); PG8_MMA(0, 1, At, B1); PG8_BAR; PG8_SCHED;
;             PG8_LDA(At, 1, 1); PG8_STAGE(PG8_SB(1, 0), b3, voffB); PG8_STAGE(PG8_SB(1, 1), b3 + hstep, voffB); PG8_STAGE(PG8_SA(1, 0), a3, voffA);
;             PG8_WAIT_V(8); PG8_WAIT_L(0); PG8_BAR; PG8_MMA(1, 0, At, B0); PG8_MMA(1, 1, At, B1); PG8_BAR; PG8_SCHED;
;     ...
;         if constexpr (ALIGN_EPI) { if (wr == 0) PG8_BAR; }
	s_setprio 0
	s_add_i32 s65, 0, 0x18000
	s_add_i32 s66, 0, 0x1c000
	ds_read_b128 v[132:135], v242
	ds_read_b128 v[136:139], v242 offset:1024
	ds_read_b128 v[158:161], v242 offset:2048
	ds_read_b128 v[162:165], v242 offset:3072
	ds_read_b128 v[188:191], v243
	ds_read_b128 v[192:195], v243 offset:1024
	ds_read_b128 v[196:199], v243 offset:2048
	ds_read_b128 v[200:203], v243 offset:3072
	s_add_u32 s26, s26, 0x80000
	s_addc_u32 s27, s27, 0
	s_mov_b32 m0, s35
	ds_read_b128 v[204:207], v187 offset:32768
	ds_read_b128 v[208:211], v187 offset:33792
	ds_read_b128 v[212:215], v187 offset:34816
	ds_read_b128 v[216:219], v187 offset:35840
	ds_read_b128 v[220:223], v187 offset:36864
	ds_read_b128 v[224:227], v187 offset:37888
	ds_read_b128 v[228:231], v187 offset:38912
	ds_read_b128 v[232:235], v187 offset:39936
	global_load_lds_dwordx4 v0, s[26:27]
	s_mov_b32 m0, s42
	s_nop 0
	global_load_lds_dwordx4 v150, s[26:27]
	s_waitcnt vmcnt(8)
	s_waitcnt lgkmcnt(0)
	s_setprio 1
	s_barrier
	v_mfma_f32_16x16x32_bf16 v[128:131], v[132:135], v[204:207], v[128:131]
	v_mfma_f32_16x16x32_bf16 v[124:127], v[158:161], v[204:207], v[124:127]
	v_mfma_f32_16x16x32_bf16 v[112:115], v[132:135], v[212:215], v[112:115]
	v_mfma_f32_16x16x32_bf16 v[108:111], v[158:161], v[212:215], v[108:111]
	v_mfma_f32_16x16x32_bf16 v[96:99], v[132:135], v[220:223], v[96:99]
	v_mfma_f32_16x16x32_bf16 v[92:95], v[158:161], v[220:223], v[92:95]
	v_mfma_f32_16x16x32_bf16 v[80:83], v[132:135], v[228:231], v[80:83]
	v_mfma_f32_16x16x32_bf16 v[76:79], v[158:161], v[228:231], v[76:79]
	v_mfma_f32_16x16x32_bf16 v[128:131], v[136:139], v[208:211], v[128:131]
	v_mfma_f32_16x16x32_bf16 v[124:127], v[162:165], v[208:211], v[124:127]
	v_mfma_f32_16x16x32_bf16 v[112:115], v[136:139], v[216:219], v[112:115]
	v_mfma_f32_16x16x32_bf16 v[108:111], v[162:165], v[216:219], v[108:111]
	v_mfma_f32_16x16x32_bf16 v[96:99], v[136:139], v[224:227], v[96:99]
	v_mfma_f32_16x16x32_bf16 v[92:95], v[162:165], v[224:227], v[92:95]
	v_mfma_f32_16x16x32_bf16 v[80:83], v[136:139], v[232:235], v[80:83]
	v_mfma_f32_16x16x32_bf16 v[76:79], v[162:165], v[232:235], v[76:79]
	v_mfma_f32_16x16x32_bf16 v[120:123], v[188:191], v[204:207], v[120:123]
	v_mfma_f32_16x16x32_bf16 v[116:119], v[196:199], v[204:207], v[116:119]
	v_mfma_f32_16x16x32_bf16 v[104:107], v[188:191], v[212:215], v[104:107]
	v_mfma_f32_16x16x32_bf16 v[100:103], v[196:199], v[212:215], v[100:103]
	v_mfma_f32_16x16x32_bf16 v[88:91], v[188:191], v[220:223], v[88:91]
	v_mfma_f32_16x16x32_bf16 v[84:87], v[196:199], v[220:223], v[84:87]
	v_mfma_f32_16x16x32_bf16 v[72:75], v[188:191], v[228:231], v[72:75]
	v_mfma_f32_16x16x32_bf16 v[68:71], v[196:199], v[228:231], v[68:71]
	v_mfma_f32_16x16x32_bf16 v[120:123], v[192:195], v[208:211], v[120:123]
	v_mfma_f32_16x16x32_bf16 v[116:119], v[200:203], v[208:211], v[116:119]
	v_mfma_f32_16x16x32_bf16 v[104:107], v[192:195], v[216:219], v[104:107]
	v_mfma_f32_16x16x32_bf16 v[100:103], v[200:203], v[216:219], v[100:103]
	v_mfma_f32_16x16x32_bf16 v[88:91], v[192:195], v[224:227], v[88:91]
	v_mfma_f32_16x16x32_bf16 v[84:87], v[200:203], v[224:227], v[84:87]
	v_mfma_f32_16x16x32_bf16 v[72:75], v[192:195], v[232:235], v[72:75]
	v_mfma_f32_16x16x32_bf16 v[68:71], v[200:203], v[232:235], v[68:71]
	s_barrier
	s_setprio 0
	s_add_i32 s26, s65, s31
	s_mov_b32 m0, s26
	ds_read_b128 v[204:207], v187 offset:49152
	ds_read_b128 v[208:211], v187 offset:50176
	ds_read_b128 v[212:215], v187 offset:51200
	ds_read_b128 v[216:219], v187 offset:52224
	ds_read_b128 v[220:223], v187 offset:53248
	ds_read_b128 v[224:227], v187 offset:54272
	ds_read_b128 v[228:231], v187 offset:55296
	ds_read_b128 v[232:235], v187 offset:56320
	s_add_u32 vcc_lo, s24, 0x80
	s_addc_u32 vcc_hi, s25, 0
	global_load_lds_dwordx4 v2, vcc
	s_add_i32 m0, s26, 0x2000
	s_add_u32 s24, s24, 0x80080
	s_addc_u32 s25, s25, 0
	s_add_i32 s26, s66, s31
	s_add_u32 vcc_lo, s24, 0xfff80000
	s_addc_u32 vcc_hi, s25, -1
	global_load_lds_dwordx4 v152, vcc
	s_mov_b32 m0, s26
	s_nop 0
	global_load_lds_dwordx4 v2, s[24:25]
	s_add_i32 m0, s26, 0x2000
	s_nop 0
	global_load_lds_dwordx4 v152, s[24:25]
	v_lshl_add_u64 v[166:167], v[238:239], 0, s[36:37]
	s_mov_b32 m0, s44
	s_nop 0
	global_load_lds_dwordx4 v[166:167], off
	v_lshl_add_u64 v[166:167], v[240:241], 0, s[36:37]
	s_mov_b32 m0, s45
	s_nop 0
	global_load_lds_dwordx4 v[166:167], off
	s_waitcnt vmcnt(8)
	s_waitcnt lgkmcnt(0)
	s_setprio 1
	s_barrier
	v_mfma_f32_16x16x32_bf16 v[64:67], v[132:135], v[204:207], v[64:67]
	v_mfma_f32_16x16x32_bf16 v[60:63], v[158:161], v[204:207], v[60:63]
	v_mfma_f32_16x16x32_bf16 v[48:51], v[132:135], v[212:215], v[48:51]
	v_mfma_f32_16x16x32_bf16 v[44:47], v[158:161], v[212:215], v[44:47]
	v_mfma_f32_16x16x32_bf16 v[32:35], v[132:135], v[220:223], v[32:35]
	v_mfma_f32_16x16x32_bf16 v[28:31], v[158:161], v[220:223], v[28:31]
	v_mfma_f32_16x16x32_bf16 v[16:19], v[132:135], v[228:231], v[16:19]
	v_mfma_f32_16x16x32_bf16 v[12:15], v[158:161], v[228:231], v[12:15]
	v_mfma_f32_16x16x32_bf16 v[64:67], v[136:139], v[208:211], v[64:67]
	v_mfma_f32_16x16x32_bf16 v[60:63], v[162:165], v[208:211], v[60:63]
	v_mfma_f32_16x16x32_bf16 v[48:51], v[136:139], v[216:219], v[48:51]
	v_mfma_f32_16x16x32_bf16 v[44:47], v[162:165], v[216:219], v[44:47]
	v_mfma_f32_16x16x32_bf16 v[32:35], v[136:139], v[224:227], v[32:35]
	v_mfma_f32_16x16x32_bf16 v[28:31], v[162:165], v[224:227], v[28:31]
	v_mfma_f32_16x16x32_bf16 v[16:19], v[136:139], v[232:235], v[16:19]
	v_mfma_f32_16x16x32_bf16 v[12:15], v[162:165], v[232:235], v[12:15]
	v_mfma_f32_16x16x32_bf16 v[56:59], v[188:191], v[204:207], v[56:59]
	v_mfma_f32_16x16x32_bf16 v[52:55], v[196:199], v[204:207], v[52:55]
	v_mfma_f32_16x16x32_bf16 v[40:43], v[188:191], v[212:215], v[40:43]
	v_mfma_f32_16x16x32_bf16 v[36:39], v[196:199], v[212:215], v[36:39]
	v_mfma_f32_16x16x32_bf16 v[24:27], v[188:191], v[220:223], v[24:27]
	v_mfma_f32_16x16x32_bf16 v[20:23], v[196:199], v[220:223], v[20:23]
	v_mfma_f32_16x16x32_bf16 v[8:11], v[188:191], v[228:231], v[8:11]
	v_mfma_f32_16x16x32_bf16 v[4:7], v[196:199], v[228:231], v[4:7]
	v_mfma_f32_16x16x32_bf16 v[56:59], v[192:195], v[208:211], v[56:59]
	v_mfma_f32_16x16x32_bf16 v[52:55], v[200:203], v[208:211], v[52:55]
	v_mfma_f32_16x16x32_bf16 v[40:43], v[192:195], v[216:219], v[40:43]
	v_mfma_f32_16x16x32_bf16 v[36:39], v[200:203], v[216:219], v[36:39]
	v_mfma_f32_16x16x32_bf16 v[24:27], v[192:195], v[224:227], v[24:27]
	v_mfma_f32_16x16x32_bf16 v[20:23], v[200:203], v[224:227], v[20:23]
	v_mfma_f32_16x16x32_bf16 v[8:11], v[192:195], v[232:235], v[8:11]
	v_mfma_f32_16x16x32_bf16 v[4:7], v[200:203], v[232:235], v[4:7]
	s_barrier
	s_setprio 0
	s_add_i32 s64, s64, 2
	s_add_u32 s22, s22, 0x100
	s_addc_u32 s23, s23, 0
	s_add_u32 s57, s57, 0x100
	s_addc_u32 s63, s63, 0
	s_cmp_gt_u32 s64, 29
	s_cbranch_scc0 .LBB0_483
	s_and_b64 vcc, exec, s[8:9]
	s_cbranch_vccz .LBB0_486
	s_barrier

; #define PG8_STAGE(bufoff, gbase, voff) do { _Pragma("unroll") for (int _i = 0; _i < 2; ++_i) \
;         __builtin_amdgcn_global_load_lds((const unsigned*)((const char*)(gbase) + (voff)[_i]), (PG8_LAS unsigned*)(lds + (bufoff) + ldsw + _i * 8192), 16, 0, 0); } while (0)
; #define PG8_LDA(dst, b, h) do { _Pragma("unroll") for (int m = 0; m < 4; ++m) _Pragma("unroll") for (int k = 0; k < 2; ++k) dst[m][k] = *(const PG8_LAS bf16x8*)(lds + PG8_SA(b, h) + aoff + m * 2048 + k * 1024); } while (0)
; #define PG8_LDB(dst, b, h) do { _Pragma("unroll") for (int n = 0; n < 2; ++n) _Pragma("unroll") for (int k = 0; k < 2; ++k) dst[n][k] = *(const PG8_LAS bf16x8*)(lds + PG8_SB(b, h) + boff + n * 2048 + k * 1024); } while (0)
; #define PG8_WAIT_V(n) asm volatile("s_waitcnt vmcnt(" #n ")" ::: "memory")
; #define PG8_WAIT_L(n) asm volatile("s_waitcnt lgkmcnt(" #n ")" ::: "memory")
; #define PG8_BAR __builtin_amdgcn_s_barrier()
; #define PG8_SCHED __builtin_amdgcn_sched_barrier(0)
; template <class Epi, class Sched, bool ALIGN_EPI = false, bool SP2 = false>
; __device__ __forceinline__ void gemm_phase(PG8_LAS unsigned char* lds, const Gemm g, const Sched& S, const Epi& E) {
;     ...
;         const bool has_next = S.next(ui + 1, nxt);
;         const char* nA = has_next ? (const char*)g.A + (size_t)nxt.pm * tstep : cA; const char* nB = has_next ? (const char*)g.Bt + (size_t)nxt.pn * tstep : cB;
;         for (int t = 0; t < nt; t += 2) {
;             const bool last = (t == nt - 2);
;             const char* a1 = cA + (size_t)(t + 1) * kstep;
;             const char* a2 = last ? nA : cA + (size_t)(t + 2) * kstep; const char* b2 = last ? nB : cB + (size_t)(t + 2) * kstep;
;             const char* a3 = a2 + kstep; const char* b3 = b2 + kstep;
;             if (last && has_next) S.a_ready(nxt);
;             if constexpr (SP2) {
;             PG8_LDB(B0, 0, 0); PG8_LDB(B1, 0, 1); PG8_SCHED; PG8_LDA(At, 0, 0); PG8_STAGE(PG8_SA(1, 1), a1 + hstep, voffA);
;             PG8_WAIT_V(8); PG8_WAIT_L(0); PG8_BAR; PG8_MMA(0, 0, At, B0); PG8_MMA(0, 1, At, B1); PG8_BAR; PG8_SCHED;
;             PG8_LDA(At, 0, 1); PG8_STAGE(PG8_SB(0, 0), b2, voffB); PG8_STAGE(PG8_SB(0, 1), b2 + hstep, voffB); PG8_STAGE(PG8_SA(0, 0), a2, voffA);
;             PG8_WAIT_V(8); PG8_WAIT_L(0); PG8_BAR; PG8_MMA(1, 0, At, B0); PG8_MMA(1, 1, At, B1); PG8_BAR; PG8_SCHED;
.LBB0_566:
	s_ashr_i32 s11, s10, 31
	s_lshl_b64 s[12:13], s[10:11], 20
	s_add_u32 s12, s46, s12
	s_addc_u32 s13, s47, s13
	s_and_b64 s[14:15], s[2:3], exec
	s_cselect_b32 s11, s13, s19
	s_cselect_b32 s45, s12, s18
	s_ashr_i32 s9, s8, 31
	s_lshl_b64 s[14:15], s[8:9], 20
	s_add_u32 s14, s25, s14
	s_addc_u32 s15, s26, s15
	s_and_b64 s[22:23], s[2:3], exec
	s_cselect_b32 s9, s15, s21
	s_cselect_b32 s50, s14, s20
	s_add_u32 s18, s18, 0x80080
	s_addc_u32 s19, s19, 0
	s_add_u32 s51, s20, 0x100
	s_addc_u32 s56, s21, 0
	s_mov_b32 s57, -2
	v_add_u32_e32 v166, 0x10000, v153
	v_add_u32_e32 v167, 0x14000, v153
	v_add_u32_e32 v252, 0x18000, v153
	v_add_u32_e32 v253, 0x1c000, v153
	s_add_u32 s20, s18, 0xfff80080
	s_addc_u32 s21, s19, -1
	s_add_i32 s63, 0, 0x10000
	s_cmp_eq_u32 s57, 28
	s_cselect_b32 s23, s11, s21
	s_cselect_b32 s22, s45, s20
	s_cselect_b32 s21, s9, s56
	s_cselect_b32 s20, s50, s51
	s_add_i32 s66, 0, 0x14000
	ds_read_b128 v[184:187], v166
	ds_read_b128 v[188:191], v166 offset:1024
	ds_read_b128 v[192:195], v166 offset:2048
	ds_read_b128 v[196:199], v166 offset:3072
	ds_read_b128 v[200:203], v167
	ds_read_b128 v[204:207], v167 offset:1024
	ds_read_b128 v[208:211], v167 offset:2048
	ds_read_b128 v[212:215], v167 offset:3072
	s_add_i32 m0, s29, 0xc000
	ds_read_b128 v[216:219], v155
	ds_read_b128 v[220:223], v155 offset:1024
	ds_read_b128 v[224:227], v155 offset:2048
	ds_read_b128 v[228:231], v155 offset:3072
	ds_read_b128 v[232:235], v155 offset:4096
	ds_read_b128 v[236:239], v155 offset:5120
	ds_read_b128 v[240:243], v155 offset:6144
	ds_read_b128 v[244:247], v155 offset:7168
	global_load_lds_dwordx4 v136, s[18:19]
	s_add_i32 m0, s29, 0xe000
	s_nop 0
	global_load_lds_dwordx4 v138, s[18:19]
	s_waitcnt vmcnt(8)
	s_waitcnt lgkmcnt(0)
	s_setprio 1
	s_barrier
	v_mfma_f32_16x16x32_bf16 v[128:131], v[184:187], v[216:219], 0
	v_mfma_f32_16x16x32_bf16 v[120:123], v[192:195], v[216:219], 0
	v_mfma_f32_16x16x32_bf16 v[112:115], v[184:187], v[224:227], 0
	v_mfma_f32_16x16x32_bf16 v[104:107], v[192:195], v[224:227], 0
	v_mfma_f32_16x16x32_bf16 v[96:99], v[184:187], v[232:235], 0
	v_mfma_f32_16x16x32_bf16 v[88:91], v[192:195], v[232:235], 0
	v_mfma_f32_16x16x32_bf16 v[80:83], v[184:187], v[240:243], 0
	v_mfma_f32_16x16x32_bf16 v[72:75], v[192:195], v[240:243], 0
	v_mfma_f32_16x16x32_bf16 v[128:131], v[188:191], v[220:223], v[128:131]
	v_mfma_f32_16x16x32_bf16 v[120:123], v[196:199], v[220:223], v[120:123]
	v_mfma_f32_16x16x32_bf16 v[112:115], v[188:191], v[228:231], v[112:115]
	v_mfma_f32_16x16x32_bf16 v[104:107], v[196:199], v[228:231], v[104:107]
	v_mfma_f32_16x16x32_bf16 v[96:99], v[188:191], v[236:239], v[96:99]
	v_mfma_f32_16x16x32_bf16 v[88:91], v[196:199], v[236:239], v[88:91]
	v_mfma_f32_16x16x32_bf16 v[80:83], v[188:191], v[244:247], v[80:83]
	v_mfma_f32_16x16x32_bf16 v[72:75], v[196:199], v[244:247], v[72:75]
	v_mfma_f32_16x16x32_bf16 v[124:127], v[200:203], v[216:219], 0
	v_mfma_f32_16x16x32_bf16 v[116:119], v[208:211], v[216:219], 0
	v_mfma_f32_16x16x32_bf16 v[108:111], v[200:203], v[224:227], 0
	v_mfma_f32_16x16x32_bf16 v[100:103], v[208:211], v[224:227], 0
	v_mfma_f32_16x16x32_bf16 v[92:95], v[200:203], v[232:235], 0
	v_mfma_f32_16x16x32_bf16 v[84:87], v[208:211], v[232:235], 0
	v_mfma_f32_16x16x32_bf16 v[76:79], v[200:203], v[240:243], 0
	v_mfma_f32_16x16x32_bf16 v[68:71], v[208:211], v[240:243], 0
	v_mfma_f32_16x16x32_bf16 v[124:127], v[204:207], v[220:223], v[124:127]
	v_mfma_f32_16x16x32_bf16 v[116:119], v[212:215], v[220:223], v[116:119]
	v_mfma_f32_16x16x32_bf16 v[108:111], v[204:207], v[228:231], v[108:111]
	v_mfma_f32_16x16x32_bf16 v[100:103], v[212:215], v[228:231], v[100:103]
	v_mfma_f32_16x16x32_bf16 v[92:95], v[204:207], v[236:239], v[92:95]
	v_mfma_f32_16x16x32_bf16 v[84:87], v[212:215], v[236:239], v[84:87]
	v_mfma_f32_16x16x32_bf16 v[76:79], v[204:207], v[244:247], v[76:79]
	v_mfma_f32_16x16x32_bf16 v[68:71], v[212:215], v[244:247], v[68:71]
	s_barrier
	s_setprio 0
	s_add_i32 s63, s63, s27
	s_mov_b32 m0, s63
	ds_read_b128 v[216:219], v155 offset:16384
	ds_read_b128 v[220:223], v155 offset:17408
	ds_read_b128 v[224:227], v155 offset:18432
	ds_read_b128 v[228:231], v155 offset:19456
	ds_read_b128 v[232:235], v155 offset:20480
	ds_read_b128 v[236:239], v155 offset:21504
	ds_read_b128 v[240:243], v155 offset:22528
	ds_read_b128 v[244:247], v155 offset:23552
	global_load_lds_dwordx4 v2, s[20:21]
	s_add_i32 m0, s63, 0x2000
	s_add_u32 s64, s20, 0x80000
	s_addc_u32 s65, s21, 0
	s_add_i32 s63, s66, s27
	global_load_lds_dwordx4 v0, s[20:21]
	s_mov_b32 m0, s63
	v_lshl_add_u64 v[250:251], s[22:23], 0, v[132:133]
	global_load_lds_dwordx4 v2, s[64:65]
	s_add_i32 m0, s63, 0x2000
	s_nop 0
	global_load_lds_dwordx4 v0, s[64:65]
	v_lshl_add_u64 v[248:249], s[22:23], 0, v[134:135]
	s_mov_b32 m0, s29
	s_nop 0
	global_load_lds_dwordx4 v[248:249], off
	s_mov_b32 m0, s30
	s_nop 0
	global_load_lds_dwordx4 v[250:251], off
	s_waitcnt vmcnt(8)
	s_waitcnt lgkmcnt(0)
	s_setprio 1
	s_barrier
; #define PG8_STAGE(bufoff, gbase, voff) do { _Pragma("unroll") for (int _i = 0; _i < 2; ++_i) \
;         __builtin_amdgcn_global_load_lds((const unsigned*)((const char*)(gbase) + (voff)[_i]), (PG8_LAS unsigned*)(lds + (bufoff) + ldsw + _i * 8192), 16, 0, 0); } while (0)
; #define PG8_LDA(dst, b, h) do { _Pragma("unroll") for (int m = 0; m < 4; ++m) _Pragma("unroll") for (int k = 0; k < 2; ++k) dst[m][k] = *(const PG8_LAS bf16x8*)(lds + PG8_SA(b, h) + aoff + m * 2048 + k * 1024); } while (0)
; #define PG8_LDB(dst, b, h) do { _Pragma("unroll") for (int n = 0; n < 2; ++n) _Pragma("unroll") for (int k = 0; k < 2; ++k) dst[n][k] = *(const PG8_LAS bf16x8*)(lds + PG8_SB(b, h) + boff + n * 2048 + k * 1024); } while (0)
; #define PG8_MMA(ai, bj, At, Bt) do { __builtin_amdgcn_s_setprio(1); _Pragma("unroll") for (int m = 0; m < 4; ++m) _Pragma("unroll") for (int n = 0; n < 2; ++n) _Pragma("unroll") for (int k = 0; k < 2; ++k) \
;         acc[ai][bj][m][n] = __builtin_amdgcn_mfma_f32_16x16x32_bf16(Bt[n][k], At[m][k], acc[ai][bj][m][n], 0, 0, 0); __builtin_amdgcn_s_setprio(0); } while (0)
; #define PG8_WAIT_V(n) asm volatile("s_waitcnt vmcnt(" #n ")" ::: "memory")
; #define PG8_WAIT_L(n) asm volatile("s_waitcnt lgkmcnt(" #n ")" ::: "memory")
; #define PG8_BAR __builtin_amdgcn_s_barrier()
; #define PG8_SCHED __builtin_amdgcn_sched_barrier(0)
; template <class Epi, class Sched, bool ALIGN_EPI = false, bool SP2 = false>
; __device__ __forceinline__ void gemm_phase(PG8_LAS unsigned char* lds, const Gemm g, const Sched& S, const Epi& E) {
;     ...
;             PG8_WAIT_V(8); PG8_WAIT_L(0); PG8_BAR; PG8_MMA(1, 0, At, B0); PG8_MMA(1, 1, At, B1); PG8_BAR; PG8_SCHED;
;             PG8_LDB(B0, 1, 0); PG8_LDB(B1, 1, 1); PG8_SCHED; PG8_LDA(At, 1, 0); PG8_STAGE(PG8_SA(0, 1), a2 + hstep, voffA);
;             PG8_WAIT_V(8); PG8_WAIT_L(0); PG8_BAR; PG8_MMA(0, 0, At, B0); PG8_MMA(0, 1, At, B1); PG8_BAR; PG8_SCHED;
	v_mfma_f32_16x16x32_bf16 v[64:67], v[184:187], v[216:219], 0
	v_mfma_f32_16x16x32_bf16 v[56:59], v[192:195], v[216:219], 0
	v_mfma_f32_16x16x32_bf16 v[48:51], v[184:187], v[224:227], 0
	v_mfma_f32_16x16x32_bf16 v[40:43], v[192:195], v[224:227], 0
	v_mfma_f32_16x16x32_bf16 v[32:35], v[184:187], v[232:235], 0
	v_mfma_f32_16x16x32_bf16 v[24:27], v[192:195], v[232:235], 0
	v_mfma_f32_16x16x32_bf16 v[16:19], v[184:187], v[240:243], 0
	v_mfma_f32_16x16x32_bf16 v[8:11], v[192:195], v[240:243], 0
	v_mfma_f32_16x16x32_bf16 v[64:67], v[188:191], v[220:223], v[64:67]
	v_mfma_f32_16x16x32_bf16 v[56:59], v[196:199], v[220:223], v[56:59]
	v_mfma_f32_16x16x32_bf16 v[48:51], v[188:191], v[228:231], v[48:51]
	v_mfma_f32_16x16x32_bf16 v[40:43], v[196:199], v[228:231], v[40:43]
	v_mfma_f32_16x16x32_bf16 v[32:35], v[188:191], v[236:239], v[32:35]
	v_mfma_f32_16x16x32_bf16 v[24:27], v[196:199], v[236:239], v[24:27]
	v_mfma_f32_16x16x32_bf16 v[16:19], v[188:191], v[244:247], v[16:19]
	v_mfma_f32_16x16x32_bf16 v[8:11], v[196:199], v[244:247], v[8:11]
	v_mfma_f32_16x16x32_bf16 v[60:63], v[200:203], v[216:219], 0
	v_mfma_f32_16x16x32_bf16 v[52:55], v[208:211], v[216:219], 0
	v_mfma_f32_16x16x32_bf16 v[44:47], v[200:203], v[224:227], 0
	v_mfma_f32_16x16x32_bf16 v[36:39], v[208:211], v[224:227], 0
	v_mfma_f32_16x16x32_bf16 v[28:31], v[200:203], v[232:235], 0
	v_mfma_f32_16x16x32_bf16 v[20:23], v[208:211], v[232:235], 0
	v_mfma_f32_16x16x32_bf16 v[12:15], v[200:203], v[240:243], 0
	v_mfma_f32_16x16x32_bf16 v[4:7], v[208:211], v[240:243], 0
	v_mfma_f32_16x16x32_bf16 v[60:63], v[204:207], v[220:223], v[60:63]
	v_mfma_f32_16x16x32_bf16 v[52:55], v[212:215], v[220:223], v[52:55]
	v_mfma_f32_16x16x32_bf16 v[44:47], v[204:207], v[228:231], v[44:47]
	v_mfma_f32_16x16x32_bf16 v[36:39], v[212:215], v[228:231], v[36:39]
	v_mfma_f32_16x16x32_bf16 v[28:31], v[204:207], v[236:239], v[28:31]
	v_mfma_f32_16x16x32_bf16 v[20:23], v[212:215], v[236:239], v[20:23]
	v_mfma_f32_16x16x32_bf16 v[12:15], v[204:207], v[244:247], v[12:15]
	v_mfma_f32_16x16x32_bf16 v[4:7], v[212:215], v[244:247], v[4:7]
	s_barrier
	s_setprio 0
	s_add_i32 s63, 0, 0x18000
	s_add_i32 s64, 0, 0x1c000
	ds_read_b128 v[184:187], v252
	ds_read_b128 v[188:191], v252 offset:1024
	ds_read_b128 v[192:195], v252 offset:2048
	ds_read_b128 v[196:199], v252 offset:3072
	ds_read_b128 v[200:203], v253
	ds_read_b128 v[204:207], v253 offset:1024
	ds_read_b128 v[208:211], v253 offset:2048
	ds_read_b128 v[212:215], v253 offset:3072
	s_add_u32 s22, s22, 0x80000
	s_addc_u32 s23, s23, 0
	s_mov_b32 m0, s31
	ds_read_b128 v[216:219], v155 offset:32768
	ds_read_b128 v[220:223], v155 offset:33792
	ds_read_b128 v[224:227], v155 offset:34816
	ds_read_b128 v[228:231], v155 offset:35840
	ds_read_b128 v[232:235], v155 offset:36864
	ds_read_b128 v[236:239], v155 offset:37888
	ds_read_b128 v[240:243], v155 offset:38912
	ds_read_b128 v[244:247], v155 offset:39936
	global_load_lds_dwordx4 v134, s[22:23]
	s_mov_b32 m0, s34
	s_nop 0
	global_load_lds_dwordx4 v132, s[22:23]
	s_waitcnt vmcnt(8)
	s_waitcnt lgkmcnt(0)
	s_setprio 1
	s_barrier
	v_mfma_f32_16x16x32_bf16 v[128:131], v[184:187], v[216:219], v[128:131]
	v_mfma_f32_16x16x32_bf16 v[120:123], v[192:195], v[216:219], v[120:123]
	v_mfma_f32_16x16x32_bf16 v[112:115], v[184:187], v[224:227], v[112:115]
	v_mfma_f32_16x16x32_bf16 v[104:107], v[192:195], v[224:227], v[104:107]
	v_mfma_f32_16x16x32_bf16 v[96:99], v[184:187], v[232:235], v[96:99]
	v_mfma_f32_16x16x32_bf16 v[88:91], v[192:195], v[232:235], v[88:91]
	v_mfma_f32_16x16x32_bf16 v[80:83], v[184:187], v[240:243], v[80:83]
	v_mfma_f32_16x16x32_bf16 v[72:75], v[192:195], v[240:243], v[72:75]
	v_mfma_f32_16x16x32_bf16 v[128:131], v[188:191], v[220:223], v[128:131]
	v_mfma_f32_16x16x32_bf16 v[120:123], v[196:199], v[220:223], v[120:123]
	v_mfma_f32_16x16x32_bf16 v[112:115], v[188:191], v[228:231], v[112:115]
	v_mfma_f32_16x16x32_bf16 v[104:107], v[196:199], v[228:231], v[104:107]
	v_mfma_f32_16x16x32_bf16 v[96:99], v[188:191], v[236:239], v[96:99]
	v_mfma_f32_16x16x32_bf16 v[88:91], v[196:199], v[236:239], v[88:91]
	v_mfma_f32_16x16x32_bf16 v[80:83], v[188:191], v[244:247], v[80:83]
	v_mfma_f32_16x16x32_bf16 v[72:75], v[196:199], v[244:247], v[72:75]
	v_mfma_f32_16x16x32_bf16 v[124:127], v[200:203], v[216:219], v[124:127]
	v_mfma_f32_16x16x32_bf16 v[116:119], v[208:211], v[216:219], v[116:119]
	v_mfma_f32_16x16x32_bf16 v[108:111], v[200:203], v[224:227], v[108:111]
	v_mfma_f32_16x16x32_bf16 v[100:103], v[208:211], v[224:227], v[100:103]
	v_mfma_f32_16x16x32_bf16 v[92:95], v[200:203], v[232:235], v[92:95]
	v_mfma_f32_16x16x32_bf16 v[84:87], v[208:211], v[232:235], v[84:87]
	v_mfma_f32_16x16x32_bf16 v[76:79], v[200:203], v[240:243], v[76:79]
	v_mfma_f32_16x16x32_bf16 v[68:71], v[208:211], v[240:243], v[68:71]
	v_mfma_f32_16x16x32_bf16 v[124:127], v[204:207], v[220:223], v[124:127]
	v_mfma_f32_16x16x32_bf16 v[116:119], v[212:215], v[220:223], v[116:119]
	v_mfma_f32_16x16x32_bf16 v[108:111], v[204:207], v[228:231], v[108:111]
	v_mfma_f32_16x16x32_bf16 v[100:103], v[212:215], v[228:231], v[100:103]
	v_mfma_f32_16x16x32_bf16 v[92:95], v[204:207], v[236:239], v[92:95]
	v_mfma_f32_16x16x32_bf16 v[84:87], v[212:215], v[236:239], v[84:87]
	v_mfma_f32_16x16x32_bf16 v[76:79], v[204:207], v[244:247], v[76:79]
	v_mfma_f32_16x16x32_bf16 v[68:71], v[212:215], v[244:247], v[68:71]
	s_barrier
; #define PG8_STAGE(bufoff, gbase, voff) do { _Pragma("unroll") for (int _i = 0; _i < 2; ++_i) \
;         __builtin_amdgcn_global_load_lds((const unsigned*)((const char*)(gbase) + (voff)[_i]), (PG8_LAS unsigned*)(lds + (bufoff) + ldsw + _i * 8192), 16, 0, 0); } while (0)
; #define PG8_LDA(dst, b, h) do { _Pragma("unroll") for (int m = 0; m < 4; ++m) _Pragma("unroll") for (int k = 0; k < 2; ++k) dst[m][k] = *(const PG8_LAS bf16x8*)(lds + PG8_SA(b, h) + aoff + m * 2048 + k * 1024); } while (0)
; #define PG8_LDB(dst, b, h) do { _Pragma("unroll") for (int n = 0; n < 2; ++n) _Pragma("unroll") for (int k = 0; k < 2; ++k) dst[n][k] = *(const PG8_LAS bf16x8*)(lds + PG8_SB(b, h) + boff + n * 2048 + k * 1024); } while (0)
; #define PG8_MMA(ai, bj, At, Bt) do { __builtin_amdgcn_s_setprio(1); _Pragma("unroll") for (int m = 0; m < 4; ++m) _Pragma("unroll") for (int n = 0; n < 2; ++n) _Pragma("unroll") for (int k = 0; k < 2; ++k) \
;         acc[ai][bj][m][n] = __builtin_amdgcn_mfma_f32_16x16x32_bf16(Bt[n][k], At[m][k], acc[ai][bj][m][n], 0, 0, 0); __builtin_amdgcn_s_setprio(0); } while (0)
; #define PG8_WAIT_V(n) asm volatile("s_waitcnt vmcnt(" #n ")" ::: "memory")
; #define PG8_WAIT_L(n) asm volatile("s_waitcnt lgkmcnt(" #n ")" ::: "memory")
; template <class Epi, class Sched, bool ALIGN_EPI = false, bool SP2 = false>
; __device__ __forceinline__ void gemm_phase(PG8_LAS unsigned char* lds, const Gemm g, const Sched& S, const Epi& E) {
;     ...
;             const bool last = (t == nt - 2);
;             const char* a1 = cA + (size_t)(t + 1) * kstep;
;             const char* a2 = last ? nA : cA + (size_t)(t + 2) * kstep; const char* b2 = last ? nB : cB + (size_t)(t + 2) * kstep;
;             const char* a3 = a2 + kstep; const char* b3 = b2 + kstep;
;             if (last && has_next) S.a_ready(nxt);
;             if constexpr (SP2) {
;             PG8_LDB(B0, 0, 0); PG8_LDB(B1, 0, 1); PG8_SCHED; PG8_LDA(At, 0, 0); PG8_STAGE(PG8_SA(1, 1), a1 + hstep, voffA);
;             PG8_WAIT_V(8); PG8_WAIT_L(0); PG8_BAR; PG8_MMA(0, 0, At, B0); PG8_MMA(0, 1, At, B1); PG8_BAR; PG8_SCHED;
;     ...
;             PG8_LDA(At, 1, 1); PG8_STAGE(PG8_SB(1, 0), b3, voffB); PG8_STAGE(PG8_SB(1, 1), b3 + hstep, voffB); PG8_STAGE(PG8_SA(1, 0), a3, voffA);
;             PG8_WAIT_V(8); PG8_WAIT_L(0); PG8_BAR; PG8_MMA(1, 0, At, B0); PG8_MMA(1, 1, At, B1); PG8_BAR; PG8_SCHED;
	s_setprio 0
	s_add_i32 s22, s63, s27
	s_mov_b32 m0, s22
	ds_read_b128 v[216:219], v155 offset:49152
	ds_read_b128 v[220:223], v155 offset:50176
	ds_read_b128 v[224:227], v155 offset:51200
	ds_read_b128 v[228:231], v155 offset:52224
	ds_read_b128 v[232:235], v155 offset:53248
	ds_read_b128 v[236:239], v155 offset:54272
	ds_read_b128 v[240:243], v155 offset:55296
	ds_read_b128 v[244:247], v155 offset:56320
	s_add_u32 vcc_lo, s20, 0x80
	s_addc_u32 vcc_hi, s21, 0
	global_load_lds_dwordx4 v2, vcc
	s_add_i32 m0, s22, 0x2000
	s_add_u32 s20, s20, 0x80080
	s_addc_u32 s21, s21, 0
	s_add_i32 s22, s64, s27
	s_add_u32 vcc_lo, s20, 0xfff80000
	s_addc_u32 vcc_hi, s21, -1
	global_load_lds_dwordx4 v0, vcc
	s_mov_b32 m0, s22
	s_nop 0
	global_load_lds_dwordx4 v2, s[20:21]
	s_add_i32 m0, s22, 0x2000
	s_nop 0
	global_load_lds_dwordx4 v0, s[20:21]
	v_lshl_add_u64 v[150:151], v[248:249], 0, s[36:37]
	s_mov_b32 m0, s35
	s_nop 0
	global_load_lds_dwordx4 v[150:151], off
	v_lshl_add_u64 v[150:151], v[250:251], 0, s[36:37]
	s_mov_b32 m0, s42
	s_nop 0
	global_load_lds_dwordx4 v[150:151], off
	s_waitcnt vmcnt(8)
	s_waitcnt lgkmcnt(0)
	s_setprio 1
	s_barrier
	v_mfma_f32_16x16x32_bf16 v[64:67], v[184:187], v[216:219], v[64:67]
	v_mfma_f32_16x16x32_bf16 v[56:59], v[192:195], v[216:219], v[56:59]
	v_mfma_f32_16x16x32_bf16 v[48:51], v[184:187], v[224:227], v[48:51]
	v_mfma_f32_16x16x32_bf16 v[40:43], v[192:195], v[224:227], v[40:43]
	v_mfma_f32_16x16x32_bf16 v[32:35], v[184:187], v[232:235], v[32:35]
	v_mfma_f32_16x16x32_bf16 v[24:27], v[192:195], v[232:235], v[24:27]
	v_mfma_f32_16x16x32_bf16 v[16:19], v[184:187], v[240:243], v[16:19]
	v_mfma_f32_16x16x32_bf16 v[8:11], v[192:195], v[240:243], v[8:11]
	v_mfma_f32_16x16x32_bf16 v[64:67], v[188:191], v[220:223], v[64:67]
	v_mfma_f32_16x16x32_bf16 v[56:59], v[196:199], v[220:223], v[56:59]
	v_mfma_f32_16x16x32_bf16 v[48:51], v[188:191], v[228:231], v[48:51]
	v_mfma_f32_16x16x32_bf16 v[40:43], v[196:199], v[228:231], v[40:43]
	v_mfma_f32_16x16x32_bf16 v[32:35], v[188:191], v[236:239], v[32:35]
	v_mfma_f32_16x16x32_bf16 v[24:27], v[196:199], v[236:239], v[24:27]
	v_mfma_f32_16x16x32_bf16 v[16:19], v[188:191], v[244:247], v[16:19]
	v_mfma_f32_16x16x32_bf16 v[8:11], v[196:199], v[244:247], v[8:11]
	v_mfma_f32_16x16x32_bf16 v[60:63], v[200:203], v[216:219], v[60:63]
	v_mfma_f32_16x16x32_bf16 v[52:55], v[208:211], v[216:219], v[52:55]
	v_mfma_f32_16x16x32_bf16 v[44:47], v[200:203], v[224:227], v[44:47]
	v_mfma_f32_16x16x32_bf16 v[36:39], v[208:211], v[224:227], v[36:39]
	v_mfma_f32_16x16x32_bf16 v[28:31], v[200:203], v[232:235], v[28:31]
	v_mfma_f32_16x16x32_bf16 v[20:23], v[208:211], v[232:235], v[20:23]
	v_mfma_f32_16x16x32_bf16 v[12:15], v[200:203], v[240:243], v[12:15]
	v_mfma_f32_16x16x32_bf16 v[4:7], v[208:211], v[240:243], v[4:7]
	v_mfma_f32_16x16x32_bf16 v[60:63], v[204:207], v[220:223], v[60:63]
	v_mfma_f32_16x16x32_bf16 v[52:55], v[212:215], v[220:223], v[52:55]
	v_mfma_f32_16x16x32_bf16 v[44:47], v[204:207], v[228:231], v[44:47]
	v_mfma_f32_16x16x32_bf16 v[36:39], v[212:215], v[228:231], v[36:39]
	v_mfma_f32_16x16x32_bf16 v[28:31], v[204:207], v[236:239], v[28:31]
	v_mfma_f32_16x16x32_bf16 v[20:23], v[212:215], v[236:239], v[20:23]
	v_mfma_f32_16x16x32_bf16 v[12:15], v[204:207], v[244:247], v[12:15]
	v_mfma_f32_16x16x32_bf16 v[4:7], v[212:215], v[244:247], v[4:7]
	s_barrier
	s_setprio 0
	s_add_i32 s57, s57, 2
	s_add_u32 s18, s18, 0x100
	s_addc_u32 s19, s19, 0
	s_add_u32 s51, s51, 0x100
	s_addc_u32 s56, s56, 0
	s_cmp_gt_u32 s57, 29
.LBB0_567:
	s_add_u32 s20, s18, 0xfff80080
	s_addc_u32 s21, s19, -1
	s_add_i32 s63, 0, 0x10000
	s_cmp_eq_u32 s57, 28
	s_cselect_b32 s23, s11, s21
	s_cselect_b32 s22, s45, s20
	s_cselect_b32 s21, s9, s56
	s_cselect_b32 s20, s50, s51
	s_add_i32 s66, 0, 0x14000
	ds_read_b128 v[184:187], v166
	ds_read_b128 v[188:191], v166 offset:1024
	ds_read_b128 v[192:195], v166 offset:2048
	ds_read_b128 v[196:199], v166 offset:3072
	ds_read_b128 v[200:203], v167
	ds_read_b128 v[204:207], v167 offset:1024
	ds_read_b128 v[208:211], v167 offset:2048
	ds_read_b128 v[212:215], v167 offset:3072
	s_add_i32 m0, s29, 0xc000
	ds_read_b128 v[216:219], v155
	ds_read_b128 v[220:223], v155 offset:1024
	ds_read_b128 v[224:227], v155 offset:2048
	ds_read_b128 v[228:231], v155 offset:3072
	ds_read_b128 v[232:235], v155 offset:4096
	ds_read_b128 v[236:239], v155 offset:5120
	ds_read_b128 v[240:243], v155 offset:6144
	ds_read_b128 v[244:247], v155 offset:7168
	global_load_lds_dwordx4 v136, s[18:19]
	s_add_i32 m0, s29, 0xe000
	s_nop 0
	global_load_lds_dwordx4 v138, s[18:19]
	s_waitcnt vmcnt(8)
	s_waitcnt lgkmcnt(0)
	s_setprio 1
	s_barrier
; #define PG8_STAGE(bufoff, gbase, voff) do { _Pragma("unroll") for (int _i = 0; _i < 2; ++_i) \
;         __builtin_amdgcn_global_load_lds((const unsigned*)((const char*)(gbase) + (voff)[_i]), (PG8_LAS unsigned*)(lds + (bufoff) + ldsw + _i * 8192), 16, 0, 0); } while (0)
; #define PG8_LDA(dst, b, h) do { _Pragma("unroll") for (int m = 0; m < 4; ++m) _Pragma("unroll") for (int k = 0; k < 2; ++k) dst[m][k] = *(const PG8_LAS bf16x8*)(lds + PG8_SA(b, h) + aoff + m * 2048 + k * 1024); } while (0)
; #define PG8_MMA(ai, bj, At, Bt) do { __builtin_amdgcn_s_setprio(1); _Pragma("unroll") for (int m = 0; m < 4; ++m) _Pragma("unroll") for (int n = 0; n < 2; ++n) _Pragma("unroll") for (int k = 0; k < 2; ++k) \
;         acc[ai][bj][m][n] = __builtin_amdgcn_mfma_f32_16x16x32_bf16(Bt[n][k], At[m][k], acc[ai][bj][m][n], 0, 0, 0); __builtin_amdgcn_s_setprio(0); } while (0)
; #define PG8_WAIT_V(n) asm volatile("s_waitcnt vmcnt(" #n ")" ::: "memory")
; #define PG8_WAIT_L(n) asm volatile("s_waitcnt lgkmcnt(" #n ")" ::: "memory")
; #define PG8_BAR __builtin_amdgcn_s_barrier()
; #define PG8_SCHED __builtin_amdgcn_sched_barrier(0)
; template <class Epi, class Sched, bool ALIGN_EPI = false, bool SP2 = false>
; __device__ __forceinline__ void gemm_phase(PG8_LAS unsigned char* lds, const Gemm g, const Sched& S, const Epi& E) {
;     ...
;             PG8_WAIT_V(8); PG8_WAIT_L(0); PG8_BAR; PG8_MMA(0, 0, At, B0); PG8_MMA(0, 1, At, B1); PG8_BAR; PG8_SCHED;
;             PG8_LDA(At, 0, 1); PG8_STAGE(PG8_SB(0, 0), b2, voffB); PG8_STAGE(PG8_SB(0, 1), b2 + hstep, voffB); PG8_STAGE(PG8_SA(0, 0), a2, voffA);
;             PG8_WAIT_V(8); PG8_WAIT_L(0); PG8_BAR; PG8_MMA(1, 0, At, B0); PG8_MMA(1, 1, At, B1); PG8_BAR; PG8_SCHED;
	v_mfma_f32_16x16x32_bf16 v[128:131], v[184:187], v[216:219], v[128:131]
	v_mfma_f32_16x16x32_bf16 v[120:123], v[192:195], v[216:219], v[120:123]
	v_mfma_f32_16x16x32_bf16 v[112:115], v[184:187], v[224:227], v[112:115]
	v_mfma_f32_16x16x32_bf16 v[104:107], v[192:195], v[224:227], v[104:107]
	v_mfma_f32_16x16x32_bf16 v[96:99], v[184:187], v[232:235], v[96:99]
	v_mfma_f32_16x16x32_bf16 v[88:91], v[192:195], v[232:235], v[88:91]
	v_mfma_f32_16x16x32_bf16 v[80:83], v[184:187], v[240:243], v[80:83]
	v_mfma_f32_16x16x32_bf16 v[72:75], v[192:195], v[240:243], v[72:75]
	v_mfma_f32_16x16x32_bf16 v[128:131], v[188:191], v[220:223], v[128:131]
	v_mfma_f32_16x16x32_bf16 v[120:123], v[196:199], v[220:223], v[120:123]
	v_mfma_f32_16x16x32_bf16 v[112:115], v[188:191], v[228:231], v[112:115]
	v_mfma_f32_16x16x32_bf16 v[104:107], v[196:199], v[228:231], v[104:107]
	v_mfma_f32_16x16x32_bf16 v[96:99], v[188:191], v[236:239], v[96:99]
	v_mfma_f32_16x16x32_bf16 v[88:91], v[196:199], v[236:239], v[88:91]
	v_mfma_f32_16x16x32_bf16 v[80:83], v[188:191], v[244:247], v[80:83]
	v_mfma_f32_16x16x32_bf16 v[72:75], v[196:199], v[244:247], v[72:75]
	v_mfma_f32_16x16x32_bf16 v[124:127], v[200:203], v[216:219], v[124:127]
	v_mfma_f32_16x16x32_bf16 v[116:119], v[208:211], v[216:219], v[116:119]
	v_mfma_f32_16x16x32_bf16 v[108:111], v[200:203], v[224:227], v[108:111]
	v_mfma_f32_16x16x32_bf16 v[100:103], v[208:211], v[224:227], v[100:103]
	v_mfma_f32_16x16x32_bf16 v[92:95], v[200:203], v[232:235], v[92:95]
	v_mfma_f32_16x16x32_bf16 v[84:87], v[208:211], v[232:235], v[84:87]
	v_mfma_f32_16x16x32_bf16 v[76:79], v[200:203], v[240:243], v[76:79]
	v_mfma_f32_16x16x32_bf16 v[68:71], v[208:211], v[240:243], v[68:71]
	v_mfma_f32_16x16x32_bf16 v[124:127], v[204:207], v[220:223], v[124:127]
	v_mfma_f32_16x16x32_bf16 v[116:119], v[212:215], v[220:223], v[116:119]
	v_mfma_f32_16x16x32_bf16 v[108:111], v[204:207], v[228:231], v[108:111]
	v_mfma_f32_16x16x32_bf16 v[100:103], v[212:215], v[228:231], v[100:103]
	v_mfma_f32_16x16x32_bf16 v[92:95], v[204:207], v[236:239], v[92:95]
	v_mfma_f32_16x16x32_bf16 v[84:87], v[212:215], v[236:239], v[84:87]
	v_mfma_f32_16x16x32_bf16 v[76:79], v[204:207], v[244:247], v[76:79]
	v_mfma_f32_16x16x32_bf16 v[68:71], v[212:215], v[244:247], v[68:71]
	s_barrier
	s_setprio 0
	s_add_i32 s63, s63, s27
	s_mov_b32 m0, s63
	ds_read_b128 v[216:219], v155 offset:16384
	ds_read_b128 v[220:223], v155 offset:17408
	ds_read_b128 v[224:227], v155 offset:18432
	ds_read_b128 v[228:231], v155 offset:19456
	ds_read_b128 v[232:235], v155 offset:20480
	ds_read_b128 v[236:239], v155 offset:21504
	ds_read_b128 v[240:243], v155 offset:22528
	ds_read_b128 v[244:247], v155 offset:23552
	global_load_lds_dwordx4 v2, s[20:21]
	s_add_i32 m0, s63, 0x2000
	s_add_u32 s64, s20, 0x80000
	s_addc_u32 s65, s21, 0
	s_add_i32 s63, s66, s27
	global_load_lds_dwordx4 v0, s[20:21]
	s_mov_b32 m0, s63
	v_lshl_add_u64 v[250:251], s[22:23], 0, v[132:133]
	global_load_lds_dwordx4 v2, s[64:65]
	s_add_i32 m0, s63, 0x2000
	s_nop 0
	global_load_lds_dwordx4 v0, s[64:65]
	v_lshl_add_u64 v[248:249], s[22:23], 0, v[134:135]
	s_mov_b32 m0, s29
	s_nop 0
	global_load_lds_dwordx4 v[248:249], off
	s_mov_b32 m0, s30
	s_nop 0
	global_load_lds_dwordx4 v[250:251], off
	s_waitcnt vmcnt(8)
	s_waitcnt lgkmcnt(0)
	s_setprio 1
	s_barrier
	v_mfma_f32_16x16x32_bf16 v[64:67], v[184:187], v[216:219], v[64:67]
	v_mfma_f32_16x16x32_bf16 v[56:59], v[192:195], v[216:219], v[56:59]
	v_mfma_f32_16x16x32_bf16 v[48:51], v[184:187], v[224:227], v[48:51]
	v_mfma_f32_16x16x32_bf16 v[40:43], v[192:195], v[224:227], v[40:43]
	v_mfma_f32_16x16x32_bf16 v[32:35], v[184:187], v[232:235], v[32:35]
	v_mfma_f32_16x16x32_bf16 v[24:27], v[192:195], v[232:235], v[24:27]
	v_mfma_f32_16x16x32_bf16 v[16:19], v[184:187], v[240:243], v[16:19]
	v_mfma_f32_16x16x32_bf16 v[8:11], v[192:195], v[240:243], v[8:11]
	v_mfma_f32_16x16x32_bf16 v[64:67], v[188:191], v[220:223], v[64:67]
	v_mfma_f32_16x16x32_bf16 v[56:59], v[196:199], v[220:223], v[56:59]
	v_mfma_f32_16x16x32_bf16 v[48:51], v[188:191], v[228:231], v[48:51]
	v_mfma_f32_16x16x32_bf16 v[40:43], v[196:199], v[228:231], v[40:43]
	v_mfma_f32_16x16x32_bf16 v[32:35], v[188:191], v[236:239], v[32:35]
	v_mfma_f32_16x16x32_bf16 v[24:27], v[196:199], v[236:239], v[24:27]
	v_mfma_f32_16x16x32_bf16 v[16:19], v[188:191], v[244:247], v[16:19]
	v_mfma_f32_16x16x32_bf16 v[8:11], v[196:199], v[244:247], v[8:11]
	v_mfma_f32_16x16x32_bf16 v[60:63], v[200:203], v[216:219], v[60:63]
	v_mfma_f32_16x16x32_bf16 v[52:55], v[208:211], v[216:219], v[52:55]
	v_mfma_f32_16x16x32_bf16 v[44:47], v[200:203], v[224:227], v[44:47]
	v_mfma_f32_16x16x32_bf16 v[36:39], v[208:211], v[224:227], v[36:39]
	v_mfma_f32_16x16x32_bf16 v[28:31], v[200:203], v[232:235], v[28:31]
	v_mfma_f32_16x16x32_bf16 v[20:23], v[208:211], v[232:235], v[20:23]
	v_mfma_f32_16x16x32_bf16 v[12:15], v[200:203], v[240:243], v[12:15]
	v_mfma_f32_16x16x32_bf16 v[4:7], v[208:211], v[240:243], v[4:7]
	v_mfma_f32_16x16x32_bf16 v[60:63], v[204:207], v[220:223], v[60:63]
	v_mfma_f32_16x16x32_bf16 v[52:55], v[212:215], v[220:223], v[52:55]
	v_mfma_f32_16x16x32_bf16 v[44:47], v[204:207], v[228:231], v[44:47]
	v_mfma_f32_16x16x32_bf16 v[36:39], v[212:215], v[228:231], v[36:39]
	v_mfma_f32_16x16x32_bf16 v[28:31], v[204:207], v[236:239], v[28:31]
	v_mfma_f32_16x16x32_bf16 v[20:23], v[212:215], v[236:239], v[20:23]
	v_mfma_f32_16x16x32_bf16 v[12:15], v[204:207], v[244:247], v[12:15]
	v_mfma_f32_16x16x32_bf16 v[4:7], v[212:215], v[244:247], v[4:7]
	s_barrier
; #define PG8_STAGE(bufoff, gbase, voff) do { _Pragma("unroll") for (int _i = 0; _i < 2; ++_i) \
;         __builtin_amdgcn_global_load_lds((const unsigned*)((const char*)(gbase) + (voff)[_i]), (PG8_LAS unsigned*)(lds + (bufoff) + ldsw + _i * 8192), 16, 0, 0); } while (0)
; #define PG8_LDA(dst, b, h) do { _Pragma("unroll") for (int m = 0; m < 4; ++m) _Pragma("unroll") for (int k = 0; k < 2; ++k) dst[m][k] = *(const PG8_LAS bf16x8*)(lds + PG8_SA(b, h) + aoff + m * 2048 + k * 1024); } while (0)
; #define PG8_LDB(dst, b, h) do { _Pragma("unroll") for (int n = 0; n < 2; ++n) _Pragma("unroll") for (int k = 0; k < 2; ++k) dst[n][k] = *(const PG8_LAS bf16x8*)(lds + PG8_SB(b, h) + boff + n * 2048 + k * 1024); } while (0)
; #define PG8_MMA(ai, bj, At, Bt) do { __builtin_amdgcn_s_setprio(1); _Pragma("unroll") for (int m = 0; m < 4; ++m) _Pragma("unroll") for (int n = 0; n < 2; ++n) _Pragma("unroll") for (int k = 0; k < 2; ++k) \
;         acc[ai][bj][m][n] = __builtin_amdgcn_mfma_f32_16x16x32_bf16(Bt[n][k], At[m][k], acc[ai][bj][m][n], 0, 0, 0); __builtin_amdgcn_s_setprio(0); } while (0)
; #define PG8_WAIT_V(n) asm volatile("s_waitcnt vmcnt(" #n ")" ::: "memory")
; #define PG8_WAIT_L(n) asm volatile("s_waitcnt lgkmcnt(" #n ")" ::: "memory")
; #define PG8_BAR __builtin_amdgcn_s_barrier()
; #define PG8_SCHED __builtin_amdgcn_sched_barrier(0)
; template <class Epi, class Sched, bool ALIGN_EPI = false, bool SP2 = false>
; __device__ __forceinline__ void gemm_phase(PG8_LAS unsigned char* lds, const Gemm g, const Sched& S, const Epi& E) {
;     ...
;             PG8_LDB(B0, 1, 0); PG8_LDB(B1, 1, 1); PG8_SCHED; PG8_LDA(At, 1, 0); PG8_STAGE(PG8_SA(0, 1), a2 + hstep, voffA);
;             PG8_WAIT_V(8); PG8_WAIT_L(0); PG8_BAR; PG8_MMA(0, 0, At, B0); PG8_MMA(0, 1, At, B1); PG8_BAR; PG8_SCHED;
;             PG8_LDA(At, 1, 1); PG8_STAGE(PG8_SB(1, 0), b3, voffB); PG8_STAGE(PG8_SB(1, 1), b3 + hstep, voffB); PG8_STAGE(PG8_SA(1, 0), a3, voffA);
;             PG8_WAIT_V(8); PG8_WAIT_L(0); PG8_BAR; PG8_MMA(1, 0, At, B0); PG8_MMA(1, 1, At, B1); PG8_BAR; PG8_SCHED;
;     ...
;         if constexpr (ALIGN_EPI) { if (wr == 0) PG8_BAR; }
	s_setprio 0
	s_add_i32 s63, 0, 0x18000
	s_add_i32 s64, 0, 0x1c000
	ds_read_b128 v[184:187], v252
	ds_read_b128 v[188:191], v252 offset:1024
	ds_read_b128 v[192:195], v252 offset:2048
	ds_read_b128 v[196:199], v252 offset:3072
	ds_read_b128 v[200:203], v253
	ds_read_b128 v[204:207], v253 offset:1024
	ds_read_b128 v[208:211], v253 offset:2048
	ds_read_b128 v[212:215], v253 offset:3072
	s_add_u32 s22, s22, 0x80000
	s_addc_u32 s23, s23, 0
	s_mov_b32 m0, s31
	ds_read_b128 v[216:219], v155 offset:32768
	ds_read_b128 v[220:223], v155 offset:33792
	ds_read_b128 v[224:227], v155 offset:34816
	ds_read_b128 v[228:231], v155 offset:35840
	ds_read_b128 v[232:235], v155 offset:36864
	ds_read_b128 v[236:239], v155 offset:37888
	ds_read_b128 v[240:243], v155 offset:38912
	ds_read_b128 v[244:247], v155 offset:39936
	global_load_lds_dwordx4 v134, s[22:23]
	s_mov_b32 m0, s34
	s_nop 0
	global_load_lds_dwordx4 v132, s[22:23]
	s_waitcnt vmcnt(8)
	s_waitcnt lgkmcnt(0)
	s_setprio 1
	s_barrier
	v_mfma_f32_16x16x32_bf16 v[128:131], v[184:187], v[216:219], v[128:131]
	v_mfma_f32_16x16x32_bf16 v[120:123], v[192:195], v[216:219], v[120:123]
	v_mfma_f32_16x16x32_bf16 v[112:115], v[184:187], v[224:227], v[112:115]
	v_mfma_f32_16x16x32_bf16 v[104:107], v[192:195], v[224:227], v[104:107]
	v_mfma_f32_16x16x32_bf16 v[96:99], v[184:187], v[232:235], v[96:99]
	v_mfma_f32_16x16x32_bf16 v[88:91], v[192:195], v[232:235], v[88:91]
	v_mfma_f32_16x16x32_bf16 v[80:83], v[184:187], v[240:243], v[80:83]
	v_mfma_f32_16x16x32_bf16 v[72:75], v[192:195], v[240:243], v[72:75]
	v_mfma_f32_16x16x32_bf16 v[128:131], v[188:191], v[220:223], v[128:131]
	v_mfma_f32_16x16x32_bf16 v[120:123], v[196:199], v[220:223], v[120:123]
	v_mfma_f32_16x16x32_bf16 v[112:115], v[188:191], v[228:231], v[112:115]
	v_mfma_f32_16x16x32_bf16 v[104:107], v[196:199], v[228:231], v[104:107]
	v_mfma_f32_16x16x32_bf16 v[96:99], v[188:191], v[236:239], v[96:99]
	v_mfma_f32_16x16x32_bf16 v[88:91], v[196:199], v[236:239], v[88:91]
	v_mfma_f32_16x16x32_bf16 v[80:83], v[188:191], v[244:247], v[80:83]
	v_mfma_f32_16x16x32_bf16 v[72:75], v[196:199], v[244:247], v[72:75]
	v_mfma_f32_16x16x32_bf16 v[124:127], v[200:203], v[216:219], v[124:127]
	v_mfma_f32_16x16x32_bf16 v[116:119], v[208:211], v[216:219], v[116:119]
	v_mfma_f32_16x16x32_bf16 v[108:111], v[200:203], v[224:227], v[108:111]
	v_mfma_f32_16x16x32_bf16 v[100:103], v[208:211], v[224:227], v[100:103]
	v_mfma_f32_16x16x32_bf16 v[92:95], v[200:203], v[232:235], v[92:95]
	v_mfma_f32_16x16x32_bf16 v[84:87], v[208:211], v[232:235], v[84:87]
	v_mfma_f32_16x16x32_bf16 v[76:79], v[200:203], v[240:243], v[76:79]
	v_mfma_f32_16x16x32_bf16 v[68:71], v[208:211], v[240:243], v[68:71]
	v_mfma_f32_16x16x32_bf16 v[124:127], v[204:207], v[220:223], v[124:127]
	v_mfma_f32_16x16x32_bf16 v[116:119], v[212:215], v[220:223], v[116:119]
	v_mfma_f32_16x16x32_bf16 v[108:111], v[204:207], v[228:231], v[108:111]
	v_mfma_f32_16x16x32_bf16 v[100:103], v[212:215], v[228:231], v[100:103]
	v_mfma_f32_16x16x32_bf16 v[92:95], v[204:207], v[236:239], v[92:95]
	v_mfma_f32_16x16x32_bf16 v[84:87], v[212:215], v[236:239], v[84:87]
	v_mfma_f32_16x16x32_bf16 v[76:79], v[204:207], v[244:247], v[76:79]
	v_mfma_f32_16x16x32_bf16 v[68:71], v[212:215], v[244:247], v[68:71]
	s_barrier
	s_setprio 0
	s_add_i32 s22, s63, s27
	s_mov_b32 m0, s22
	ds_read_b128 v[216:219], v155 offset:49152
	ds_read_b128 v[220:223], v155 offset:50176
	ds_read_b128 v[224:227], v155 offset:51200
	ds_read_b128 v[228:231], v155 offset:52224
	ds_read_b128 v[232:235], v155 offset:53248
	ds_read_b128 v[236:239], v155 offset:54272
	ds_read_b128 v[240:243], v155 offset:55296
	ds_read_b128 v[244:247], v155 offset:56320
	s_add_u32 vcc_lo, s20, 0x80
	s_addc_u32 vcc_hi, s21, 0
	global_load_lds_dwordx4 v2, vcc
	s_add_i32 m0, s22, 0x2000
	s_add_u32 s20, s20, 0x80080
	s_addc_u32 s21, s21, 0
	s_add_i32 s22, s64, s27
	s_add_u32 vcc_lo, s20, 0xfff80000
	s_addc_u32 vcc_hi, s21, -1
	global_load_lds_dwordx4 v0, vcc
	s_mov_b32 m0, s22
	s_nop 0
	global_load_lds_dwordx4 v2, s[20:21]
	s_add_i32 m0, s22, 0x2000
	s_nop 0
	global_load_lds_dwordx4 v0, s[20:21]
	v_lshl_add_u64 v[150:151], v[248:249], 0, s[36:37]
	s_mov_b32 m0, s35
	s_nop 0
	global_load_lds_dwordx4 v[150:151], off
	v_lshl_add_u64 v[150:151], v[250:251], 0, s[36:37]
	s_mov_b32 m0, s42
	s_nop 0
	global_load_lds_dwordx4 v[150:151], off
	s_waitcnt vmcnt(8)
	s_waitcnt lgkmcnt(0)
	s_setprio 1
	s_barrier
	v_mfma_f32_16x16x32_bf16 v[64:67], v[184:187], v[216:219], v[64:67]
	v_mfma_f32_16x16x32_bf16 v[56:59], v[192:195], v[216:219], v[56:59]
	v_mfma_f32_16x16x32_bf16 v[48:51], v[184:187], v[224:227], v[48:51]
	v_mfma_f32_16x16x32_bf16 v[40:43], v[192:195], v[224:227], v[40:43]
	v_mfma_f32_16x16x32_bf16 v[32:35], v[184:187], v[232:235], v[32:35]
	v_mfma_f32_16x16x32_bf16 v[24:27], v[192:195], v[232:235], v[24:27]
	v_mfma_f32_16x16x32_bf16 v[16:19], v[184:187], v[240:243], v[16:19]
	v_mfma_f32_16x16x32_bf16 v[8:11], v[192:195], v[240:243], v[8:11]
	v_mfma_f32_16x16x32_bf16 v[64:67], v[188:191], v[220:223], v[64:67]
	v_mfma_f32_16x16x32_bf16 v[56:59], v[196:199], v[220:223], v[56:59]
	v_mfma_f32_16x16x32_bf16 v[48:51], v[188:191], v[228:231], v[48:51]
	v_mfma_f32_16x16x32_bf16 v[40:43], v[196:199], v[228:231], v[40:43]
	v_mfma_f32_16x16x32_bf16 v[32:35], v[188:191], v[236:239], v[32:35]
	v_mfma_f32_16x16x32_bf16 v[24:27], v[196:199], v[236:239], v[24:27]
	v_mfma_f32_16x16x32_bf16 v[16:19], v[188:191], v[244:247], v[16:19]
	v_mfma_f32_16x16x32_bf16 v[8:11], v[196:199], v[244:247], v[8:11]
	v_mfma_f32_16x16x32_bf16 v[60:63], v[200:203], v[216:219], v[60:63]
	v_mfma_f32_16x16x32_bf16 v[52:55], v[208:211], v[216:219], v[52:55]
	v_mfma_f32_16x16x32_bf16 v[44:47], v[200:203], v[224:227], v[44:47]
	v_mfma_f32_16x16x32_bf16 v[36:39], v[208:211], v[224:227], v[36:39]
	v_mfma_f32_16x16x32_bf16 v[28:31], v[200:203], v[232:235], v[28:31]
	v_mfma_f32_16x16x32_bf16 v[20:23], v[208:211], v[232:235], v[20:23]
	v_mfma_f32_16x16x32_bf16 v[12:15], v[200:203], v[240:243], v[12:15]
	v_mfma_f32_16x16x32_bf16 v[4:7], v[208:211], v[240:243], v[4:7]
	v_mfma_f32_16x16x32_bf16 v[60:63], v[204:207], v[220:223], v[60:63]
	v_mfma_f32_16x16x32_bf16 v[52:55], v[212:215], v[220:223], v[52:55]
	v_mfma_f32_16x16x32_bf16 v[44:47], v[204:207], v[228:231], v[44:47]
	v_mfma_f32_16x16x32_bf16 v[36:39], v[212:215], v[228:231], v[36:39]
	v_mfma_f32_16x16x32_bf16 v[28:31], v[204:207], v[236:239], v[28:31]
	v_mfma_f32_16x16x32_bf16 v[20:23], v[212:215], v[236:239], v[20:23]
	v_mfma_f32_16x16x32_bf16 v[12:15], v[204:207], v[244:247], v[12:15]
	v_mfma_f32_16x16x32_bf16 v[4:7], v[212:215], v[244:247], v[4:7]
	s_barrier
	s_setprio 0
	s_add_i32 s57, s57, 2
	s_add_u32 s18, s18, 0x100
	s_addc_u32 s19, s19, 0
	s_add_u32 s51, s51, 0x100
	s_addc_u32 s56, s56, 0
	s_cmp_gt_u32 s57, 29
	s_cbranch_scc0 .LBB0_567
	s_and_b64 vcc, exec, s[6:7]
	s_cbranch_vccz .LBB0_570
	s_barrier
